# GEMM read slots: the vmcnt(N) and lgkmcnt(0) inline waits ahead of each barrier merged into one s_waitcnt (60 sites)
# baseline (speedup 1.0000x reference)
.LBB0_187:
	s_ashr_i32 s15, s14, 31
	s_lshl_b64 s[16:17], s[14:15], 19
	s_add_u32 s16, s30, s16
	s_addc_u32 s17, s31, s17
	s_and_b64 s[18:19], s[0:1], exec
	s_cselect_b32 s3, s17, s25
	s_cselect_b32 s15, s16, s24
	s_ashr_i32 s13, s12, 31
	s_lshl_b64 s[18:19], s[12:13], 19
	s_add_u32 s18, s34, s18
	s_addc_u32 s19, s35, s19
	s_and_b64 s[26:27], s[0:1], exec
	s_cselect_b32 s13, s19, s23
	s_cselect_b32 s21, s18, s22
	s_add_u32 s48, s22, 0x100
	s_addc_u32 s49, s23, 0
	s_add_u32 s22, s24, 0x40080
	s_addc_u32 s23, s25, 0
	s_mov_b32 s50, -2
	s_waitcnt vmcnt(0)
	s_add_u32 s24, s22, 0xfffc0080
	s_addc_u32 s25, s23, -1
	s_add_i32 s51, 0, 0x10000
	s_cmp_eq_u32 s50, 12
	s_cselect_b32 s27, s3, s25
	s_cselect_b32 s26, s15, s24
	v_add_u32_e32 v142, s51, v144
	s_cselect_b32 s25, s13, s49
	s_cselect_b32 s24, s21, s48
	s_add_i32 s54, 0, 0x14000
	ds_read_b128 v[138:141], v142
	ds_read_b128 v[146:149], v142 offset:1024
	ds_read_b128 v[150:153], v142 offset:2048
	ds_read_b128 v[154:157], v142 offset:3072
	v_add_u32_e32 v142, s54, v144
	ds_read_b128 v[158:161], v142
	ds_read_b128 v[162:165], v142 offset:1024
	ds_read_b128 v[166:169], v142 offset:2048
	ds_read_b128 v[170:173], v142 offset:3072
	v_lshl_add_u64 v[142:143], s[22:23], 0, v[136:137]
	s_add_i32 m0, s37, 0xc000
	ds_read_b128 v[174:177], v145
	ds_read_b128 v[178:181], v145 offset:1024
	ds_read_b128 v[182:185], v145 offset:2048
	ds_read_b128 v[186:189], v145 offset:3072
	ds_read_b128 v[190:193], v145 offset:4096
	ds_read_b128 v[194:197], v145 offset:5120
	ds_read_b128 v[198:201], v145 offset:6144
	ds_read_b128 v[202:205], v145 offset:7168
	global_load_lds_dwordx4 v[142:143], off
	v_lshl_add_u64 v[142:143], s[22:23], 0, v[134:135]
	s_add_i32 m0, s37, 0xe000
	s_nop 0
	global_load_lds_dwordx4 v[142:143], off
	s_waitcnt vmcnt(8) lgkmcnt(0)
	s_barrier
	v_mfma_f32_16x16x32_bf16 v[124:127], v[138:141], v[174:177], 0
	v_mfma_f32_16x16x32_bf16 v[120:123], v[150:153], v[174:177], 0
	v_mfma_f32_16x16x32_bf16 v[112:115], v[138:141], v[182:185], 0
	v_mfma_f32_16x16x32_bf16 v[104:107], v[150:153], v[182:185], 0
	v_mfma_f32_16x16x32_bf16 v[96:99], v[138:141], v[190:193], 0
	v_mfma_f32_16x16x32_bf16 v[88:91], v[150:153], v[190:193], 0
	v_mfma_f32_16x16x32_bf16 v[80:83], v[138:141], v[198:201], 0
	v_mfma_f32_16x16x32_bf16 v[72:75], v[150:153], v[198:201], 0
	v_mfma_f32_16x16x32_bf16 v[124:127], v[146:149], v[178:181], v[124:127]
	v_mfma_f32_16x16x32_bf16 v[120:123], v[154:157], v[178:181], v[120:123]
	v_mfma_f32_16x16x32_bf16 v[112:115], v[146:149], v[186:189], v[112:115]
	v_mfma_f32_16x16x32_bf16 v[104:107], v[154:157], v[186:189], v[104:107]
	v_mfma_f32_16x16x32_bf16 v[96:99], v[146:149], v[194:197], v[96:99]
	v_mfma_f32_16x16x32_bf16 v[88:91], v[154:157], v[194:197], v[88:91]
	v_mfma_f32_16x16x32_bf16 v[80:83], v[146:149], v[202:205], v[80:83]
	v_mfma_f32_16x16x32_bf16 v[72:75], v[154:157], v[202:205], v[72:75]
	v_mfma_f32_16x16x32_bf16 v[116:119], v[158:161], v[174:177], 0
	v_mfma_f32_16x16x32_bf16 v[108:111], v[166:169], v[174:177], 0
	v_mfma_f32_16x16x32_bf16 v[100:103], v[158:161], v[182:185], 0
	v_mfma_f32_16x16x32_bf16 v[92:95], v[166:169], v[182:185], 0
	v_mfma_f32_16x16x32_bf16 v[84:87], v[158:161], v[190:193], 0
	v_mfma_f32_16x16x32_bf16 v[76:79], v[166:169], v[190:193], 0
	v_mfma_f32_16x16x32_bf16 v[68:71], v[158:161], v[198:201], 0
	v_mfma_f32_16x16x32_bf16 v[64:67], v[166:169], v[198:201], 0
	v_mfma_f32_16x16x32_bf16 v[116:119], v[162:165], v[178:181], v[116:119]
	v_mfma_f32_16x16x32_bf16 v[108:111], v[170:173], v[178:181], v[108:111]
	v_mfma_f32_16x16x32_bf16 v[100:103], v[162:165], v[186:189], v[100:103]
	v_mfma_f32_16x16x32_bf16 v[92:95], v[170:173], v[186:189], v[92:95]
	v_mfma_f32_16x16x32_bf16 v[84:87], v[162:165], v[194:197], v[84:87]
	v_mfma_f32_16x16x32_bf16 v[76:79], v[170:173], v[194:197], v[76:79]
	v_mfma_f32_16x16x32_bf16 v[68:71], v[162:165], v[202:205], v[68:71]
	v_mfma_f32_16x16x32_bf16 v[64:67], v[170:173], v[202:205], v[64:67]
	s_barrier
	s_add_i32 s51, s51, s36
	v_lshl_add_u64 v[142:143], s[24:25], 0, v[232:233]
	s_mov_b32 m0, s51
	ds_read_b128 v[174:177], v145 offset:16384
	ds_read_b128 v[178:181], v145 offset:17408
	ds_read_b128 v[182:185], v145 offset:18432
	ds_read_b128 v[186:189], v145 offset:19456
	ds_read_b128 v[190:193], v145 offset:20480
	ds_read_b128 v[194:197], v145 offset:21504
	ds_read_b128 v[198:201], v145 offset:22528
	ds_read_b128 v[202:205], v145 offset:23552
	global_load_lds_dwordx4 v[142:143], off
	s_add_i32 m0, s51, 0x2000
	s_add_u32 s52, s24, 0x40000
	v_lshl_add_u64 v[206:207], s[24:25], 0, v[132:133]
	s_addc_u32 s53, s25, 0
	s_add_i32 s51, s54, s36
	global_load_lds_dwordx4 v[206:207], off
	v_lshl_add_u64 v[208:209], s[52:53], 0, v[232:233]
	s_mov_b32 m0, s51
	v_lshl_add_u64 v[210:211], s[26:27], 0, v[130:131]
	global_load_lds_dwordx4 v[208:209], off
	v_lshl_add_u64 v[208:209], s[52:53], 0, v[132:133]
	s_add_i32 m0, s51, 0x2000
	s_nop 0
	global_load_lds_dwordx4 v[208:209], off
	v_lshl_add_u64 v[208:209], s[26:27], 0, v[128:129]
	s_waitcnt vmcnt(6) lgkmcnt(0)
	s_barrier
	v_mfma_f32_16x16x32_bf16 v[60:63], v[138:141], v[174:177], 0
	v_mfma_f32_16x16x32_bf16 v[56:59], v[150:153], v[174:177], 0
	v_mfma_f32_16x16x32_bf16 v[48:51], v[138:141], v[182:185], 0
	v_mfma_f32_16x16x32_bf16 v[40:43], v[150:153], v[182:185], 0
	v_mfma_f32_16x16x32_bf16 v[32:35], v[138:141], v[190:193], 0
	v_mfma_f32_16x16x32_bf16 v[24:27], v[150:153], v[190:193], 0
	v_mfma_f32_16x16x32_bf16 v[16:19], v[138:141], v[198:201], 0
	v_mfma_f32_16x16x32_bf16 v[8:11], v[150:153], v[198:201], 0
	v_mfma_f32_16x16x32_bf16 v[60:63], v[146:149], v[178:181], v[60:63]
	v_mfma_f32_16x16x32_bf16 v[56:59], v[154:157], v[178:181], v[56:59]
	v_mfma_f32_16x16x32_bf16 v[48:51], v[146:149], v[186:189], v[48:51]
	v_mfma_f32_16x16x32_bf16 v[40:43], v[154:157], v[186:189], v[40:43]
	v_mfma_f32_16x16x32_bf16 v[32:35], v[146:149], v[194:197], v[32:35]
	v_mfma_f32_16x16x32_bf16 v[24:27], v[154:157], v[194:197], v[24:27]
	v_mfma_f32_16x16x32_bf16 v[16:19], v[146:149], v[202:205], v[16:19]
	v_mfma_f32_16x16x32_bf16 v[8:11], v[154:157], v[202:205], v[8:11]
	v_mfma_f32_16x16x32_bf16 v[52:55], v[158:161], v[174:177], 0
	v_mfma_f32_16x16x32_bf16 v[44:47], v[166:169], v[174:177], 0
	v_mfma_f32_16x16x32_bf16 v[36:39], v[158:161], v[182:185], 0
	v_mfma_f32_16x16x32_bf16 v[28:31], v[166:169], v[182:185], 0
	v_mfma_f32_16x16x32_bf16 v[20:23], v[158:161], v[190:193], 0
	v_mfma_f32_16x16x32_bf16 v[12:15], v[166:169], v[190:193], 0
	v_mfma_f32_16x16x32_bf16 v[4:7], v[158:161], v[198:201], 0
	v_mfma_f32_16x16x32_bf16 v[0:3], v[166:169], v[198:201], 0
	v_mfma_f32_16x16x32_bf16 v[52:55], v[162:165], v[178:181], v[52:55]
	v_mfma_f32_16x16x32_bf16 v[44:47], v[170:173], v[178:181], v[44:47]
	v_mfma_f32_16x16x32_bf16 v[36:39], v[162:165], v[186:189], v[36:39]
	v_mfma_f32_16x16x32_bf16 v[28:31], v[170:173], v[186:189], v[28:31]
	v_mfma_f32_16x16x32_bf16 v[20:23], v[162:165], v[194:197], v[20:23]
	v_mfma_f32_16x16x32_bf16 v[12:15], v[170:173], v[194:197], v[12:15]
	v_mfma_f32_16x16x32_bf16 v[4:7], v[162:165], v[202:205], v[4:7]
	v_mfma_f32_16x16x32_bf16 v[0:3], v[170:173], v[202:205], v[0:3]
	s_barrier
	s_branch .Lzmid_1
.LBB0_188:
	s_add_u32 s24, s22, 0xfffc0080
	s_addc_u32 s25, s23, -1
	s_add_i32 s51, 0, 0x10000
	s_cmp_eq_u32 s50, 12
	s_cselect_b32 s27, s3, s25
	s_cselect_b32 s26, s15, s24
	v_add_u32_e32 v142, s51, v144
	s_cselect_b32 s25, s13, s49
	s_cselect_b32 s24, s21, s48
	s_add_i32 s54, 0, 0x14000
	ds_read_b128 v[138:141], v142
	ds_read_b128 v[146:149], v142 offset:1024
	ds_read_b128 v[150:153], v142 offset:2048
	ds_read_b128 v[154:157], v142 offset:3072
	v_add_u32_e32 v142, s54, v144
	ds_read_b128 v[158:161], v142
	ds_read_b128 v[162:165], v142 offset:1024
	ds_read_b128 v[166:169], v142 offset:2048
	ds_read_b128 v[170:173], v142 offset:3072
	v_lshl_add_u64 v[142:143], s[22:23], 0, v[136:137]
	s_add_i32 m0, s37, 0xc000
	ds_read_b128 v[174:177], v145
	ds_read_b128 v[178:181], v145 offset:1024
	ds_read_b128 v[182:185], v145 offset:2048
	ds_read_b128 v[186:189], v145 offset:3072
	ds_read_b128 v[190:193], v145 offset:4096
	ds_read_b128 v[194:197], v145 offset:5120
	ds_read_b128 v[198:201], v145 offset:6144
	ds_read_b128 v[202:205], v145 offset:7168
	global_load_lds_dwordx4 v[142:143], off
	v_lshl_add_u64 v[142:143], s[22:23], 0, v[134:135]
	s_add_i32 m0, s37, 0xe000
	s_nop 0
	global_load_lds_dwordx4 v[142:143], off
	s_waitcnt vmcnt(8) lgkmcnt(0)
	s_barrier
	v_mfma_f32_16x16x32_bf16 v[124:127], v[138:141], v[174:177], v[124:127]
	v_mfma_f32_16x16x32_bf16 v[120:123], v[150:153], v[174:177], v[120:123]
	v_mfma_f32_16x16x32_bf16 v[112:115], v[138:141], v[182:185], v[112:115]
	v_mfma_f32_16x16x32_bf16 v[104:107], v[150:153], v[182:185], v[104:107]
	v_mfma_f32_16x16x32_bf16 v[96:99], v[138:141], v[190:193], v[96:99]
	v_mfma_f32_16x16x32_bf16 v[88:91], v[150:153], v[190:193], v[88:91]
	v_mfma_f32_16x16x32_bf16 v[80:83], v[138:141], v[198:201], v[80:83]
	v_mfma_f32_16x16x32_bf16 v[72:75], v[150:153], v[198:201], v[72:75]
	v_mfma_f32_16x16x32_bf16 v[124:127], v[146:149], v[178:181], v[124:127]
	v_mfma_f32_16x16x32_bf16 v[120:123], v[154:157], v[178:181], v[120:123]
	v_mfma_f32_16x16x32_bf16 v[112:115], v[146:149], v[186:189], v[112:115]
	v_mfma_f32_16x16x32_bf16 v[104:107], v[154:157], v[186:189], v[104:107]
	v_mfma_f32_16x16x32_bf16 v[96:99], v[146:149], v[194:197], v[96:99]
	v_mfma_f32_16x16x32_bf16 v[88:91], v[154:157], v[194:197], v[88:91]
	v_mfma_f32_16x16x32_bf16 v[80:83], v[146:149], v[202:205], v[80:83]
	v_mfma_f32_16x16x32_bf16 v[72:75], v[154:157], v[202:205], v[72:75]
	v_mfma_f32_16x16x32_bf16 v[116:119], v[158:161], v[174:177], v[116:119]
	v_mfma_f32_16x16x32_bf16 v[108:111], v[166:169], v[174:177], v[108:111]
	v_mfma_f32_16x16x32_bf16 v[100:103], v[158:161], v[182:185], v[100:103]
	v_mfma_f32_16x16x32_bf16 v[92:95], v[166:169], v[182:185], v[92:95]
	v_mfma_f32_16x16x32_bf16 v[84:87], v[158:161], v[190:193], v[84:87]
	v_mfma_f32_16x16x32_bf16 v[76:79], v[166:169], v[190:193], v[76:79]
	v_mfma_f32_16x16x32_bf16 v[68:71], v[158:161], v[198:201], v[68:71]
	v_mfma_f32_16x16x32_bf16 v[64:67], v[166:169], v[198:201], v[64:67]
	v_mfma_f32_16x16x32_bf16 v[116:119], v[162:165], v[178:181], v[116:119]
	v_mfma_f32_16x16x32_bf16 v[108:111], v[170:173], v[178:181], v[108:111]
	v_mfma_f32_16x16x32_bf16 v[100:103], v[162:165], v[186:189], v[100:103]
	v_mfma_f32_16x16x32_bf16 v[92:95], v[170:173], v[186:189], v[92:95]
	v_mfma_f32_16x16x32_bf16 v[84:87], v[162:165], v[194:197], v[84:87]
	v_mfma_f32_16x16x32_bf16 v[76:79], v[170:173], v[194:197], v[76:79]
	v_mfma_f32_16x16x32_bf16 v[68:71], v[162:165], v[202:205], v[68:71]
	v_mfma_f32_16x16x32_bf16 v[64:67], v[170:173], v[202:205], v[64:67]
	s_barrier
	s_add_i32 s51, s51, s36
	v_lshl_add_u64 v[142:143], s[24:25], 0, v[232:233]
	s_mov_b32 m0, s51
	ds_read_b128 v[174:177], v145 offset:16384
	ds_read_b128 v[178:181], v145 offset:17408
	ds_read_b128 v[182:185], v145 offset:18432
	ds_read_b128 v[186:189], v145 offset:19456
	ds_read_b128 v[190:193], v145 offset:20480
	ds_read_b128 v[194:197], v145 offset:21504
	ds_read_b128 v[198:201], v145 offset:22528
	ds_read_b128 v[202:205], v145 offset:23552
	global_load_lds_dwordx4 v[142:143], off
	s_add_i32 m0, s51, 0x2000
	s_add_u32 s52, s24, 0x40000
	v_lshl_add_u64 v[206:207], s[24:25], 0, v[132:133]
	s_addc_u32 s53, s25, 0
	s_add_i32 s51, s54, s36
	global_load_lds_dwordx4 v[206:207], off
	v_lshl_add_u64 v[208:209], s[52:53], 0, v[232:233]
	s_mov_b32 m0, s51
	v_lshl_add_u64 v[210:211], s[26:27], 0, v[130:131]
	global_load_lds_dwordx4 v[208:209], off
	v_lshl_add_u64 v[208:209], s[52:53], 0, v[132:133]
	s_add_i32 m0, s51, 0x2000
	s_nop 0
	global_load_lds_dwordx4 v[208:209], off
	v_lshl_add_u64 v[208:209], s[26:27], 0, v[128:129]
	s_waitcnt vmcnt(6) lgkmcnt(0)
	s_barrier
	v_mfma_f32_16x16x32_bf16 v[60:63], v[138:141], v[174:177], v[60:63]
	v_mfma_f32_16x16x32_bf16 v[56:59], v[150:153], v[174:177], v[56:59]
	v_mfma_f32_16x16x32_bf16 v[48:51], v[138:141], v[182:185], v[48:51]
	v_mfma_f32_16x16x32_bf16 v[40:43], v[150:153], v[182:185], v[40:43]
	v_mfma_f32_16x16x32_bf16 v[32:35], v[138:141], v[190:193], v[32:35]
	v_mfma_f32_16x16x32_bf16 v[24:27], v[150:153], v[190:193], v[24:27]
	v_mfma_f32_16x16x32_bf16 v[16:19], v[138:141], v[198:201], v[16:19]
	v_mfma_f32_16x16x32_bf16 v[8:11], v[150:153], v[198:201], v[8:11]
	v_mfma_f32_16x16x32_bf16 v[60:63], v[146:149], v[178:181], v[60:63]
	v_mfma_f32_16x16x32_bf16 v[56:59], v[154:157], v[178:181], v[56:59]
	v_mfma_f32_16x16x32_bf16 v[48:51], v[146:149], v[186:189], v[48:51]
	v_mfma_f32_16x16x32_bf16 v[40:43], v[154:157], v[186:189], v[40:43]
	v_mfma_f32_16x16x32_bf16 v[32:35], v[146:149], v[194:197], v[32:35]
	v_mfma_f32_16x16x32_bf16 v[24:27], v[154:157], v[194:197], v[24:27]
	v_mfma_f32_16x16x32_bf16 v[16:19], v[146:149], v[202:205], v[16:19]
	v_mfma_f32_16x16x32_bf16 v[8:11], v[154:157], v[202:205], v[8:11]
	v_mfma_f32_16x16x32_bf16 v[52:55], v[158:161], v[174:177], v[52:55]
	v_mfma_f32_16x16x32_bf16 v[44:47], v[166:169], v[174:177], v[44:47]
	v_mfma_f32_16x16x32_bf16 v[36:39], v[158:161], v[182:185], v[36:39]
	v_mfma_f32_16x16x32_bf16 v[28:31], v[166:169], v[182:185], v[28:31]
	v_mfma_f32_16x16x32_bf16 v[20:23], v[158:161], v[190:193], v[20:23]
	v_mfma_f32_16x16x32_bf16 v[12:15], v[166:169], v[190:193], v[12:15]
	v_mfma_f32_16x16x32_bf16 v[4:7], v[158:161], v[198:201], v[4:7]
	v_mfma_f32_16x16x32_bf16 v[0:3], v[166:169], v[198:201], v[0:3]
	v_mfma_f32_16x16x32_bf16 v[52:55], v[162:165], v[178:181], v[52:55]
	v_mfma_f32_16x16x32_bf16 v[44:47], v[170:173], v[178:181], v[44:47]
	v_mfma_f32_16x16x32_bf16 v[36:39], v[162:165], v[186:189], v[36:39]
	v_mfma_f32_16x16x32_bf16 v[28:31], v[170:173], v[186:189], v[28:31]
	v_mfma_f32_16x16x32_bf16 v[20:23], v[162:165], v[194:197], v[20:23]
	v_mfma_f32_16x16x32_bf16 v[12:15], v[170:173], v[194:197], v[12:15]
	v_mfma_f32_16x16x32_bf16 v[4:7], v[162:165], v[202:205], v[4:7]
	v_mfma_f32_16x16x32_bf16 v[0:3], v[170:173], v[202:205], v[0:3]
	s_barrier
.Lzmid_1:
	s_add_i32 s51, 0, 0x18000
	s_add_i32 s52, 0, 0x1c000
	v_add_u32_e32 v154, s51, v144
	v_add_u32_e32 v170, s52, v144
	ds_read_b128 v[138:141], v154
	ds_read_b128 v[146:149], v154 offset:1024
	ds_read_b128 v[150:153], v154 offset:2048
	ds_read_b128 v[154:157], v154 offset:3072
	ds_read_b128 v[158:161], v170
	ds_read_b128 v[162:165], v170 offset:1024
	ds_read_b128 v[166:169], v170 offset:2048
	ds_read_b128 v[170:173], v170 offset:3072
	s_add_u32 s26, s26, 0x40000
	s_addc_u32 s27, s27, 0
	s_mov_b32 m0, s37
	s_nop 0
	global_load_lds_dwordx4 v[208:209], off
	s_mov_b32 m0, s38
	s_nop 0
	global_load_lds_dwordx4 v[210:211], off
	s_mov_b32 m0, s39
	v_lshl_add_u64 v[212:213], s[26:27], 0, v[128:129]
	ds_read_b128 v[174:177], v145 offset:32768
	ds_read_b128 v[178:181], v145 offset:33792
	ds_read_b128 v[182:185], v145 offset:34816
	ds_read_b128 v[186:189], v145 offset:35840
	ds_read_b128 v[190:193], v145 offset:36864
	ds_read_b128 v[194:197], v145 offset:37888
	ds_read_b128 v[198:201], v145 offset:38912
	ds_read_b128 v[202:205], v145 offset:39936
	global_load_lds_dwordx4 v[212:213], off
	v_lshl_add_u64 v[212:213], s[26:27], 0, v[130:131]
	s_mov_b32 m0, s40
	s_nop 0
	global_load_lds_dwordx4 v[212:213], off
	s_waitcnt vmcnt(8) lgkmcnt(0)
	s_barrier
	v_mfma_f32_16x16x32_bf16 v[124:127], v[138:141], v[174:177], v[124:127]
	v_mfma_f32_16x16x32_bf16 v[120:123], v[150:153], v[174:177], v[120:123]
	v_mfma_f32_16x16x32_bf16 v[112:115], v[138:141], v[182:185], v[112:115]
	v_mfma_f32_16x16x32_bf16 v[104:107], v[150:153], v[182:185], v[104:107]
	v_mfma_f32_16x16x32_bf16 v[96:99], v[138:141], v[190:193], v[96:99]
	v_mfma_f32_16x16x32_bf16 v[88:91], v[150:153], v[190:193], v[88:91]
	v_mfma_f32_16x16x32_bf16 v[80:83], v[138:141], v[198:201], v[80:83]
	v_mfma_f32_16x16x32_bf16 v[72:75], v[150:153], v[198:201], v[72:75]
	v_mfma_f32_16x16x32_bf16 v[124:127], v[146:149], v[178:181], v[124:127]
	v_mfma_f32_16x16x32_bf16 v[120:123], v[154:157], v[178:181], v[120:123]
	v_mfma_f32_16x16x32_bf16 v[112:115], v[146:149], v[186:189], v[112:115]
	v_mfma_f32_16x16x32_bf16 v[104:107], v[154:157], v[186:189], v[104:107]
	v_mfma_f32_16x16x32_bf16 v[96:99], v[146:149], v[194:197], v[96:99]
	v_mfma_f32_16x16x32_bf16 v[88:91], v[154:157], v[194:197], v[88:91]
	v_mfma_f32_16x16x32_bf16 v[80:83], v[146:149], v[202:205], v[80:83]
	v_mfma_f32_16x16x32_bf16 v[72:75], v[154:157], v[202:205], v[72:75]
	v_mfma_f32_16x16x32_bf16 v[116:119], v[158:161], v[174:177], v[116:119]
	v_mfma_f32_16x16x32_bf16 v[108:111], v[166:169], v[174:177], v[108:111]
	v_mfma_f32_16x16x32_bf16 v[100:103], v[158:161], v[182:185], v[100:103]
	v_mfma_f32_16x16x32_bf16 v[92:95], v[166:169], v[182:185], v[92:95]
	v_mfma_f32_16x16x32_bf16 v[84:87], v[158:161], v[190:193], v[84:87]
	v_mfma_f32_16x16x32_bf16 v[76:79], v[166:169], v[190:193], v[76:79]
	v_mfma_f32_16x16x32_bf16 v[68:71], v[158:161], v[198:201], v[68:71]
	v_mfma_f32_16x16x32_bf16 v[64:67], v[166:169], v[198:201], v[64:67]
	v_mfma_f32_16x16x32_bf16 v[116:119], v[162:165], v[178:181], v[116:119]
	v_mfma_f32_16x16x32_bf16 v[108:111], v[170:173], v[178:181], v[108:111]
	v_mfma_f32_16x16x32_bf16 v[100:103], v[162:165], v[186:189], v[100:103]
	v_mfma_f32_16x16x32_bf16 v[92:95], v[170:173], v[186:189], v[92:95]
	v_mfma_f32_16x16x32_bf16 v[84:87], v[162:165], v[194:197], v[84:87]
	v_mfma_f32_16x16x32_bf16 v[76:79], v[170:173], v[194:197], v[76:79]
	v_mfma_f32_16x16x32_bf16 v[68:71], v[162:165], v[202:205], v[68:71]
	v_mfma_f32_16x16x32_bf16 v[64:67], v[170:173], v[202:205], v[64:67]
	s_barrier
	s_add_i32 s26, s51, s36
	v_lshl_add_u64 v[142:143], v[142:143], 0, s[94:95]
	s_mov_b32 m0, s26
	ds_read_b128 v[174:177], v145 offset:49152
	ds_read_b128 v[178:181], v145 offset:50176
	ds_read_b128 v[182:185], v145 offset:51200
	ds_read_b128 v[186:189], v145 offset:52224
	ds_read_b128 v[190:193], v145 offset:53248
	ds_read_b128 v[194:197], v145 offset:54272
	ds_read_b128 v[198:201], v145 offset:55296
	ds_read_b128 v[202:205], v145 offset:56320
	global_load_lds_dwordx4 v[142:143], off
	s_add_i32 m0, s26, 0x2000
	s_add_u32 s24, s24, 0x40080
	v_lshl_add_u64 v[142:143], v[206:207], 0, s[94:95]
	s_addc_u32 s25, s25, 0
	s_add_i32 s26, s52, s36
	global_load_lds_dwordx4 v[142:143], off
	v_lshl_add_u64 v[142:143], s[24:25], 0, v[232:233]
	s_mov_b32 m0, s26
	s_nop 0
	global_load_lds_dwordx4 v[142:143], off
	v_lshl_add_u64 v[142:143], s[24:25], 0, v[132:133]
	s_add_i32 m0, s26, 0x2000
	s_nop 0
	global_load_lds_dwordx4 v[142:143], off
	v_lshl_add_u64 v[142:143], v[208:209], 0, s[94:95]
	s_mov_b32 m0, s43
	s_nop 0
	global_load_lds_dwordx4 v[142:143], off
	v_lshl_add_u64 v[142:143], v[210:211], 0, s[94:95]
	s_mov_b32 m0, s44
	s_nop 0
	global_load_lds_dwordx4 v[142:143], off
	s_waitcnt vmcnt(8) lgkmcnt(0)
	s_barrier
	v_mfma_f32_16x16x32_bf16 v[60:63], v[138:141], v[174:177], v[60:63]
	v_mfma_f32_16x16x32_bf16 v[56:59], v[150:153], v[174:177], v[56:59]
	v_mfma_f32_16x16x32_bf16 v[48:51], v[138:141], v[182:185], v[48:51]
	v_mfma_f32_16x16x32_bf16 v[40:43], v[150:153], v[182:185], v[40:43]
	v_mfma_f32_16x16x32_bf16 v[32:35], v[138:141], v[190:193], v[32:35]
	v_mfma_f32_16x16x32_bf16 v[24:27], v[150:153], v[190:193], v[24:27]
	v_mfma_f32_16x16x32_bf16 v[16:19], v[138:141], v[198:201], v[16:19]
	v_mfma_f32_16x16x32_bf16 v[8:11], v[150:153], v[198:201], v[8:11]
	v_mfma_f32_16x16x32_bf16 v[60:63], v[146:149], v[178:181], v[60:63]
	v_mfma_f32_16x16x32_bf16 v[56:59], v[154:157], v[178:181], v[56:59]
	v_mfma_f32_16x16x32_bf16 v[48:51], v[146:149], v[186:189], v[48:51]
	v_mfma_f32_16x16x32_bf16 v[40:43], v[154:157], v[186:189], v[40:43]
	v_mfma_f32_16x16x32_bf16 v[32:35], v[146:149], v[194:197], v[32:35]
	v_mfma_f32_16x16x32_bf16 v[24:27], v[154:157], v[194:197], v[24:27]
	v_mfma_f32_16x16x32_bf16 v[16:19], v[146:149], v[202:205], v[16:19]
	v_mfma_f32_16x16x32_bf16 v[8:11], v[154:157], v[202:205], v[8:11]
	v_mfma_f32_16x16x32_bf16 v[52:55], v[158:161], v[174:177], v[52:55]
	v_mfma_f32_16x16x32_bf16 v[44:47], v[166:169], v[174:177], v[44:47]
	v_mfma_f32_16x16x32_bf16 v[36:39], v[158:161], v[182:185], v[36:39]
	v_mfma_f32_16x16x32_bf16 v[28:31], v[166:169], v[182:185], v[28:31]
	v_mfma_f32_16x16x32_bf16 v[20:23], v[158:161], v[190:193], v[20:23]
	v_mfma_f32_16x16x32_bf16 v[12:15], v[166:169], v[190:193], v[12:15]
	v_mfma_f32_16x16x32_bf16 v[4:7], v[158:161], v[198:201], v[4:7]
	v_mfma_f32_16x16x32_bf16 v[0:3], v[166:169], v[198:201], v[0:3]
	v_mfma_f32_16x16x32_bf16 v[52:55], v[162:165], v[178:181], v[52:55]
	v_mfma_f32_16x16x32_bf16 v[44:47], v[170:173], v[178:181], v[44:47]
	v_mfma_f32_16x16x32_bf16 v[36:39], v[162:165], v[186:189], v[36:39]
	v_mfma_f32_16x16x32_bf16 v[28:31], v[170:173], v[186:189], v[28:31]
	v_mfma_f32_16x16x32_bf16 v[20:23], v[162:165], v[194:197], v[20:23]
	v_mfma_f32_16x16x32_bf16 v[12:15], v[170:173], v[194:197], v[12:15]
	v_mfma_f32_16x16x32_bf16 v[4:7], v[162:165], v[202:205], v[4:7]
	v_mfma_f32_16x16x32_bf16 v[0:3], v[170:173], v[202:205], v[0:3]
	s_barrier
	s_add_i32 s50, s50, 2
	s_add_u32 s48, s48, 0x100
	s_addc_u32 s49, s49, 0
	s_add_u32 s22, s22, 0x100
	s_addc_u32 s23, s23, 0
	s_cmp_gt_u32 s50, 13
	s_cbranch_scc0 .LBB0_188
	s_and_b64 vcc, exec, s[10:11]
	s_cbranch_vccz .LBB0_191
	s_barrier

.LBB0_311:
	s_add_u32 s35, s26, s34
	s_addc_u32 s40, s27, 0
	s_add_u32 s38, s35, 0x100
	s_addc_u32 s39, s40, 0
	s_and_b64 s[36:37], s[30:31], exec
	s_cselect_b32 s37, s5, s39
	s_cselect_b32 s36, s17, s38
	s_add_u32 s34, s24, s34
	s_addc_u32 s38, s25, 0
	s_add_u32 s34, s34, 0x100
	s_addc_u32 s38, s38, 0
	s_add_i32 s70, 0, 0x10000
	s_and_b64 s[30:31], s[30:31], exec
	s_cselect_b32 s39, s15, s38
	s_cselect_b32 s38, s23, s34
	s_add_i32 s31, 0, 0x14000
	s_add_u32 s42, s35, 0x100080
	s_addc_u32 s43, s40, 0
	s_add_i32 s69, s70, s50
	s_add_i32 m0, s51, 0xc000
	s_add_i32 s72, s51, 0xe000
	s_add_i32 s66, s69, 0x2000
	s_add_u32 s40, s38, 0x10000
	v_add_u32_e32 v146, s70, v154
	v_add_u32_e32 v164, s31, v154
	s_addc_u32 s41, s39, 0
	s_add_i32 s68, s31, s50
	ds_read_b128 v[134:137], v146
	ds_read_b128 v[138:141], v146 offset:1024
	ds_read_b128 v[142:145], v146 offset:2048
	ds_read_b128 v[146:149], v146 offset:3072
	ds_read_b128 v[150:153], v164
	ds_read_b128 v[156:159], v164 offset:1024
	ds_read_b128 v[160:163], v164 offset:2048
	ds_read_b128 v[164:167], v164 offset:3072
	s_add_i32 s67, s68, 0x2000
	s_add_i32 s65, 0, 0x18000
	s_add_i32 s64, 0, 0x1c000
	s_add_u32 s34, s36, 0x100000
	s_addc_u32 s35, s37, 0
	s_add_i32 s63, s65, s50
	s_add_i32 s62, s63, 0x2000
	s_add_u32 s30, s38, 0x10080
	s_addc_u32 s31, s39, 0
	s_add_i32 s71, s64, s50
	s_add_i32 s70, s71, 0x2000
	v_lshl_add_u64 v[200:201], s[42:43], 0, v[128:129]
	ds_read_b128 v[168:171], v155
	ds_read_b128 v[172:175], v155 offset:1024
	ds_read_b128 v[176:179], v155 offset:2048
	ds_read_b128 v[180:183], v155 offset:3072
	ds_read_b128 v[184:187], v155 offset:4096
	ds_read_b128 v[188:191], v155 offset:5120
	ds_read_b128 v[192:195], v155 offset:6144
	ds_read_b128 v[196:199], v155 offset:7168
	global_load_lds_dwordx4 v[200:201], off
	v_lshl_add_u64 v[200:201], s[42:43], 0, v[130:131]
	s_mov_b32 m0, s72
	s_nop 0
	global_load_lds_dwordx4 v[200:201], off
	s_waitcnt vmcnt(8) lgkmcnt(0)
	s_barrier
	v_mfma_f32_16x16x32_bf16 v[124:127], v[134:137], v[168:171], v[124:127]
	v_mfma_f32_16x16x32_bf16 v[120:123], v[142:145], v[168:171], v[120:123]
	v_mfma_f32_16x16x32_bf16 v[108:111], v[134:137], v[176:179], v[108:111]
	v_mfma_f32_16x16x32_bf16 v[104:107], v[142:145], v[176:179], v[104:107]
	v_mfma_f32_16x16x32_bf16 v[92:95], v[134:137], v[184:187], v[92:95]
	v_mfma_f32_16x16x32_bf16 v[88:91], v[142:145], v[184:187], v[88:91]
	v_mfma_f32_16x16x32_bf16 v[76:79], v[134:137], v[192:195], v[76:79]
	v_mfma_f32_16x16x32_bf16 v[72:75], v[142:145], v[192:195], v[72:75]
	v_mfma_f32_16x16x32_bf16 v[124:127], v[138:141], v[172:175], v[124:127]
	v_mfma_f32_16x16x32_bf16 v[120:123], v[146:149], v[172:175], v[120:123]
	v_mfma_f32_16x16x32_bf16 v[108:111], v[138:141], v[180:183], v[108:111]
	v_mfma_f32_16x16x32_bf16 v[104:107], v[146:149], v[180:183], v[104:107]
	v_mfma_f32_16x16x32_bf16 v[92:95], v[138:141], v[188:191], v[92:95]
	v_mfma_f32_16x16x32_bf16 v[88:91], v[146:149], v[188:191], v[88:91]
	v_mfma_f32_16x16x32_bf16 v[76:79], v[138:141], v[196:199], v[76:79]
	v_mfma_f32_16x16x32_bf16 v[72:75], v[146:149], v[196:199], v[72:75]
	v_mfma_f32_16x16x32_bf16 v[116:119], v[150:153], v[168:171], v[116:119]
	v_mfma_f32_16x16x32_bf16 v[112:115], v[160:163], v[168:171], v[112:115]
	v_mfma_f32_16x16x32_bf16 v[100:103], v[150:153], v[176:179], v[100:103]
	v_mfma_f32_16x16x32_bf16 v[96:99], v[160:163], v[176:179], v[96:99]
	v_mfma_f32_16x16x32_bf16 v[84:87], v[150:153], v[184:187], v[84:87]
	v_mfma_f32_16x16x32_bf16 v[80:83], v[160:163], v[184:187], v[80:83]
	v_mfma_f32_16x16x32_bf16 v[68:71], v[150:153], v[192:195], v[68:71]
	v_mfma_f32_16x16x32_bf16 v[64:67], v[160:163], v[192:195], v[64:67]
	v_mfma_f32_16x16x32_bf16 v[116:119], v[156:159], v[172:175], v[116:119]
	v_mfma_f32_16x16x32_bf16 v[112:115], v[164:167], v[172:175], v[112:115]
	v_mfma_f32_16x16x32_bf16 v[100:103], v[156:159], v[180:183], v[100:103]
	v_mfma_f32_16x16x32_bf16 v[96:99], v[164:167], v[180:183], v[96:99]
	v_mfma_f32_16x16x32_bf16 v[84:87], v[156:159], v[188:191], v[84:87]
	v_mfma_f32_16x16x32_bf16 v[80:83], v[164:167], v[188:191], v[80:83]
	v_mfma_f32_16x16x32_bf16 v[68:71], v[156:159], v[196:199], v[68:71]
	v_mfma_f32_16x16x32_bf16 v[64:67], v[164:167], v[196:199], v[64:67]
	s_barrier
	s_mov_b32 m0, s69
	v_lshl_add_u64 v[200:201], s[38:39], 0, v[232:233]
	ds_read_b128 v[168:171], v155 offset:16384
	ds_read_b128 v[172:175], v155 offset:17408
	ds_read_b128 v[176:179], v155 offset:18432
	ds_read_b128 v[180:183], v155 offset:19456
	ds_read_b128 v[184:187], v155 offset:20480
	ds_read_b128 v[188:191], v155 offset:21504
	ds_read_b128 v[192:195], v155 offset:22528
	ds_read_b128 v[196:199], v155 offset:23552
	global_load_lds_dwordx4 v[200:201], off
	v_lshl_add_u64 v[202:203], s[38:39], 0, v[132:133]
	s_mov_b32 m0, s66
	v_lshl_add_u64 v[204:205], s[40:41], 0, v[232:233]
	global_load_lds_dwordx4 v[202:203], off
	s_mov_b32 m0, s68
	v_lshl_add_u64 v[206:207], s[36:37], 0, v[130:131]
	global_load_lds_dwordx4 v[204:205], off
	v_lshl_add_u64 v[204:205], s[40:41], 0, v[132:133]
	s_mov_b32 m0, s67
	s_nop 0
	global_load_lds_dwordx4 v[204:205], off
	v_lshl_add_u64 v[204:205], s[36:37], 0, v[128:129]
	s_mov_b32 m0, s51
	s_nop 0
	global_load_lds_dwordx4 v[204:205], off
	s_mov_b32 m0, s52
	s_nop 0
	global_load_lds_dwordx4 v[206:207], off
	s_waitcnt vmcnt(8) lgkmcnt(0)
	s_barrier
	v_mfma_f32_16x16x32_bf16 v[60:63], v[134:137], v[168:171], v[60:63]
	v_mfma_f32_16x16x32_bf16 v[56:59], v[142:145], v[168:171], v[56:59]
	v_mfma_f32_16x16x32_bf16 v[44:47], v[134:137], v[176:179], v[44:47]
	v_mfma_f32_16x16x32_bf16 v[40:43], v[142:145], v[176:179], v[40:43]
	v_mfma_f32_16x16x32_bf16 v[28:31], v[134:137], v[184:187], v[28:31]
	v_mfma_f32_16x16x32_bf16 v[24:27], v[142:145], v[184:187], v[24:27]
	v_mfma_f32_16x16x32_bf16 v[12:15], v[134:137], v[192:195], v[12:15]
	v_mfma_f32_16x16x32_bf16 v[8:11], v[142:145], v[192:195], v[8:11]
	v_mfma_f32_16x16x32_bf16 v[60:63], v[138:141], v[172:175], v[60:63]
	v_mfma_f32_16x16x32_bf16 v[56:59], v[146:149], v[172:175], v[56:59]
	v_mfma_f32_16x16x32_bf16 v[44:47], v[138:141], v[180:183], v[44:47]
	v_mfma_f32_16x16x32_bf16 v[40:43], v[146:149], v[180:183], v[40:43]
	v_mfma_f32_16x16x32_bf16 v[28:31], v[138:141], v[188:191], v[28:31]
	v_mfma_f32_16x16x32_bf16 v[24:27], v[146:149], v[188:191], v[24:27]
	v_mfma_f32_16x16x32_bf16 v[12:15], v[138:141], v[196:199], v[12:15]
	v_mfma_f32_16x16x32_bf16 v[8:11], v[146:149], v[196:199], v[8:11]
	v_mfma_f32_16x16x32_bf16 v[52:55], v[150:153], v[168:171], v[52:55]
	v_mfma_f32_16x16x32_bf16 v[48:51], v[160:163], v[168:171], v[48:51]
	v_mfma_f32_16x16x32_bf16 v[36:39], v[150:153], v[176:179], v[36:39]
	v_mfma_f32_16x16x32_bf16 v[32:35], v[160:163], v[176:179], v[32:35]
	v_mfma_f32_16x16x32_bf16 v[20:23], v[150:153], v[184:187], v[20:23]
	v_mfma_f32_16x16x32_bf16 v[16:19], v[160:163], v[184:187], v[16:19]
	v_mfma_f32_16x16x32_bf16 v[4:7], v[150:153], v[192:195], v[4:7]
	v_mfma_f32_16x16x32_bf16 v[0:3], v[160:163], v[192:195], v[0:3]
	v_mfma_f32_16x16x32_bf16 v[52:55], v[156:159], v[172:175], v[52:55]
	v_mfma_f32_16x16x32_bf16 v[48:51], v[164:167], v[172:175], v[48:51]
	v_mfma_f32_16x16x32_bf16 v[36:39], v[156:159], v[180:183], v[36:39]
	v_mfma_f32_16x16x32_bf16 v[32:35], v[164:167], v[180:183], v[32:35]
	v_mfma_f32_16x16x32_bf16 v[20:23], v[156:159], v[188:191], v[20:23]
	v_mfma_f32_16x16x32_bf16 v[16:19], v[164:167], v[188:191], v[16:19]
	v_mfma_f32_16x16x32_bf16 v[4:7], v[156:159], v[196:199], v[4:7]
	v_mfma_f32_16x16x32_bf16 v[0:3], v[164:167], v[196:199], v[0:3]
	s_barrier
	v_add_u32_e32 v146, s65, v154
	v_add_u32_e32 v164, s64, v154
	ds_read_b128 v[134:137], v146
	ds_read_b128 v[138:141], v146 offset:1024
	ds_read_b128 v[142:145], v146 offset:2048
	ds_read_b128 v[146:149], v146 offset:3072
	ds_read_b128 v[150:153], v164
	ds_read_b128 v[156:159], v164 offset:1024
	ds_read_b128 v[160:163], v164 offset:2048
	ds_read_b128 v[164:167], v164 offset:3072
	s_mov_b32 m0, s53
	v_lshl_add_u64 v[208:209], s[34:35], 0, v[128:129]
	ds_read_b128 v[168:171], v155 offset:32768
	ds_read_b128 v[172:175], v155 offset:33792
	ds_read_b128 v[176:179], v155 offset:34816
	ds_read_b128 v[180:183], v155 offset:35840
	ds_read_b128 v[184:187], v155 offset:36864
	ds_read_b128 v[188:191], v155 offset:37888
	ds_read_b128 v[192:195], v155 offset:38912
	ds_read_b128 v[196:199], v155 offset:39936
	global_load_lds_dwordx4 v[208:209], off
	v_lshl_add_u64 v[208:209], s[34:35], 0, v[130:131]
	s_mov_b32 m0, s54
	s_nop 0
	global_load_lds_dwordx4 v[208:209], off
	s_waitcnt vmcnt(8) lgkmcnt(0)
	s_barrier
	v_mfma_f32_16x16x32_bf16 v[124:127], v[134:137], v[168:171], v[124:127]
	v_mfma_f32_16x16x32_bf16 v[120:123], v[142:145], v[168:171], v[120:123]
	v_mfma_f32_16x16x32_bf16 v[108:111], v[134:137], v[176:179], v[108:111]
	v_mfma_f32_16x16x32_bf16 v[104:107], v[142:145], v[176:179], v[104:107]
	v_mfma_f32_16x16x32_bf16 v[92:95], v[134:137], v[184:187], v[92:95]
	v_mfma_f32_16x16x32_bf16 v[88:91], v[142:145], v[184:187], v[88:91]
	v_mfma_f32_16x16x32_bf16 v[76:79], v[134:137], v[192:195], v[76:79]
	v_mfma_f32_16x16x32_bf16 v[72:75], v[142:145], v[192:195], v[72:75]
	v_mfma_f32_16x16x32_bf16 v[124:127], v[138:141], v[172:175], v[124:127]
	v_mfma_f32_16x16x32_bf16 v[120:123], v[146:149], v[172:175], v[120:123]
	v_mfma_f32_16x16x32_bf16 v[108:111], v[138:141], v[180:183], v[108:111]
	v_mfma_f32_16x16x32_bf16 v[104:107], v[146:149], v[180:183], v[104:107]
	v_mfma_f32_16x16x32_bf16 v[92:95], v[138:141], v[188:191], v[92:95]
	v_mfma_f32_16x16x32_bf16 v[88:91], v[146:149], v[188:191], v[88:91]
	v_mfma_f32_16x16x32_bf16 v[76:79], v[138:141], v[196:199], v[76:79]
	v_mfma_f32_16x16x32_bf16 v[72:75], v[146:149], v[196:199], v[72:75]
	v_mfma_f32_16x16x32_bf16 v[116:119], v[150:153], v[168:171], v[116:119]
	v_mfma_f32_16x16x32_bf16 v[112:115], v[160:163], v[168:171], v[112:115]
	v_mfma_f32_16x16x32_bf16 v[100:103], v[150:153], v[176:179], v[100:103]
	v_mfma_f32_16x16x32_bf16 v[96:99], v[160:163], v[176:179], v[96:99]
	v_mfma_f32_16x16x32_bf16 v[84:87], v[150:153], v[184:187], v[84:87]
	v_mfma_f32_16x16x32_bf16 v[80:83], v[160:163], v[184:187], v[80:83]
	v_mfma_f32_16x16x32_bf16 v[68:71], v[150:153], v[192:195], v[68:71]
	v_mfma_f32_16x16x32_bf16 v[64:67], v[160:163], v[192:195], v[64:67]
	v_mfma_f32_16x16x32_bf16 v[116:119], v[156:159], v[172:175], v[116:119]
	v_mfma_f32_16x16x32_bf16 v[112:115], v[164:167], v[172:175], v[112:115]
	v_mfma_f32_16x16x32_bf16 v[100:103], v[156:159], v[180:183], v[100:103]
	v_mfma_f32_16x16x32_bf16 v[96:99], v[164:167], v[180:183], v[96:99]
	v_mfma_f32_16x16x32_bf16 v[84:87], v[156:159], v[188:191], v[84:87]
	v_mfma_f32_16x16x32_bf16 v[80:83], v[164:167], v[188:191], v[80:83]
	v_mfma_f32_16x16x32_bf16 v[68:71], v[156:159], v[196:199], v[68:71]
	v_mfma_f32_16x16x32_bf16 v[64:67], v[164:167], v[196:199], v[64:67]
	s_barrier
	s_mov_b32 m0, s63
	v_lshl_add_u64 v[200:201], v[200:201], 0, s[94:95]
	ds_read_b128 v[168:171], v155 offset:49152
	ds_read_b128 v[172:175], v155 offset:50176
	ds_read_b128 v[176:179], v155 offset:51200
	ds_read_b128 v[180:183], v155 offset:52224
	ds_read_b128 v[184:187], v155 offset:53248
	ds_read_b128 v[188:191], v155 offset:54272
	ds_read_b128 v[192:195], v155 offset:55296
	ds_read_b128 v[196:199], v155 offset:56320
	global_load_lds_dwordx4 v[200:201], off
	v_lshl_add_u64 v[200:201], v[202:203], 0, s[94:95]
	s_mov_b32 m0, s62
	s_nop 0
	global_load_lds_dwordx4 v[200:201], off
	v_lshl_add_u64 v[200:201], s[30:31], 0, v[232:233]
	s_mov_b32 m0, s71
	s_nop 0
	global_load_lds_dwordx4 v[200:201], off
	v_lshl_add_u64 v[200:201], s[30:31], 0, v[132:133]
	s_mov_b32 m0, s70
	s_nop 0
	global_load_lds_dwordx4 v[200:201], off
	v_lshl_add_u64 v[200:201], v[204:205], 0, s[94:95]
	s_mov_b32 m0, s57
	s_nop 0
	global_load_lds_dwordx4 v[200:201], off
	v_lshl_add_u64 v[200:201], v[206:207], 0, s[94:95]
	s_mov_b32 m0, s58
	s_nop 0
	global_load_lds_dwordx4 v[200:201], off
	s_waitcnt vmcnt(8) lgkmcnt(0)
	s_barrier
	v_mfma_f32_16x16x32_bf16 v[60:63], v[134:137], v[168:171], v[60:63]
	v_mfma_f32_16x16x32_bf16 v[56:59], v[142:145], v[168:171], v[56:59]
	v_mfma_f32_16x16x32_bf16 v[44:47], v[134:137], v[176:179], v[44:47]
	v_mfma_f32_16x16x32_bf16 v[40:43], v[142:145], v[176:179], v[40:43]
	v_mfma_f32_16x16x32_bf16 v[28:31], v[134:137], v[184:187], v[28:31]
	v_mfma_f32_16x16x32_bf16 v[24:27], v[142:145], v[184:187], v[24:27]
	v_mfma_f32_16x16x32_bf16 v[12:15], v[134:137], v[192:195], v[12:15]
	v_mfma_f32_16x16x32_bf16 v[8:11], v[142:145], v[192:195], v[8:11]
	v_mfma_f32_16x16x32_bf16 v[60:63], v[138:141], v[172:175], v[60:63]
	v_mfma_f32_16x16x32_bf16 v[56:59], v[146:149], v[172:175], v[56:59]
	v_mfma_f32_16x16x32_bf16 v[44:47], v[138:141], v[180:183], v[44:47]
	v_mfma_f32_16x16x32_bf16 v[40:43], v[146:149], v[180:183], v[40:43]
	v_mfma_f32_16x16x32_bf16 v[28:31], v[138:141], v[188:191], v[28:31]
	v_mfma_f32_16x16x32_bf16 v[24:27], v[146:149], v[188:191], v[24:27]
	v_mfma_f32_16x16x32_bf16 v[12:15], v[138:141], v[196:199], v[12:15]
	v_mfma_f32_16x16x32_bf16 v[8:11], v[146:149], v[196:199], v[8:11]
	v_mfma_f32_16x16x32_bf16 v[52:55], v[150:153], v[168:171], v[52:55]
	v_mfma_f32_16x16x32_bf16 v[48:51], v[160:163], v[168:171], v[48:51]
	v_mfma_f32_16x16x32_bf16 v[36:39], v[150:153], v[176:179], v[36:39]
	v_mfma_f32_16x16x32_bf16 v[32:35], v[160:163], v[176:179], v[32:35]
	v_mfma_f32_16x16x32_bf16 v[20:23], v[150:153], v[184:187], v[20:23]
	v_mfma_f32_16x16x32_bf16 v[16:19], v[160:163], v[184:187], v[16:19]
	v_mfma_f32_16x16x32_bf16 v[4:7], v[150:153], v[192:195], v[4:7]
	v_mfma_f32_16x16x32_bf16 v[0:3], v[160:163], v[192:195], v[0:3]
	v_mfma_f32_16x16x32_bf16 v[52:55], v[156:159], v[172:175], v[52:55]
	v_mfma_f32_16x16x32_bf16 v[48:51], v[164:167], v[172:175], v[48:51]
	v_mfma_f32_16x16x32_bf16 v[36:39], v[156:159], v[180:183], v[36:39]
	v_mfma_f32_16x16x32_bf16 v[32:35], v[164:167], v[180:183], v[32:35]
	v_mfma_f32_16x16x32_bf16 v[20:23], v[156:159], v[188:191], v[20:23]
	v_mfma_f32_16x16x32_bf16 v[16:19], v[164:167], v[188:191], v[16:19]
	v_mfma_f32_16x16x32_bf16 v[4:7], v[156:159], v[196:199], v[4:7]
	v_mfma_f32_16x16x32_bf16 v[0:3], v[164:167], v[196:199], v[0:3]
	s_barrier
	s_movk_i32 s34, 0x100
	s_andn2_b64 vcc, exec, s[28:29]
	s_mov_b64 s[30:31], -1
	s_mov_b64 s[28:29], 0
	s_cbranch_vccz .LBB0_311
	s_and_b64 vcc, exec, s[12:13]
	s_cbranch_vccz .LBB0_314
	s_barrier

.LBB0_369:
	s_add_u32 s35, s26, s34
	s_addc_u32 s40, s27, 0
	s_add_u32 s38, s35, 0x100
	s_addc_u32 s39, s40, 0
	s_and_b64 s[36:37], s[30:31], exec
	s_cselect_b32 s37, s5, s39
	s_cselect_b32 s36, s17, s38
	s_add_u32 s34, s24, s34
	s_addc_u32 s38, s25, 0
	s_add_u32 s34, s34, 0x100
	s_addc_u32 s38, s38, 0
	s_add_i32 s70, 0, 0x10000
	s_and_b64 s[30:31], s[30:31], exec
	s_cselect_b32 s39, s15, s38
	s_cselect_b32 s38, s23, s34
	s_add_i32 s31, 0, 0x14000
	s_add_u32 s42, s35, 0x100080
	s_addc_u32 s43, s40, 0
	s_add_i32 s69, s70, s50
	s_add_i32 m0, s51, 0xc000
	s_add_i32 s72, s51, 0xe000
	s_add_i32 s66, s69, 0x2000
	s_add_u32 s40, s38, 0x10000
	v_add_u32_e32 v146, s70, v168
	v_add_u32_e32 v162, s31, v168
	s_addc_u32 s41, s39, 0
	s_add_i32 s68, s31, s50
	ds_read_b128 v[134:137], v146
	ds_read_b128 v[138:141], v146 offset:1024
	ds_read_b128 v[142:145], v146 offset:2048
	ds_read_b128 v[146:149], v146 offset:3072
	ds_read_b128 v[150:153], v162
	ds_read_b128 v[154:157], v162 offset:1024
	ds_read_b128 v[158:161], v162 offset:2048
	ds_read_b128 v[162:165], v162 offset:3072
	s_add_i32 s67, s68, 0x2000
	s_add_i32 s65, 0, 0x18000
	s_add_i32 s64, 0, 0x1c000
	s_add_u32 s34, s36, 0x100000
	s_addc_u32 s35, s37, 0
	s_add_i32 s63, s65, s50
	s_add_i32 s62, s63, 0x2000
	s_add_u32 s30, s38, 0x10080
	s_addc_u32 s31, s39, 0
	s_add_i32 s71, s64, s50
	s_add_i32 s70, s71, 0x2000
	v_lshl_add_u64 v[166:167], s[42:43], 0, v[128:129]
	ds_read_b128 v[170:173], v169
	ds_read_b128 v[174:177], v169 offset:1024
	ds_read_b128 v[178:181], v169 offset:2048
	ds_read_b128 v[182:185], v169 offset:3072
	ds_read_b128 v[186:189], v169 offset:4096
	ds_read_b128 v[190:193], v169 offset:5120
	ds_read_b128 v[194:197], v169 offset:6144
	ds_read_b128 v[198:201], v169 offset:7168
	global_load_lds_dwordx4 v[166:167], off
	v_lshl_add_u64 v[166:167], s[42:43], 0, v[130:131]
	s_mov_b32 m0, s72
	s_nop 0
	global_load_lds_dwordx4 v[166:167], off
	s_waitcnt vmcnt(8) lgkmcnt(0)
	s_barrier
	v_mfma_f32_16x16x32_bf16 v[124:127], v[134:137], v[170:173], v[124:127]
	v_mfma_f32_16x16x32_bf16 v[120:123], v[142:145], v[170:173], v[120:123]
	v_mfma_f32_16x16x32_bf16 v[108:111], v[134:137], v[178:181], v[108:111]
	v_mfma_f32_16x16x32_bf16 v[104:107], v[142:145], v[178:181], v[104:107]
	v_mfma_f32_16x16x32_bf16 v[92:95], v[134:137], v[186:189], v[92:95]
	v_mfma_f32_16x16x32_bf16 v[88:91], v[142:145], v[186:189], v[88:91]
	v_mfma_f32_16x16x32_bf16 v[76:79], v[134:137], v[194:197], v[76:79]
	v_mfma_f32_16x16x32_bf16 v[72:75], v[142:145], v[194:197], v[72:75]
	v_mfma_f32_16x16x32_bf16 v[124:127], v[138:141], v[174:177], v[124:127]
	v_mfma_f32_16x16x32_bf16 v[120:123], v[146:149], v[174:177], v[120:123]
	v_mfma_f32_16x16x32_bf16 v[108:111], v[138:141], v[182:185], v[108:111]
	v_mfma_f32_16x16x32_bf16 v[104:107], v[146:149], v[182:185], v[104:107]
	v_mfma_f32_16x16x32_bf16 v[92:95], v[138:141], v[190:193], v[92:95]
	v_mfma_f32_16x16x32_bf16 v[88:91], v[146:149], v[190:193], v[88:91]
	v_mfma_f32_16x16x32_bf16 v[76:79], v[138:141], v[198:201], v[76:79]
	v_mfma_f32_16x16x32_bf16 v[72:75], v[146:149], v[198:201], v[72:75]
	v_mfma_f32_16x16x32_bf16 v[116:119], v[150:153], v[170:173], v[116:119]
	v_mfma_f32_16x16x32_bf16 v[112:115], v[158:161], v[170:173], v[112:115]
	v_mfma_f32_16x16x32_bf16 v[100:103], v[150:153], v[178:181], v[100:103]
	v_mfma_f32_16x16x32_bf16 v[96:99], v[158:161], v[178:181], v[96:99]
	v_mfma_f32_16x16x32_bf16 v[84:87], v[150:153], v[186:189], v[84:87]
	v_mfma_f32_16x16x32_bf16 v[80:83], v[158:161], v[186:189], v[80:83]
	v_mfma_f32_16x16x32_bf16 v[68:71], v[150:153], v[194:197], v[68:71]
	v_mfma_f32_16x16x32_bf16 v[64:67], v[158:161], v[194:197], v[64:67]
	v_mfma_f32_16x16x32_bf16 v[116:119], v[154:157], v[174:177], v[116:119]
	v_mfma_f32_16x16x32_bf16 v[112:115], v[162:165], v[174:177], v[112:115]
	v_mfma_f32_16x16x32_bf16 v[100:103], v[154:157], v[182:185], v[100:103]
	v_mfma_f32_16x16x32_bf16 v[96:99], v[162:165], v[182:185], v[96:99]
	v_mfma_f32_16x16x32_bf16 v[84:87], v[154:157], v[190:193], v[84:87]
	v_mfma_f32_16x16x32_bf16 v[80:83], v[162:165], v[190:193], v[80:83]
	v_mfma_f32_16x16x32_bf16 v[68:71], v[154:157], v[198:201], v[68:71]
	v_mfma_f32_16x16x32_bf16 v[64:67], v[162:165], v[198:201], v[64:67]
	s_barrier
	s_mov_b32 m0, s69
	v_lshl_add_u64 v[166:167], s[38:39], 0, v[232:233]
	ds_read_b128 v[170:173], v169 offset:16384
	ds_read_b128 v[174:177], v169 offset:17408
	ds_read_b128 v[178:181], v169 offset:18432
	ds_read_b128 v[182:185], v169 offset:19456
	ds_read_b128 v[186:189], v169 offset:20480
	ds_read_b128 v[190:193], v169 offset:21504
	ds_read_b128 v[194:197], v169 offset:22528
	ds_read_b128 v[198:201], v169 offset:23552
	global_load_lds_dwordx4 v[166:167], off
	v_lshl_add_u64 v[202:203], s[38:39], 0, v[132:133]
	s_mov_b32 m0, s66
	v_lshl_add_u64 v[204:205], s[40:41], 0, v[232:233]
	global_load_lds_dwordx4 v[202:203], off
	s_mov_b32 m0, s68
	v_lshl_add_u64 v[206:207], s[36:37], 0, v[130:131]
	global_load_lds_dwordx4 v[204:205], off
	v_lshl_add_u64 v[204:205], s[40:41], 0, v[132:133]
	s_mov_b32 m0, s67
	s_nop 0
	global_load_lds_dwordx4 v[204:205], off
	v_lshl_add_u64 v[204:205], s[36:37], 0, v[128:129]
	s_mov_b32 m0, s51
	s_nop 0
	global_load_lds_dwordx4 v[204:205], off
	s_mov_b32 m0, s52
	s_nop 0
	global_load_lds_dwordx4 v[206:207], off
	s_waitcnt vmcnt(8) lgkmcnt(0)
	s_barrier
	v_mfma_f32_16x16x32_bf16 v[60:63], v[134:137], v[170:173], v[60:63]
	v_mfma_f32_16x16x32_bf16 v[56:59], v[142:145], v[170:173], v[56:59]
	v_mfma_f32_16x16x32_bf16 v[44:47], v[134:137], v[178:181], v[44:47]
	v_mfma_f32_16x16x32_bf16 v[40:43], v[142:145], v[178:181], v[40:43]
	v_mfma_f32_16x16x32_bf16 v[28:31], v[134:137], v[186:189], v[28:31]
	v_mfma_f32_16x16x32_bf16 v[24:27], v[142:145], v[186:189], v[24:27]
	v_mfma_f32_16x16x32_bf16 v[12:15], v[134:137], v[194:197], v[12:15]
	v_mfma_f32_16x16x32_bf16 v[8:11], v[142:145], v[194:197], v[8:11]
	v_mfma_f32_16x16x32_bf16 v[60:63], v[138:141], v[174:177], v[60:63]
	v_mfma_f32_16x16x32_bf16 v[56:59], v[146:149], v[174:177], v[56:59]
	v_mfma_f32_16x16x32_bf16 v[44:47], v[138:141], v[182:185], v[44:47]
	v_mfma_f32_16x16x32_bf16 v[40:43], v[146:149], v[182:185], v[40:43]
	v_mfma_f32_16x16x32_bf16 v[28:31], v[138:141], v[190:193], v[28:31]
	v_mfma_f32_16x16x32_bf16 v[24:27], v[146:149], v[190:193], v[24:27]
	v_mfma_f32_16x16x32_bf16 v[12:15], v[138:141], v[198:201], v[12:15]
	v_mfma_f32_16x16x32_bf16 v[8:11], v[146:149], v[198:201], v[8:11]
	v_mfma_f32_16x16x32_bf16 v[52:55], v[150:153], v[170:173], v[52:55]
	v_mfma_f32_16x16x32_bf16 v[48:51], v[158:161], v[170:173], v[48:51]
	v_mfma_f32_16x16x32_bf16 v[36:39], v[150:153], v[178:181], v[36:39]
	v_mfma_f32_16x16x32_bf16 v[32:35], v[158:161], v[178:181], v[32:35]
	v_mfma_f32_16x16x32_bf16 v[20:23], v[150:153], v[186:189], v[20:23]
	v_mfma_f32_16x16x32_bf16 v[16:19], v[158:161], v[186:189], v[16:19]
	v_mfma_f32_16x16x32_bf16 v[4:7], v[150:153], v[194:197], v[4:7]
	v_mfma_f32_16x16x32_bf16 v[0:3], v[158:161], v[194:197], v[0:3]
	v_mfma_f32_16x16x32_bf16 v[52:55], v[154:157], v[174:177], v[52:55]
	v_mfma_f32_16x16x32_bf16 v[48:51], v[162:165], v[174:177], v[48:51]
	v_mfma_f32_16x16x32_bf16 v[36:39], v[154:157], v[182:185], v[36:39]
	v_mfma_f32_16x16x32_bf16 v[32:35], v[162:165], v[182:185], v[32:35]
	v_mfma_f32_16x16x32_bf16 v[20:23], v[154:157], v[190:193], v[20:23]
	v_mfma_f32_16x16x32_bf16 v[16:19], v[162:165], v[190:193], v[16:19]
	v_mfma_f32_16x16x32_bf16 v[4:7], v[154:157], v[198:201], v[4:7]
	v_mfma_f32_16x16x32_bf16 v[0:3], v[162:165], v[198:201], v[0:3]
	s_barrier
	v_add_u32_e32 v146, s65, v168
	v_add_u32_e32 v162, s64, v168
	ds_read_b128 v[134:137], v146
	ds_read_b128 v[138:141], v146 offset:1024
	ds_read_b128 v[142:145], v146 offset:2048
	ds_read_b128 v[146:149], v146 offset:3072
	ds_read_b128 v[150:153], v162
	ds_read_b128 v[154:157], v162 offset:1024
	ds_read_b128 v[158:161], v162 offset:2048
	ds_read_b128 v[162:165], v162 offset:3072
	s_mov_b32 m0, s53
	v_lshl_add_u64 v[208:209], s[34:35], 0, v[128:129]
	ds_read_b128 v[170:173], v169 offset:32768
	ds_read_b128 v[174:177], v169 offset:33792
	ds_read_b128 v[178:181], v169 offset:34816
	ds_read_b128 v[182:185], v169 offset:35840
	ds_read_b128 v[186:189], v169 offset:36864
	ds_read_b128 v[190:193], v169 offset:37888
	ds_read_b128 v[194:197], v169 offset:38912
	ds_read_b128 v[198:201], v169 offset:39936
	global_load_lds_dwordx4 v[208:209], off
	v_lshl_add_u64 v[208:209], s[34:35], 0, v[130:131]
	s_mov_b32 m0, s54
	s_nop 0
	global_load_lds_dwordx4 v[208:209], off
	s_waitcnt vmcnt(8) lgkmcnt(0)
	s_barrier
	v_mfma_f32_16x16x32_bf16 v[124:127], v[134:137], v[170:173], v[124:127]
	v_mfma_f32_16x16x32_bf16 v[120:123], v[142:145], v[170:173], v[120:123]
	v_mfma_f32_16x16x32_bf16 v[108:111], v[134:137], v[178:181], v[108:111]
	v_mfma_f32_16x16x32_bf16 v[104:107], v[142:145], v[178:181], v[104:107]
	v_mfma_f32_16x16x32_bf16 v[92:95], v[134:137], v[186:189], v[92:95]
	v_mfma_f32_16x16x32_bf16 v[88:91], v[142:145], v[186:189], v[88:91]
	v_mfma_f32_16x16x32_bf16 v[76:79], v[134:137], v[194:197], v[76:79]
	v_mfma_f32_16x16x32_bf16 v[72:75], v[142:145], v[194:197], v[72:75]
	v_mfma_f32_16x16x32_bf16 v[124:127], v[138:141], v[174:177], v[124:127]
	v_mfma_f32_16x16x32_bf16 v[120:123], v[146:149], v[174:177], v[120:123]
	v_mfma_f32_16x16x32_bf16 v[108:111], v[138:141], v[182:185], v[108:111]
	v_mfma_f32_16x16x32_bf16 v[104:107], v[146:149], v[182:185], v[104:107]
	v_mfma_f32_16x16x32_bf16 v[92:95], v[138:141], v[190:193], v[92:95]
	v_mfma_f32_16x16x32_bf16 v[88:91], v[146:149], v[190:193], v[88:91]
	v_mfma_f32_16x16x32_bf16 v[76:79], v[138:141], v[198:201], v[76:79]
	v_mfma_f32_16x16x32_bf16 v[72:75], v[146:149], v[198:201], v[72:75]
	v_mfma_f32_16x16x32_bf16 v[116:119], v[150:153], v[170:173], v[116:119]
	v_mfma_f32_16x16x32_bf16 v[112:115], v[158:161], v[170:173], v[112:115]
	v_mfma_f32_16x16x32_bf16 v[100:103], v[150:153], v[178:181], v[100:103]
	v_mfma_f32_16x16x32_bf16 v[96:99], v[158:161], v[178:181], v[96:99]
	v_mfma_f32_16x16x32_bf16 v[84:87], v[150:153], v[186:189], v[84:87]
	v_mfma_f32_16x16x32_bf16 v[80:83], v[158:161], v[186:189], v[80:83]
	v_mfma_f32_16x16x32_bf16 v[68:71], v[150:153], v[194:197], v[68:71]
	v_mfma_f32_16x16x32_bf16 v[64:67], v[158:161], v[194:197], v[64:67]
	v_mfma_f32_16x16x32_bf16 v[116:119], v[154:157], v[174:177], v[116:119]
	v_mfma_f32_16x16x32_bf16 v[112:115], v[162:165], v[174:177], v[112:115]
	v_mfma_f32_16x16x32_bf16 v[100:103], v[154:157], v[182:185], v[100:103]
	v_mfma_f32_16x16x32_bf16 v[96:99], v[162:165], v[182:185], v[96:99]
	v_mfma_f32_16x16x32_bf16 v[84:87], v[154:157], v[190:193], v[84:87]
	v_mfma_f32_16x16x32_bf16 v[80:83], v[162:165], v[190:193], v[80:83]
	v_mfma_f32_16x16x32_bf16 v[68:71], v[154:157], v[198:201], v[68:71]
	v_mfma_f32_16x16x32_bf16 v[64:67], v[162:165], v[198:201], v[64:67]
	s_barrier
	s_mov_b32 m0, s63
	v_lshl_add_u64 v[166:167], v[166:167], 0, s[94:95]
	ds_read_b128 v[170:173], v169 offset:49152
	ds_read_b128 v[174:177], v169 offset:50176
	ds_read_b128 v[178:181], v169 offset:51200
	ds_read_b128 v[182:185], v169 offset:52224
	ds_read_b128 v[186:189], v169 offset:53248
	ds_read_b128 v[190:193], v169 offset:54272
	ds_read_b128 v[194:197], v169 offset:55296
	ds_read_b128 v[198:201], v169 offset:56320
	global_load_lds_dwordx4 v[166:167], off
	v_lshl_add_u64 v[166:167], v[202:203], 0, s[94:95]
	s_mov_b32 m0, s62
	s_nop 0
	global_load_lds_dwordx4 v[166:167], off
	v_lshl_add_u64 v[166:167], s[30:31], 0, v[232:233]
	s_mov_b32 m0, s71
	s_nop 0
	global_load_lds_dwordx4 v[166:167], off
	v_lshl_add_u64 v[166:167], s[30:31], 0, v[132:133]
	s_mov_b32 m0, s70
	s_nop 0
	global_load_lds_dwordx4 v[166:167], off
	v_lshl_add_u64 v[166:167], v[204:205], 0, s[94:95]
	s_mov_b32 m0, s57
	s_nop 0
	global_load_lds_dwordx4 v[166:167], off
	v_lshl_add_u64 v[166:167], v[206:207], 0, s[94:95]
	s_mov_b32 m0, s58
	s_nop 0
	global_load_lds_dwordx4 v[166:167], off
	s_waitcnt vmcnt(8) lgkmcnt(0)
	s_barrier
	v_mfma_f32_16x16x32_bf16 v[60:63], v[134:137], v[170:173], v[60:63]
	v_mfma_f32_16x16x32_bf16 v[56:59], v[142:145], v[170:173], v[56:59]
	v_mfma_f32_16x16x32_bf16 v[44:47], v[134:137], v[178:181], v[44:47]
	v_mfma_f32_16x16x32_bf16 v[40:43], v[142:145], v[178:181], v[40:43]
	v_mfma_f32_16x16x32_bf16 v[28:31], v[134:137], v[186:189], v[28:31]
	v_mfma_f32_16x16x32_bf16 v[24:27], v[142:145], v[186:189], v[24:27]
	v_mfma_f32_16x16x32_bf16 v[12:15], v[134:137], v[194:197], v[12:15]
	v_mfma_f32_16x16x32_bf16 v[8:11], v[142:145], v[194:197], v[8:11]
	v_mfma_f32_16x16x32_bf16 v[60:63], v[138:141], v[174:177], v[60:63]
	v_mfma_f32_16x16x32_bf16 v[56:59], v[146:149], v[174:177], v[56:59]
	v_mfma_f32_16x16x32_bf16 v[44:47], v[138:141], v[182:185], v[44:47]
	v_mfma_f32_16x16x32_bf16 v[40:43], v[146:149], v[182:185], v[40:43]
	v_mfma_f32_16x16x32_bf16 v[28:31], v[138:141], v[190:193], v[28:31]
	v_mfma_f32_16x16x32_bf16 v[24:27], v[146:149], v[190:193], v[24:27]
	v_mfma_f32_16x16x32_bf16 v[12:15], v[138:141], v[198:201], v[12:15]
	v_mfma_f32_16x16x32_bf16 v[8:11], v[146:149], v[198:201], v[8:11]
	v_mfma_f32_16x16x32_bf16 v[52:55], v[150:153], v[170:173], v[52:55]
	v_mfma_f32_16x16x32_bf16 v[48:51], v[158:161], v[170:173], v[48:51]
	v_mfma_f32_16x16x32_bf16 v[36:39], v[150:153], v[178:181], v[36:39]
	v_mfma_f32_16x16x32_bf16 v[32:35], v[158:161], v[178:181], v[32:35]
	v_mfma_f32_16x16x32_bf16 v[20:23], v[150:153], v[186:189], v[20:23]
	v_mfma_f32_16x16x32_bf16 v[16:19], v[158:161], v[186:189], v[16:19]
	v_mfma_f32_16x16x32_bf16 v[4:7], v[150:153], v[194:197], v[4:7]
	v_mfma_f32_16x16x32_bf16 v[0:3], v[158:161], v[194:197], v[0:3]
	v_mfma_f32_16x16x32_bf16 v[52:55], v[154:157], v[174:177], v[52:55]
	v_mfma_f32_16x16x32_bf16 v[48:51], v[162:165], v[174:177], v[48:51]
	v_mfma_f32_16x16x32_bf16 v[36:39], v[154:157], v[182:185], v[36:39]
	v_mfma_f32_16x16x32_bf16 v[32:35], v[162:165], v[182:185], v[32:35]
	v_mfma_f32_16x16x32_bf16 v[20:23], v[154:157], v[190:193], v[20:23]
	v_mfma_f32_16x16x32_bf16 v[16:19], v[162:165], v[190:193], v[16:19]
	v_mfma_f32_16x16x32_bf16 v[4:7], v[154:157], v[198:201], v[4:7]
	v_mfma_f32_16x16x32_bf16 v[0:3], v[162:165], v[198:201], v[0:3]
	s_barrier
	s_movk_i32 s34, 0x100
	s_andn2_b64 vcc, exec, s[28:29]
	s_mov_b64 s[30:31], -1
	s_mov_b64 s[28:29], 0
	s_cbranch_vccz .LBB0_369
	s_and_b64 vcc, exec, s[12:13]
	s_cbranch_vccz .LBB0_372
	s_barrier

.LBB0_911:
	s_ashr_i32 s15, s14, 31
	s_lshl_b64 s[16:17], s[14:15], 19
	s_add_u32 s16, s30, s16
	s_addc_u32 s17, s31, s17
	s_and_b64 s[18:19], s[2:3], exec
	s_cselect_b32 s5, s17, s25
	s_cselect_b32 s15, s16, s24
	s_ashr_i32 s13, s12, 31
	s_lshl_b64 s[18:19], s[12:13], 19
	s_add_u32 s18, s34, s18
	s_addc_u32 s19, s35, s19
	s_and_b64 s[26:27], s[2:3], exec
	s_cselect_b32 s13, s19, s23
	s_cselect_b32 s21, s18, s22
	s_add_u32 s48, s22, 0x100
	s_addc_u32 s49, s23, 0
	s_add_u32 s22, s24, 0x40080
	s_addc_u32 s23, s25, 0
	s_mov_b32 s50, -2
	s_add_u32 s24, s22, 0xfffc0080
	s_addc_u32 s25, s23, -1
	s_add_i32 s51, 0, 0x10000
	s_cmp_eq_u32 s50, 12
	s_cselect_b32 s27, s5, s25
	s_cselect_b32 s26, s15, s24
	v_add_u32_e32 v142, s51, v144
	s_cselect_b32 s25, s13, s49
	s_cselect_b32 s24, s21, s48
	s_add_i32 s54, 0, 0x14000
	ds_read_b128 v[138:141], v142
	ds_read_b128 v[146:149], v142 offset:1024
	ds_read_b128 v[150:153], v142 offset:2048
	ds_read_b128 v[154:157], v142 offset:3072
	v_add_u32_e32 v142, s54, v144
	ds_read_b128 v[158:161], v142
	ds_read_b128 v[162:165], v142 offset:1024
	ds_read_b128 v[166:169], v142 offset:2048
	ds_read_b128 v[170:173], v142 offset:3072
	v_lshl_add_u64 v[142:143], s[22:23], 0, v[136:137]
	s_add_i32 m0, s37, 0xc000
	ds_read_b128 v[174:177], v145
	ds_read_b128 v[178:181], v145 offset:1024
	ds_read_b128 v[182:185], v145 offset:2048
	ds_read_b128 v[186:189], v145 offset:3072
	ds_read_b128 v[190:193], v145 offset:4096
	ds_read_b128 v[194:197], v145 offset:5120
	ds_read_b128 v[198:201], v145 offset:6144
	ds_read_b128 v[202:205], v145 offset:7168
	global_load_lds_dwordx4 v[142:143], off
	v_lshl_add_u64 v[142:143], s[22:23], 0, v[134:135]
	s_add_i32 m0, s37, 0xe000
	s_nop 0
	global_load_lds_dwordx4 v[142:143], off
	s_waitcnt vmcnt(8) lgkmcnt(0)
	s_barrier
	v_mfma_f32_16x16x32_bf16 v[124:127], v[138:141], v[174:177], 0
	v_mfma_f32_16x16x32_bf16 v[120:123], v[150:153], v[174:177], 0
	v_mfma_f32_16x16x32_bf16 v[108:111], v[138:141], v[182:185], 0
	v_mfma_f32_16x16x32_bf16 v[104:107], v[150:153], v[182:185], 0
	v_mfma_f32_16x16x32_bf16 v[92:95], v[138:141], v[190:193], 0
	v_mfma_f32_16x16x32_bf16 v[88:91], v[150:153], v[190:193], 0
	v_mfma_f32_16x16x32_bf16 v[76:79], v[138:141], v[198:201], 0
	v_mfma_f32_16x16x32_bf16 v[72:75], v[150:153], v[198:201], 0
	v_mfma_f32_16x16x32_bf16 v[124:127], v[146:149], v[178:181], v[124:127]
	v_mfma_f32_16x16x32_bf16 v[120:123], v[154:157], v[178:181], v[120:123]
	v_mfma_f32_16x16x32_bf16 v[108:111], v[146:149], v[186:189], v[108:111]
	v_mfma_f32_16x16x32_bf16 v[104:107], v[154:157], v[186:189], v[104:107]
	v_mfma_f32_16x16x32_bf16 v[92:95], v[146:149], v[194:197], v[92:95]
	v_mfma_f32_16x16x32_bf16 v[88:91], v[154:157], v[194:197], v[88:91]
	v_mfma_f32_16x16x32_bf16 v[76:79], v[146:149], v[202:205], v[76:79]
	v_mfma_f32_16x16x32_bf16 v[72:75], v[154:157], v[202:205], v[72:75]
	v_mfma_f32_16x16x32_bf16 v[116:119], v[158:161], v[174:177], 0
	v_mfma_f32_16x16x32_bf16 v[112:115], v[166:169], v[174:177], 0
	v_mfma_f32_16x16x32_bf16 v[100:103], v[158:161], v[182:185], 0
	v_mfma_f32_16x16x32_bf16 v[96:99], v[166:169], v[182:185], 0
	v_mfma_f32_16x16x32_bf16 v[84:87], v[158:161], v[190:193], 0
	v_mfma_f32_16x16x32_bf16 v[80:83], v[166:169], v[190:193], 0
	v_mfma_f32_16x16x32_bf16 v[68:71], v[158:161], v[198:201], 0
	v_mfma_f32_16x16x32_bf16 v[64:67], v[166:169], v[198:201], 0
	v_mfma_f32_16x16x32_bf16 v[116:119], v[162:165], v[178:181], v[116:119]
	v_mfma_f32_16x16x32_bf16 v[112:115], v[170:173], v[178:181], v[112:115]
	v_mfma_f32_16x16x32_bf16 v[100:103], v[162:165], v[186:189], v[100:103]
	v_mfma_f32_16x16x32_bf16 v[96:99], v[170:173], v[186:189], v[96:99]
	v_mfma_f32_16x16x32_bf16 v[84:87], v[162:165], v[194:197], v[84:87]
	v_mfma_f32_16x16x32_bf16 v[80:83], v[170:173], v[194:197], v[80:83]
	v_mfma_f32_16x16x32_bf16 v[68:71], v[162:165], v[202:205], v[68:71]
	v_mfma_f32_16x16x32_bf16 v[64:67], v[170:173], v[202:205], v[64:67]
	s_barrier
	s_add_i32 s51, s51, s36
	v_lshl_add_u64 v[142:143], s[24:25], 0, v[232:233]
	s_mov_b32 m0, s51
	ds_read_b128 v[174:177], v145 offset:16384
	ds_read_b128 v[178:181], v145 offset:17408
	ds_read_b128 v[182:185], v145 offset:18432
	ds_read_b128 v[186:189], v145 offset:19456
	ds_read_b128 v[190:193], v145 offset:20480
	ds_read_b128 v[194:197], v145 offset:21504
	ds_read_b128 v[198:201], v145 offset:22528
	ds_read_b128 v[202:205], v145 offset:23552
	global_load_lds_dwordx4 v[142:143], off
	s_add_i32 m0, s51, 0x2000
	s_add_u32 s52, s24, 0x40000
	v_lshl_add_u64 v[206:207], s[24:25], 0, v[132:133]
	s_addc_u32 s53, s25, 0
	s_add_i32 s51, s54, s36
	global_load_lds_dwordx4 v[206:207], off
	v_lshl_add_u64 v[208:209], s[52:53], 0, v[232:233]
	s_mov_b32 m0, s51
	v_lshl_add_u64 v[210:211], s[26:27], 0, v[130:131]
	global_load_lds_dwordx4 v[208:209], off
	v_lshl_add_u64 v[208:209], s[52:53], 0, v[132:133]
	s_add_i32 m0, s51, 0x2000
	s_nop 0
	global_load_lds_dwordx4 v[208:209], off
	v_lshl_add_u64 v[208:209], s[26:27], 0, v[128:129]
	s_waitcnt vmcnt(6) lgkmcnt(0)
	s_barrier
	v_mfma_f32_16x16x32_bf16 v[60:63], v[138:141], v[174:177], 0
	v_mfma_f32_16x16x32_bf16 v[56:59], v[150:153], v[174:177], 0
	v_mfma_f32_16x16x32_bf16 v[44:47], v[138:141], v[182:185], 0
	v_mfma_f32_16x16x32_bf16 v[40:43], v[150:153], v[182:185], 0
	v_mfma_f32_16x16x32_bf16 v[28:31], v[138:141], v[190:193], 0
	v_mfma_f32_16x16x32_bf16 v[24:27], v[150:153], v[190:193], 0
	v_mfma_f32_16x16x32_bf16 v[12:15], v[138:141], v[198:201], 0
	v_mfma_f32_16x16x32_bf16 v[8:11], v[150:153], v[198:201], 0
	v_mfma_f32_16x16x32_bf16 v[60:63], v[146:149], v[178:181], v[60:63]
	v_mfma_f32_16x16x32_bf16 v[56:59], v[154:157], v[178:181], v[56:59]
	v_mfma_f32_16x16x32_bf16 v[44:47], v[146:149], v[186:189], v[44:47]
	v_mfma_f32_16x16x32_bf16 v[40:43], v[154:157], v[186:189], v[40:43]
	v_mfma_f32_16x16x32_bf16 v[28:31], v[146:149], v[194:197], v[28:31]
	v_mfma_f32_16x16x32_bf16 v[24:27], v[154:157], v[194:197], v[24:27]
	v_mfma_f32_16x16x32_bf16 v[12:15], v[146:149], v[202:205], v[12:15]
	v_mfma_f32_16x16x32_bf16 v[8:11], v[154:157], v[202:205], v[8:11]
	v_mfma_f32_16x16x32_bf16 v[52:55], v[158:161], v[174:177], 0
	v_mfma_f32_16x16x32_bf16 v[48:51], v[166:169], v[174:177], 0
	v_mfma_f32_16x16x32_bf16 v[36:39], v[158:161], v[182:185], 0
	v_mfma_f32_16x16x32_bf16 v[32:35], v[166:169], v[182:185], 0
	v_mfma_f32_16x16x32_bf16 v[20:23], v[158:161], v[190:193], 0
	v_mfma_f32_16x16x32_bf16 v[16:19], v[166:169], v[190:193], 0
	v_mfma_f32_16x16x32_bf16 v[4:7], v[158:161], v[198:201], 0
	v_mfma_f32_16x16x32_bf16 v[0:3], v[166:169], v[198:201], 0
	v_mfma_f32_16x16x32_bf16 v[52:55], v[162:165], v[178:181], v[52:55]
	v_mfma_f32_16x16x32_bf16 v[48:51], v[170:173], v[178:181], v[48:51]
	v_mfma_f32_16x16x32_bf16 v[36:39], v[162:165], v[186:189], v[36:39]
	v_mfma_f32_16x16x32_bf16 v[32:35], v[170:173], v[186:189], v[32:35]
	v_mfma_f32_16x16x32_bf16 v[20:23], v[162:165], v[194:197], v[20:23]
	v_mfma_f32_16x16x32_bf16 v[16:19], v[170:173], v[194:197], v[16:19]
	v_mfma_f32_16x16x32_bf16 v[4:7], v[162:165], v[202:205], v[4:7]
	v_mfma_f32_16x16x32_bf16 v[0:3], v[170:173], v[202:205], v[0:3]
	s_barrier
	s_branch .Lzmid_2
.LBB0_912:
	s_add_u32 s24, s22, 0xfffc0080
	s_addc_u32 s25, s23, -1
	s_add_i32 s51, 0, 0x10000
	s_cmp_eq_u32 s50, 12
	s_cselect_b32 s27, s5, s25
	s_cselect_b32 s26, s15, s24
	v_add_u32_e32 v142, s51, v144
	s_cselect_b32 s25, s13, s49
	s_cselect_b32 s24, s21, s48
	s_add_i32 s54, 0, 0x14000
	ds_read_b128 v[138:141], v142
	ds_read_b128 v[146:149], v142 offset:1024
	ds_read_b128 v[150:153], v142 offset:2048
	ds_read_b128 v[154:157], v142 offset:3072
	v_add_u32_e32 v142, s54, v144
	ds_read_b128 v[158:161], v142
	ds_read_b128 v[162:165], v142 offset:1024
	ds_read_b128 v[166:169], v142 offset:2048
	ds_read_b128 v[170:173], v142 offset:3072
	v_lshl_add_u64 v[142:143], s[22:23], 0, v[136:137]
	s_add_i32 m0, s37, 0xc000
	ds_read_b128 v[174:177], v145
	ds_read_b128 v[178:181], v145 offset:1024
	ds_read_b128 v[182:185], v145 offset:2048
	ds_read_b128 v[186:189], v145 offset:3072
	ds_read_b128 v[190:193], v145 offset:4096
	ds_read_b128 v[194:197], v145 offset:5120
	ds_read_b128 v[198:201], v145 offset:6144
	ds_read_b128 v[202:205], v145 offset:7168
	global_load_lds_dwordx4 v[142:143], off
	v_lshl_add_u64 v[142:143], s[22:23], 0, v[134:135]
	s_add_i32 m0, s37, 0xe000
	s_nop 0
	global_load_lds_dwordx4 v[142:143], off
	s_waitcnt vmcnt(8) lgkmcnt(0)
	s_barrier
	v_mfma_f32_16x16x32_bf16 v[124:127], v[138:141], v[174:177], v[124:127]
	v_mfma_f32_16x16x32_bf16 v[120:123], v[150:153], v[174:177], v[120:123]
	v_mfma_f32_16x16x32_bf16 v[108:111], v[138:141], v[182:185], v[108:111]
	v_mfma_f32_16x16x32_bf16 v[104:107], v[150:153], v[182:185], v[104:107]
	v_mfma_f32_16x16x32_bf16 v[92:95], v[138:141], v[190:193], v[92:95]
	v_mfma_f32_16x16x32_bf16 v[88:91], v[150:153], v[190:193], v[88:91]
	v_mfma_f32_16x16x32_bf16 v[76:79], v[138:141], v[198:201], v[76:79]
	v_mfma_f32_16x16x32_bf16 v[72:75], v[150:153], v[198:201], v[72:75]
	v_mfma_f32_16x16x32_bf16 v[124:127], v[146:149], v[178:181], v[124:127]
	v_mfma_f32_16x16x32_bf16 v[120:123], v[154:157], v[178:181], v[120:123]
	v_mfma_f32_16x16x32_bf16 v[108:111], v[146:149], v[186:189], v[108:111]
	v_mfma_f32_16x16x32_bf16 v[104:107], v[154:157], v[186:189], v[104:107]
	v_mfma_f32_16x16x32_bf16 v[92:95], v[146:149], v[194:197], v[92:95]
	v_mfma_f32_16x16x32_bf16 v[88:91], v[154:157], v[194:197], v[88:91]
	v_mfma_f32_16x16x32_bf16 v[76:79], v[146:149], v[202:205], v[76:79]
	v_mfma_f32_16x16x32_bf16 v[72:75], v[154:157], v[202:205], v[72:75]
	v_mfma_f32_16x16x32_bf16 v[116:119], v[158:161], v[174:177], v[116:119]
	v_mfma_f32_16x16x32_bf16 v[112:115], v[166:169], v[174:177], v[112:115]
	v_mfma_f32_16x16x32_bf16 v[100:103], v[158:161], v[182:185], v[100:103]
	v_mfma_f32_16x16x32_bf16 v[96:99], v[166:169], v[182:185], v[96:99]
	v_mfma_f32_16x16x32_bf16 v[84:87], v[158:161], v[190:193], v[84:87]
	v_mfma_f32_16x16x32_bf16 v[80:83], v[166:169], v[190:193], v[80:83]
	v_mfma_f32_16x16x32_bf16 v[68:71], v[158:161], v[198:201], v[68:71]
	v_mfma_f32_16x16x32_bf16 v[64:67], v[166:169], v[198:201], v[64:67]
	v_mfma_f32_16x16x32_bf16 v[116:119], v[162:165], v[178:181], v[116:119]
	v_mfma_f32_16x16x32_bf16 v[112:115], v[170:173], v[178:181], v[112:115]
	v_mfma_f32_16x16x32_bf16 v[100:103], v[162:165], v[186:189], v[100:103]
	v_mfma_f32_16x16x32_bf16 v[96:99], v[170:173], v[186:189], v[96:99]
	v_mfma_f32_16x16x32_bf16 v[84:87], v[162:165], v[194:197], v[84:87]
	v_mfma_f32_16x16x32_bf16 v[80:83], v[170:173], v[194:197], v[80:83]
	v_mfma_f32_16x16x32_bf16 v[68:71], v[162:165], v[202:205], v[68:71]
	v_mfma_f32_16x16x32_bf16 v[64:67], v[170:173], v[202:205], v[64:67]
	s_barrier
	s_add_i32 s51, s51, s36
	v_lshl_add_u64 v[142:143], s[24:25], 0, v[232:233]
	s_mov_b32 m0, s51
	ds_read_b128 v[174:177], v145 offset:16384
	ds_read_b128 v[178:181], v145 offset:17408
	ds_read_b128 v[182:185], v145 offset:18432
	ds_read_b128 v[186:189], v145 offset:19456
	ds_read_b128 v[190:193], v145 offset:20480
	ds_read_b128 v[194:197], v145 offset:21504
	ds_read_b128 v[198:201], v145 offset:22528
	ds_read_b128 v[202:205], v145 offset:23552
	global_load_lds_dwordx4 v[142:143], off
	s_add_i32 m0, s51, 0x2000
	s_add_u32 s52, s24, 0x40000
	v_lshl_add_u64 v[206:207], s[24:25], 0, v[132:133]
	s_addc_u32 s53, s25, 0
	s_add_i32 s51, s54, s36
	global_load_lds_dwordx4 v[206:207], off
	v_lshl_add_u64 v[208:209], s[52:53], 0, v[232:233]
	s_mov_b32 m0, s51
	v_lshl_add_u64 v[210:211], s[26:27], 0, v[130:131]
	global_load_lds_dwordx4 v[208:209], off
	v_lshl_add_u64 v[208:209], s[52:53], 0, v[132:133]
	s_add_i32 m0, s51, 0x2000
	s_nop 0
	global_load_lds_dwordx4 v[208:209], off
	v_lshl_add_u64 v[208:209], s[26:27], 0, v[128:129]
	s_waitcnt vmcnt(6) lgkmcnt(0)
	s_barrier
	v_mfma_f32_16x16x32_bf16 v[60:63], v[138:141], v[174:177], v[60:63]
	v_mfma_f32_16x16x32_bf16 v[56:59], v[150:153], v[174:177], v[56:59]
	v_mfma_f32_16x16x32_bf16 v[44:47], v[138:141], v[182:185], v[44:47]
	v_mfma_f32_16x16x32_bf16 v[40:43], v[150:153], v[182:185], v[40:43]
	v_mfma_f32_16x16x32_bf16 v[28:31], v[138:141], v[190:193], v[28:31]
	v_mfma_f32_16x16x32_bf16 v[24:27], v[150:153], v[190:193], v[24:27]
	v_mfma_f32_16x16x32_bf16 v[12:15], v[138:141], v[198:201], v[12:15]
	v_mfma_f32_16x16x32_bf16 v[8:11], v[150:153], v[198:201], v[8:11]
	v_mfma_f32_16x16x32_bf16 v[60:63], v[146:149], v[178:181], v[60:63]
	v_mfma_f32_16x16x32_bf16 v[56:59], v[154:157], v[178:181], v[56:59]
	v_mfma_f32_16x16x32_bf16 v[44:47], v[146:149], v[186:189], v[44:47]
	v_mfma_f32_16x16x32_bf16 v[40:43], v[154:157], v[186:189], v[40:43]
	v_mfma_f32_16x16x32_bf16 v[28:31], v[146:149], v[194:197], v[28:31]
	v_mfma_f32_16x16x32_bf16 v[24:27], v[154:157], v[194:197], v[24:27]
	v_mfma_f32_16x16x32_bf16 v[12:15], v[146:149], v[202:205], v[12:15]
	v_mfma_f32_16x16x32_bf16 v[8:11], v[154:157], v[202:205], v[8:11]
	v_mfma_f32_16x16x32_bf16 v[52:55], v[158:161], v[174:177], v[52:55]
	v_mfma_f32_16x16x32_bf16 v[48:51], v[166:169], v[174:177], v[48:51]
	v_mfma_f32_16x16x32_bf16 v[36:39], v[158:161], v[182:185], v[36:39]
	v_mfma_f32_16x16x32_bf16 v[32:35], v[166:169], v[182:185], v[32:35]
	v_mfma_f32_16x16x32_bf16 v[20:23], v[158:161], v[190:193], v[20:23]
	v_mfma_f32_16x16x32_bf16 v[16:19], v[166:169], v[190:193], v[16:19]
	v_mfma_f32_16x16x32_bf16 v[4:7], v[158:161], v[198:201], v[4:7]
	v_mfma_f32_16x16x32_bf16 v[0:3], v[166:169], v[198:201], v[0:3]
	v_mfma_f32_16x16x32_bf16 v[52:55], v[162:165], v[178:181], v[52:55]
	v_mfma_f32_16x16x32_bf16 v[48:51], v[170:173], v[178:181], v[48:51]
	v_mfma_f32_16x16x32_bf16 v[36:39], v[162:165], v[186:189], v[36:39]
	v_mfma_f32_16x16x32_bf16 v[32:35], v[170:173], v[186:189], v[32:35]
	v_mfma_f32_16x16x32_bf16 v[20:23], v[162:165], v[194:197], v[20:23]
	v_mfma_f32_16x16x32_bf16 v[16:19], v[170:173], v[194:197], v[16:19]
	v_mfma_f32_16x16x32_bf16 v[4:7], v[162:165], v[202:205], v[4:7]
	v_mfma_f32_16x16x32_bf16 v[0:3], v[170:173], v[202:205], v[0:3]
	s_barrier
.Lzmid_2:
	s_add_i32 s51, 0, 0x18000
	s_add_i32 s52, 0, 0x1c000
	v_add_u32_e32 v154, s51, v144
	v_add_u32_e32 v170, s52, v144
	ds_read_b128 v[138:141], v154
	ds_read_b128 v[146:149], v154 offset:1024
	ds_read_b128 v[150:153], v154 offset:2048
	ds_read_b128 v[154:157], v154 offset:3072
	ds_read_b128 v[158:161], v170
	ds_read_b128 v[162:165], v170 offset:1024
	ds_read_b128 v[166:169], v170 offset:2048
	ds_read_b128 v[170:173], v170 offset:3072
	s_add_u32 s26, s26, 0x40000
	s_addc_u32 s27, s27, 0
	s_mov_b32 m0, s37
	s_nop 0
	global_load_lds_dwordx4 v[208:209], off
	s_mov_b32 m0, s38
	s_nop 0
	global_load_lds_dwordx4 v[210:211], off
	s_mov_b32 m0, s39
	v_lshl_add_u64 v[212:213], s[26:27], 0, v[128:129]
	ds_read_b128 v[174:177], v145 offset:32768
	ds_read_b128 v[178:181], v145 offset:33792
	ds_read_b128 v[182:185], v145 offset:34816
	ds_read_b128 v[186:189], v145 offset:35840
	ds_read_b128 v[190:193], v145 offset:36864
	ds_read_b128 v[194:197], v145 offset:37888
	ds_read_b128 v[198:201], v145 offset:38912
	ds_read_b128 v[202:205], v145 offset:39936
	global_load_lds_dwordx4 v[212:213], off
	v_lshl_add_u64 v[212:213], s[26:27], 0, v[130:131]
	s_mov_b32 m0, s40
	s_nop 0
	global_load_lds_dwordx4 v[212:213], off
	s_waitcnt vmcnt(8) lgkmcnt(0)
	s_barrier
	v_mfma_f32_16x16x32_bf16 v[124:127], v[138:141], v[174:177], v[124:127]
	v_mfma_f32_16x16x32_bf16 v[120:123], v[150:153], v[174:177], v[120:123]
	v_mfma_f32_16x16x32_bf16 v[108:111], v[138:141], v[182:185], v[108:111]
	v_mfma_f32_16x16x32_bf16 v[104:107], v[150:153], v[182:185], v[104:107]
	v_mfma_f32_16x16x32_bf16 v[92:95], v[138:141], v[190:193], v[92:95]
	v_mfma_f32_16x16x32_bf16 v[88:91], v[150:153], v[190:193], v[88:91]
	v_mfma_f32_16x16x32_bf16 v[76:79], v[138:141], v[198:201], v[76:79]
	v_mfma_f32_16x16x32_bf16 v[72:75], v[150:153], v[198:201], v[72:75]
	v_mfma_f32_16x16x32_bf16 v[124:127], v[146:149], v[178:181], v[124:127]
	v_mfma_f32_16x16x32_bf16 v[120:123], v[154:157], v[178:181], v[120:123]
	v_mfma_f32_16x16x32_bf16 v[108:111], v[146:149], v[186:189], v[108:111]
	v_mfma_f32_16x16x32_bf16 v[104:107], v[154:157], v[186:189], v[104:107]
	v_mfma_f32_16x16x32_bf16 v[92:95], v[146:149], v[194:197], v[92:95]
	v_mfma_f32_16x16x32_bf16 v[88:91], v[154:157], v[194:197], v[88:91]
	v_mfma_f32_16x16x32_bf16 v[76:79], v[146:149], v[202:205], v[76:79]
	v_mfma_f32_16x16x32_bf16 v[72:75], v[154:157], v[202:205], v[72:75]
	v_mfma_f32_16x16x32_bf16 v[116:119], v[158:161], v[174:177], v[116:119]
	v_mfma_f32_16x16x32_bf16 v[112:115], v[166:169], v[174:177], v[112:115]
	v_mfma_f32_16x16x32_bf16 v[100:103], v[158:161], v[182:185], v[100:103]
	v_mfma_f32_16x16x32_bf16 v[96:99], v[166:169], v[182:185], v[96:99]
	v_mfma_f32_16x16x32_bf16 v[84:87], v[158:161], v[190:193], v[84:87]
	v_mfma_f32_16x16x32_bf16 v[80:83], v[166:169], v[190:193], v[80:83]
	v_mfma_f32_16x16x32_bf16 v[68:71], v[158:161], v[198:201], v[68:71]
	v_mfma_f32_16x16x32_bf16 v[64:67], v[166:169], v[198:201], v[64:67]
	v_mfma_f32_16x16x32_bf16 v[116:119], v[162:165], v[178:181], v[116:119]
	v_mfma_f32_16x16x32_bf16 v[112:115], v[170:173], v[178:181], v[112:115]
	v_mfma_f32_16x16x32_bf16 v[100:103], v[162:165], v[186:189], v[100:103]
	v_mfma_f32_16x16x32_bf16 v[96:99], v[170:173], v[186:189], v[96:99]
	v_mfma_f32_16x16x32_bf16 v[84:87], v[162:165], v[194:197], v[84:87]
	v_mfma_f32_16x16x32_bf16 v[80:83], v[170:173], v[194:197], v[80:83]
	v_mfma_f32_16x16x32_bf16 v[68:71], v[162:165], v[202:205], v[68:71]
	v_mfma_f32_16x16x32_bf16 v[64:67], v[170:173], v[202:205], v[64:67]
	s_barrier
	s_add_i32 s26, s51, s36
	v_lshl_add_u64 v[142:143], v[142:143], 0, s[94:95]
	s_mov_b32 m0, s26
	ds_read_b128 v[174:177], v145 offset:49152
	ds_read_b128 v[178:181], v145 offset:50176
	ds_read_b128 v[182:185], v145 offset:51200
	ds_read_b128 v[186:189], v145 offset:52224
	ds_read_b128 v[190:193], v145 offset:53248
	ds_read_b128 v[194:197], v145 offset:54272
	ds_read_b128 v[198:201], v145 offset:55296
	ds_read_b128 v[202:205], v145 offset:56320
	global_load_lds_dwordx4 v[142:143], off
	s_add_i32 m0, s26, 0x2000
	s_add_u32 s24, s24, 0x40080
	v_lshl_add_u64 v[142:143], v[206:207], 0, s[94:95]
	s_addc_u32 s25, s25, 0
	s_add_i32 s26, s52, s36
	global_load_lds_dwordx4 v[142:143], off
	v_lshl_add_u64 v[142:143], s[24:25], 0, v[232:233]
	s_mov_b32 m0, s26
	s_nop 0
	global_load_lds_dwordx4 v[142:143], off
	v_lshl_add_u64 v[142:143], s[24:25], 0, v[132:133]
	s_add_i32 m0, s26, 0x2000
	s_nop 0
	global_load_lds_dwordx4 v[142:143], off
	v_lshl_add_u64 v[142:143], v[208:209], 0, s[94:95]
	s_mov_b32 m0, s43
	s_nop 0
	global_load_lds_dwordx4 v[142:143], off
	v_lshl_add_u64 v[142:143], v[210:211], 0, s[94:95]
	s_mov_b32 m0, s44
	s_nop 0
	global_load_lds_dwordx4 v[142:143], off
	s_waitcnt vmcnt(8) lgkmcnt(0)
	s_barrier
	v_mfma_f32_16x16x32_bf16 v[60:63], v[138:141], v[174:177], v[60:63]
	v_mfma_f32_16x16x32_bf16 v[56:59], v[150:153], v[174:177], v[56:59]
	v_mfma_f32_16x16x32_bf16 v[44:47], v[138:141], v[182:185], v[44:47]
	v_mfma_f32_16x16x32_bf16 v[40:43], v[150:153], v[182:185], v[40:43]
	v_mfma_f32_16x16x32_bf16 v[28:31], v[138:141], v[190:193], v[28:31]
	v_mfma_f32_16x16x32_bf16 v[24:27], v[150:153], v[190:193], v[24:27]
	v_mfma_f32_16x16x32_bf16 v[12:15], v[138:141], v[198:201], v[12:15]
	v_mfma_f32_16x16x32_bf16 v[8:11], v[150:153], v[198:201], v[8:11]
	v_mfma_f32_16x16x32_bf16 v[60:63], v[146:149], v[178:181], v[60:63]
	v_mfma_f32_16x16x32_bf16 v[56:59], v[154:157], v[178:181], v[56:59]
	v_mfma_f32_16x16x32_bf16 v[44:47], v[146:149], v[186:189], v[44:47]
	v_mfma_f32_16x16x32_bf16 v[40:43], v[154:157], v[186:189], v[40:43]
	v_mfma_f32_16x16x32_bf16 v[28:31], v[146:149], v[194:197], v[28:31]
	v_mfma_f32_16x16x32_bf16 v[24:27], v[154:157], v[194:197], v[24:27]
	v_mfma_f32_16x16x32_bf16 v[12:15], v[146:149], v[202:205], v[12:15]
	v_mfma_f32_16x16x32_bf16 v[8:11], v[154:157], v[202:205], v[8:11]
	v_mfma_f32_16x16x32_bf16 v[52:55], v[158:161], v[174:177], v[52:55]
	v_mfma_f32_16x16x32_bf16 v[48:51], v[166:169], v[174:177], v[48:51]
	v_mfma_f32_16x16x32_bf16 v[36:39], v[158:161], v[182:185], v[36:39]
	v_mfma_f32_16x16x32_bf16 v[32:35], v[166:169], v[182:185], v[32:35]
	v_mfma_f32_16x16x32_bf16 v[20:23], v[158:161], v[190:193], v[20:23]
	v_mfma_f32_16x16x32_bf16 v[16:19], v[166:169], v[190:193], v[16:19]
	v_mfma_f32_16x16x32_bf16 v[4:7], v[158:161], v[198:201], v[4:7]
	v_mfma_f32_16x16x32_bf16 v[0:3], v[166:169], v[198:201], v[0:3]
	v_mfma_f32_16x16x32_bf16 v[52:55], v[162:165], v[178:181], v[52:55]
	v_mfma_f32_16x16x32_bf16 v[48:51], v[170:173], v[178:181], v[48:51]
	v_mfma_f32_16x16x32_bf16 v[36:39], v[162:165], v[186:189], v[36:39]
	v_mfma_f32_16x16x32_bf16 v[32:35], v[170:173], v[186:189], v[32:35]
	v_mfma_f32_16x16x32_bf16 v[20:23], v[162:165], v[194:197], v[20:23]
	v_mfma_f32_16x16x32_bf16 v[16:19], v[170:173], v[194:197], v[16:19]
	v_mfma_f32_16x16x32_bf16 v[4:7], v[162:165], v[202:205], v[4:7]
	v_mfma_f32_16x16x32_bf16 v[0:3], v[170:173], v[202:205], v[0:3]
	s_barrier
	s_add_i32 s50, s50, 2
	s_add_u32 s48, s48, 0x100
	s_addc_u32 s49, s49, 0
	s_add_u32 s22, s22, 0x100
	s_addc_u32 s23, s23, 0
	s_cmp_gt_u32 s50, 13
	s_cbranch_scc0 .LBB0_912
	s_and_b64 vcc, exec, s[10:11]
	s_cbranch_vccz .LBB0_915
	s_barrier

.LBB0_1018:
	s_ashr_i32 s15, s14, 31
	s_ashr_i32 s13, s12, 31
	s_lshl_b64 s[16:17], s[14:15], 19
	s_lshl_b64 s[18:19], s[12:13], 9
	s_add_u32 s13, s34, s16
	s_addc_u32 s15, s35, s17
	s_add_u32 s16, s13, s18
	s_addc_u32 s17, s15, s19
	s_and_b64 s[18:19], s[2:3], exec
	s_cselect_b32 s29, s17, s23
	s_cselect_b32 s28, s16, s22
	s_lshl_b32 s13, s12, 2
	s_add_i32 s18, s13, s51
	s_ashr_i32 s19, s18, 31
	s_lshl_b64 s[18:19], s[18:19], 17
	s_add_u32 s18, s36, s18
	s_addc_u32 s19, s37, s19
	s_and_b64 s[26:27], s[2:3], exec
	s_cselect_b32 s27, s19, s25
	s_cselect_b32 s26, s18, s24
	s_add_i32 s15, 0, 0x10000
	s_add_i32 s21, 0, 0x14000
	v_add_u32_e32 v253, 0x10000, v174
	v_add_u32_e32 v252, 0x14000, v174
	ds_read_b128 v[128:131], v253
	ds_read_b128 v[132:135], v253 offset:1024
	ds_read_b128 v[136:139], v253 offset:2048
	ds_read_b128 v[140:143], v253 offset:3072
	ds_read_b128 v[144:147], v252
	ds_read_b128 v[148:151], v252 offset:1024
	ds_read_b128 v[152:155], v252 offset:2048
	ds_read_b128 v[156:159], v252 offset:3072
	s_add_u32 s52, s22, 0x40080
	s_addc_u32 s53, s23, 0
	s_add_i32 s55, s39, 0xc000
	s_waitcnt vmcnt(0)
	s_mov_b32 m0, s55
	s_add_i32 s13, s39, 0xe000
	ds_read_b128 v[168:171], v175
	ds_read_b128 v[176:179], v175 offset:1024
	ds_read_b128 v[180:183], v175 offset:2048
	ds_read_b128 v[184:187], v175 offset:3072
	ds_read_b128 v[188:191], v175 offset:4096
	ds_read_b128 v[192:195], v175 offset:5120
	ds_read_b128 v[196:199], v175 offset:6144
	ds_read_b128 v[200:203], v175 offset:7168
	global_load_lds_dwordx4 v160, s[52:53]
	s_mov_b32 m0, s13
	s_nop 0
	global_load_lds_dwordx4 v162, s[52:53]
	s_waitcnt vmcnt(8) lgkmcnt(0)
	s_barrier
	v_mfma_f32_16x16x32_bf16 v[0:3], v[128:131], v[168:171], 0
	v_mfma_f32_16x16x32_bf16 v[4:7], v[136:139], v[168:171], 0
	v_mfma_f32_16x16x32_bf16 v[16:19], v[128:131], v[180:183], 0
	v_mfma_f32_16x16x32_bf16 v[20:23], v[136:139], v[180:183], 0
	v_mfma_f32_16x16x32_bf16 v[32:35], v[128:131], v[188:191], 0
	v_mfma_f32_16x16x32_bf16 v[36:39], v[136:139], v[188:191], 0
	v_mfma_f32_16x16x32_bf16 v[48:51], v[128:131], v[196:199], 0
	v_mfma_f32_16x16x32_bf16 v[52:55], v[136:139], v[196:199], 0
	v_mfma_f32_16x16x32_bf16 v[0:3], v[132:135], v[176:179], v[0:3]
	v_mfma_f32_16x16x32_bf16 v[4:7], v[140:143], v[176:179], v[4:7]
	v_mfma_f32_16x16x32_bf16 v[16:19], v[132:135], v[184:187], v[16:19]
	v_mfma_f32_16x16x32_bf16 v[20:23], v[140:143], v[184:187], v[20:23]
	v_mfma_f32_16x16x32_bf16 v[32:35], v[132:135], v[192:195], v[32:35]
	v_mfma_f32_16x16x32_bf16 v[36:39], v[140:143], v[192:195], v[36:39]
	v_mfma_f32_16x16x32_bf16 v[48:51], v[132:135], v[200:203], v[48:51]
	v_mfma_f32_16x16x32_bf16 v[52:55], v[140:143], v[200:203], v[52:55]
	v_mfma_f32_16x16x32_bf16 v[8:11], v[144:147], v[168:171], 0
	v_mfma_f32_16x16x32_bf16 v[12:15], v[152:155], v[168:171], 0
	v_mfma_f32_16x16x32_bf16 v[8:11], v[148:151], v[176:179], v[8:11]
	v_mfma_f32_16x16x32_bf16 v[12:15], v[156:159], v[176:179], v[12:15]
	v_mfma_f32_16x16x32_bf16 v[24:27], v[144:147], v[180:183], 0
	v_mfma_f32_16x16x32_bf16 v[28:31], v[152:155], v[180:183], 0
	v_mfma_f32_16x16x32_bf16 v[24:27], v[148:151], v[184:187], v[24:27]
	v_mfma_f32_16x16x32_bf16 v[28:31], v[156:159], v[184:187], v[28:31]
	v_mfma_f32_16x16x32_bf16 v[40:43], v[144:147], v[188:191], 0
	v_mfma_f32_16x16x32_bf16 v[44:47], v[152:155], v[188:191], 0
	v_mfma_f32_16x16x32_bf16 v[40:43], v[148:151], v[192:195], v[40:43]
	v_mfma_f32_16x16x32_bf16 v[44:47], v[156:159], v[192:195], v[44:47]
	v_mfma_f32_16x16x32_bf16 v[56:59], v[144:147], v[196:199], 0
	v_mfma_f32_16x16x32_bf16 v[60:63], v[152:155], v[196:199], 0
	v_mfma_f32_16x16x32_bf16 v[56:59], v[148:151], v[200:203], v[56:59]
	v_mfma_f32_16x16x32_bf16 v[60:63], v[156:159], v[200:203], v[60:63]
	s_barrier
	s_add_i32 s53, s15, s38
	s_mov_b64 s[58:59], 0x100
	s_add_i32 s15, s53, 0x2000
	s_add_u32 s68, s24, s58
	s_addc_u32 s69, s25, s59
	s_mov_b32 m0, s53
	s_add_u32 s70, s24, s58
	s_addc_u32 s71, s25, s59
	s_add_u32 s56, s24, 0x10100
	ds_read_b128 v[168:171], v175 offset:16384
	ds_read_b128 v[176:179], v175 offset:17408
	ds_read_b128 v[180:183], v175 offset:18432
	ds_read_b128 v[184:187], v175 offset:19456
	ds_read_b128 v[188:191], v175 offset:20480
	ds_read_b128 v[192:195], v175 offset:21504
	ds_read_b128 v[196:199], v175 offset:22528
	ds_read_b128 v[200:203], v175 offset:23552
	global_load_lds_dwordx4 v232, s[68:69]
	s_mov_b32 m0, s15
	s_addc_u32 s57, s25, 0
	s_add_i32 s21, s21, s38
	global_load_lds_dwordx4 v164, s[70:71]
	s_mov_b32 m0, s21
	s_add_i32 s52, s21, 0x2000
	global_load_lds_dwordx4 v232, s[56:57]
	s_mov_b32 m0, s52
	global_load_lds_dwordx4 v164, s[56:57]
	s_add_u32 s68, s22, s58
	s_addc_u32 s69, s23, s59
	s_mov_b32 m0, s39
	global_load_lds_dwordx4 v160, s[68:69]
	s_add_u32 s68, s22, s58
	s_addc_u32 s69, s23, s59
	s_mov_b32 m0, s40
	s_nop 0
	global_load_lds_dwordx4 v162, s[68:69]
	s_waitcnt vmcnt(8) lgkmcnt(0)
	s_barrier
	v_mfma_f32_16x16x32_bf16 v[64:67], v[128:131], v[168:171], 0
	v_mfma_f32_16x16x32_bf16 v[80:83], v[128:131], v[180:183], 0
	v_mfma_f32_16x16x32_bf16 v[96:99], v[128:131], v[188:191], 0
	v_mfma_f32_16x16x32_bf16 v[112:115], v[128:131], v[196:199], 0
	v_mfma_f32_16x16x32_bf16 v[64:67], v[132:135], v[176:179], v[64:67]
	v_mfma_f32_16x16x32_bf16 v[68:71], v[136:139], v[168:171], 0
	v_mfma_f32_16x16x32_bf16 v[80:83], v[132:135], v[184:187], v[80:83]
	v_mfma_f32_16x16x32_bf16 v[84:87], v[136:139], v[180:183], 0
	v_mfma_f32_16x16x32_bf16 v[96:99], v[132:135], v[192:195], v[96:99]
	v_mfma_f32_16x16x32_bf16 v[112:115], v[132:135], v[200:203], v[112:115]
	v_mfma_f32_16x16x32_bf16 v[116:119], v[136:139], v[196:199], 0
	v_mfma_f32_16x16x32_bf16 v[68:71], v[140:143], v[176:179], v[68:71]
	v_mfma_f32_16x16x32_bf16 v[84:87], v[140:143], v[184:187], v[84:87]
	v_mfma_f32_16x16x32_bf16 v[100:103], v[136:139], v[188:191], 0
	v_mfma_f32_16x16x32_bf16 v[116:119], v[140:143], v[200:203], v[116:119]
	v_mfma_f32_16x16x32_bf16 v[100:103], v[140:143], v[192:195], v[100:103]
	v_mfma_f32_16x16x32_bf16 v[72:75], v[144:147], v[168:171], 0
	v_mfma_f32_16x16x32_bf16 v[76:79], v[152:155], v[168:171], 0
	v_mfma_f32_16x16x32_bf16 v[72:75], v[148:151], v[176:179], v[72:75]
	v_mfma_f32_16x16x32_bf16 v[76:79], v[156:159], v[176:179], v[76:79]
	v_mfma_f32_16x16x32_bf16 v[88:91], v[144:147], v[180:183], 0
	v_mfma_f32_16x16x32_bf16 v[92:95], v[152:155], v[180:183], 0
	v_mfma_f32_16x16x32_bf16 v[104:107], v[144:147], v[188:191], 0
	v_mfma_f32_16x16x32_bf16 v[120:123], v[144:147], v[196:199], 0
	v_mfma_f32_16x16x32_bf16 v[88:91], v[148:151], v[184:187], v[88:91]
	v_mfma_f32_16x16x32_bf16 v[92:95], v[156:159], v[184:187], v[92:95]
	v_mfma_f32_16x16x32_bf16 v[104:107], v[148:151], v[192:195], v[104:107]
	v_mfma_f32_16x16x32_bf16 v[108:111], v[152:155], v[188:191], 0
	v_mfma_f32_16x16x32_bf16 v[120:123], v[148:151], v[200:203], v[120:123]
	v_mfma_f32_16x16x32_bf16 v[124:127], v[152:155], v[196:199], 0
	v_mfma_f32_16x16x32_bf16 v[108:111], v[156:159], v[192:195], v[108:111]
	v_mfma_f32_16x16x32_bf16 v[124:127], v[156:159], v[200:203], v[124:127]
	s_barrier
	s_add_i32 s54, 0, 0x18000
	s_add_i32 s60, 0, 0x1c000
	v_add_u32_e32 v253, 0x18000, v174
	v_add_u32_e32 v252, 0x1c000, v174
	ds_read_b128 v[128:131], v253
	ds_read_b128 v[132:135], v253 offset:1024
	ds_read_b128 v[136:139], v253 offset:2048
	ds_read_b128 v[140:143], v253 offset:3072
	ds_read_b128 v[144:147], v252
	ds_read_b128 v[148:151], v252 offset:1024
	ds_read_b128 v[152:155], v252 offset:2048
	ds_read_b128 v[156:159], v252 offset:3072
	s_add_u32 s56, s22, 0x40100
	s_addc_u32 s57, s23, 0
	s_mov_b32 m0, s41
	ds_read_b128 v[168:171], v175 offset:32768
	ds_read_b128 v[176:179], v175 offset:33792
	ds_read_b128 v[180:183], v175 offset:34816
	ds_read_b128 v[184:187], v175 offset:35840
	ds_read_b128 v[188:191], v175 offset:36864
	ds_read_b128 v[192:195], v175 offset:37888
	ds_read_b128 v[196:199], v175 offset:38912
	ds_read_b128 v[200:203], v175 offset:39936
	global_load_lds_dwordx4 v160, s[56:57]
	s_mov_b32 m0, s42
	s_nop 0
	global_load_lds_dwordx4 v162, s[56:57]
	s_waitcnt vmcnt(8) lgkmcnt(0)
	s_barrier
	v_mfma_f32_16x16x32_bf16 v[0:3], v[128:131], v[168:171], v[0:3]
	v_mfma_f32_16x16x32_bf16 v[4:7], v[136:139], v[168:171], v[4:7]
	v_mfma_f32_16x16x32_bf16 v[16:19], v[128:131], v[180:183], v[16:19]
	v_mfma_f32_16x16x32_bf16 v[20:23], v[136:139], v[180:183], v[20:23]
	v_mfma_f32_16x16x32_bf16 v[32:35], v[128:131], v[188:191], v[32:35]
	v_mfma_f32_16x16x32_bf16 v[36:39], v[136:139], v[188:191], v[36:39]
	v_mfma_f32_16x16x32_bf16 v[48:51], v[128:131], v[196:199], v[48:51]
	v_mfma_f32_16x16x32_bf16 v[52:55], v[136:139], v[196:199], v[52:55]
	v_mfma_f32_16x16x32_bf16 v[0:3], v[132:135], v[176:179], v[0:3]
	v_mfma_f32_16x16x32_bf16 v[4:7], v[140:143], v[176:179], v[4:7]
	v_mfma_f32_16x16x32_bf16 v[16:19], v[132:135], v[184:187], v[16:19]
	v_mfma_f32_16x16x32_bf16 v[20:23], v[140:143], v[184:187], v[20:23]
	v_mfma_f32_16x16x32_bf16 v[32:35], v[132:135], v[192:195], v[32:35]
	v_mfma_f32_16x16x32_bf16 v[36:39], v[140:143], v[192:195], v[36:39]
	v_mfma_f32_16x16x32_bf16 v[48:51], v[132:135], v[200:203], v[48:51]
	v_mfma_f32_16x16x32_bf16 v[52:55], v[140:143], v[200:203], v[52:55]
	v_mfma_f32_16x16x32_bf16 v[8:11], v[144:147], v[168:171], v[8:11]
	v_mfma_f32_16x16x32_bf16 v[24:27], v[144:147], v[180:183], v[24:27]
	v_mfma_f32_16x16x32_bf16 v[28:31], v[152:155], v[180:183], v[28:31]
	v_mfma_f32_16x16x32_bf16 v[44:47], v[152:155], v[188:191], v[44:47]
	v_mfma_f32_16x16x32_bf16 v[56:59], v[144:147], v[196:199], v[56:59]
	v_mfma_f32_16x16x32_bf16 v[60:63], v[152:155], v[196:199], v[60:63]
	v_mfma_f32_16x16x32_bf16 v[8:11], v[148:151], v[176:179], v[8:11]
	v_mfma_f32_16x16x32_bf16 v[12:15], v[152:155], v[168:171], v[12:15]
	v_mfma_f32_16x16x32_bf16 v[24:27], v[148:151], v[184:187], v[24:27]
	v_mfma_f32_16x16x32_bf16 v[28:31], v[156:159], v[184:187], v[28:31]
	v_mfma_f32_16x16x32_bf16 v[40:43], v[144:147], v[188:191], v[40:43]
	v_mfma_f32_16x16x32_bf16 v[44:47], v[156:159], v[192:195], v[44:47]
	v_mfma_f32_16x16x32_bf16 v[56:59], v[148:151], v[200:203], v[56:59]
	v_mfma_f32_16x16x32_bf16 v[60:63], v[156:159], v[200:203], v[60:63]
	v_mfma_f32_16x16x32_bf16 v[12:15], v[156:159], v[176:179], v[12:15]
	v_mfma_f32_16x16x32_bf16 v[40:43], v[148:151], v[192:195], v[40:43]
	s_barrier
	s_add_i32 s56, s54, s38
	s_mov_b64 s[62:63], 0x180
	s_add_i32 s54, s56, 0x2000
	s_add_u32 s68, s24, s62
	s_addc_u32 s69, s25, s63
	s_mov_b32 m0, s56
	s_add_u32 s70, s24, s62
	s_addc_u32 s71, s25, s63
	s_add_u32 s58, s24, 0x10180
	ds_read_b128 v[168:171], v175 offset:49152
	ds_read_b128 v[176:179], v175 offset:50176
	ds_read_b128 v[180:183], v175 offset:51200
	ds_read_b128 v[184:187], v175 offset:52224
	ds_read_b128 v[188:191], v175 offset:53248
	ds_read_b128 v[192:195], v175 offset:54272
	ds_read_b128 v[196:199], v175 offset:55296
	ds_read_b128 v[200:203], v175 offset:56320
	global_load_lds_dwordx4 v232, s[68:69]
	s_mov_b32 m0, s54
	s_addc_u32 s59, s25, 0
	s_add_i32 s24, s60, s38
	global_load_lds_dwordx4 v164, s[70:71]
	s_mov_b32 m0, s24
	s_add_i32 s25, s24, 0x2000
	global_load_lds_dwordx4 v232, s[58:59]
	s_mov_b32 m0, s25
	s_nop 0
	global_load_lds_dwordx4 v164, s[58:59]
	s_add_u32 s68, s22, s62
	s_addc_u32 s69, s23, s63
	s_mov_b32 m0, s47
	s_nop 0
	global_load_lds_dwordx4 v160, s[68:69]
	s_add_u32 s68, s22, s62
	s_addc_u32 s69, s23, s63
	s_mov_b32 m0, s48
	s_nop 0
	global_load_lds_dwordx4 v162, s[68:69]
	s_waitcnt vmcnt(8) lgkmcnt(0)
	s_barrier
	v_mfma_f32_16x16x32_bf16 v[64:67], v[128:131], v[168:171], v[64:67]
	v_mfma_f32_16x16x32_bf16 v[68:71], v[136:139], v[168:171], v[68:71]
	v_mfma_f32_16x16x32_bf16 v[84:87], v[136:139], v[180:183], v[84:87]
	v_mfma_f32_16x16x32_bf16 v[96:99], v[128:131], v[188:191], v[96:99]
	v_mfma_f32_16x16x32_bf16 v[112:115], v[128:131], v[196:199], v[112:115]
	v_mfma_f32_16x16x32_bf16 v[116:119], v[136:139], v[196:199], v[116:119]
	v_mfma_f32_16x16x32_bf16 v[64:67], v[132:135], v[176:179], v[64:67]
	v_mfma_f32_16x16x32_bf16 v[68:71], v[140:143], v[176:179], v[68:71]
	v_mfma_f32_16x16x32_bf16 v[80:83], v[128:131], v[180:183], v[80:83]
	v_mfma_f32_16x16x32_bf16 v[84:87], v[140:143], v[184:187], v[84:87]
	v_mfma_f32_16x16x32_bf16 v[96:99], v[132:135], v[192:195], v[96:99]
	v_mfma_f32_16x16x32_bf16 v[100:103], v[136:139], v[188:191], v[100:103]
	v_mfma_f32_16x16x32_bf16 v[112:115], v[132:135], v[200:203], v[112:115]
	v_mfma_f32_16x16x32_bf16 v[116:119], v[140:143], v[200:203], v[116:119]
	v_mfma_f32_16x16x32_bf16 v[80:83], v[132:135], v[184:187], v[80:83]
	v_mfma_f32_16x16x32_bf16 v[100:103], v[140:143], v[192:195], v[100:103]
	v_mfma_f32_16x16x32_bf16 v[72:75], v[144:147], v[168:171], v[72:75]
	v_mfma_f32_16x16x32_bf16 v[76:79], v[152:155], v[168:171], v[76:79]
	v_mfma_f32_16x16x32_bf16 v[88:91], v[144:147], v[180:183], v[88:91]
	v_mfma_f32_16x16x32_bf16 v[92:95], v[152:155], v[180:183], v[92:95]
	v_mfma_f32_16x16x32_bf16 v[104:107], v[144:147], v[188:191], v[104:107]
	v_mfma_f32_16x16x32_bf16 v[108:111], v[152:155], v[188:191], v[108:111]
	v_mfma_f32_16x16x32_bf16 v[124:127], v[152:155], v[196:199], v[124:127]
	v_mfma_f32_16x16x32_bf16 v[72:75], v[148:151], v[176:179], v[72:75]
	v_mfma_f32_16x16x32_bf16 v[76:79], v[156:159], v[176:179], v[76:79]
	v_mfma_f32_16x16x32_bf16 v[92:95], v[156:159], v[184:187], v[92:95]
	v_mfma_f32_16x16x32_bf16 v[104:107], v[148:151], v[192:195], v[104:107]
	v_mfma_f32_16x16x32_bf16 v[108:111], v[156:159], v[192:195], v[108:111]
	v_mfma_f32_16x16x32_bf16 v[120:123], v[144:147], v[196:199], v[120:123]
	v_mfma_f32_16x16x32_bf16 v[124:127], v[156:159], v[200:203], v[124:127]
	v_mfma_f32_16x16x32_bf16 v[88:91], v[148:151], v[184:187], v[88:91]
	v_mfma_f32_16x16x32_bf16 v[120:123], v[148:151], v[200:203], v[120:123]
	s_barrier
	v_add_u32_e32 v253, 0x10000, v174
	ds_read_b128 v[128:131], v253
	ds_read_b128 v[132:135], v253 offset:1024
	ds_read_b128 v[136:139], v253 offset:2048
	ds_read_b128 v[140:143], v253 offset:3072
	v_add_u32_e32 v253, 0x14000, v174
	ds_read_b128 v[144:147], v253
	ds_read_b128 v[148:151], v253 offset:1024
	ds_read_b128 v[152:155], v253 offset:2048
	ds_read_b128 v[156:159], v253 offset:3072
	s_add_u32 s22, s22, 0x40180
	s_addc_u32 s23, s23, 0
	s_mov_b32 m0, s55
	ds_read_b128 v[168:171], v175
	ds_read_b128 v[176:179], v175 offset:1024
	ds_read_b128 v[180:183], v175 offset:2048
	ds_read_b128 v[184:187], v175 offset:3072
	ds_read_b128 v[188:191], v175 offset:4096
	ds_read_b128 v[192:195], v175 offset:5120
	ds_read_b128 v[196:199], v175 offset:6144
	ds_read_b128 v[200:203], v175 offset:7168
	global_load_lds_dwordx4 v160, s[22:23]
	s_mov_b32 m0, s13
	s_nop 0
	global_load_lds_dwordx4 v162, s[22:23]
	s_waitcnt vmcnt(8) lgkmcnt(0)
	s_barrier
	v_mfma_f32_16x16x32_bf16 v[0:3], v[128:131], v[168:171], v[0:3]
	v_mfma_f32_16x16x32_bf16 v[4:7], v[136:139], v[168:171], v[4:7]
	v_mfma_f32_16x16x32_bf16 v[16:19], v[128:131], v[180:183], v[16:19]
	v_mfma_f32_16x16x32_bf16 v[20:23], v[136:139], v[180:183], v[20:23]
	v_mfma_f32_16x16x32_bf16 v[32:35], v[128:131], v[188:191], v[32:35]
	v_mfma_f32_16x16x32_bf16 v[36:39], v[136:139], v[188:191], v[36:39]
	v_mfma_f32_16x16x32_bf16 v[48:51], v[128:131], v[196:199], v[48:51]
	v_mfma_f32_16x16x32_bf16 v[0:3], v[132:135], v[176:179], v[0:3]
	v_mfma_f32_16x16x32_bf16 v[4:7], v[140:143], v[176:179], v[4:7]
	v_mfma_f32_16x16x32_bf16 v[16:19], v[132:135], v[184:187], v[16:19]
	v_mfma_f32_16x16x32_bf16 v[20:23], v[140:143], v[184:187], v[20:23]
	v_mfma_f32_16x16x32_bf16 v[32:35], v[132:135], v[192:195], v[32:35]
	v_mfma_f32_16x16x32_bf16 v[36:39], v[140:143], v[192:195], v[36:39]
	v_mfma_f32_16x16x32_bf16 v[48:51], v[132:135], v[200:203], v[48:51]
	v_mfma_f32_16x16x32_bf16 v[52:55], v[136:139], v[196:199], v[52:55]
	v_mfma_f32_16x16x32_bf16 v[52:55], v[140:143], v[200:203], v[52:55]
	v_mfma_f32_16x16x32_bf16 v[8:11], v[144:147], v[168:171], v[8:11]
	v_mfma_f32_16x16x32_bf16 v[24:27], v[144:147], v[180:183], v[24:27]
	v_mfma_f32_16x16x32_bf16 v[28:31], v[152:155], v[180:183], v[28:31]
	v_mfma_f32_16x16x32_bf16 v[44:47], v[152:155], v[188:191], v[44:47]
	v_mfma_f32_16x16x32_bf16 v[56:59], v[144:147], v[196:199], v[56:59]
	v_mfma_f32_16x16x32_bf16 v[60:63], v[152:155], v[196:199], v[60:63]
	v_mfma_f32_16x16x32_bf16 v[8:11], v[148:151], v[176:179], v[8:11]
	v_mfma_f32_16x16x32_bf16 v[12:15], v[152:155], v[168:171], v[12:15]
	v_mfma_f32_16x16x32_bf16 v[24:27], v[148:151], v[184:187], v[24:27]
	v_mfma_f32_16x16x32_bf16 v[28:31], v[156:159], v[184:187], v[28:31]
	v_mfma_f32_16x16x32_bf16 v[40:43], v[144:147], v[188:191], v[40:43]
	v_mfma_f32_16x16x32_bf16 v[44:47], v[156:159], v[192:195], v[44:47]
	v_mfma_f32_16x16x32_bf16 v[56:59], v[148:151], v[200:203], v[56:59]
	v_mfma_f32_16x16x32_bf16 v[60:63], v[156:159], v[200:203], v[60:63]
	v_mfma_f32_16x16x32_bf16 v[12:15], v[156:159], v[176:179], v[12:15]
	v_mfma_f32_16x16x32_bf16 v[40:43], v[148:151], v[192:195], v[40:43]
	s_barrier
	s_mov_b32 m0, s53
	s_add_u32 s22, s26, 0x10000
	ds_read_b128 v[168:171], v175 offset:16384
	ds_read_b128 v[176:179], v175 offset:17408
	ds_read_b128 v[180:183], v175 offset:18432
	ds_read_b128 v[184:187], v175 offset:19456
	ds_read_b128 v[188:191], v175 offset:20480
	ds_read_b128 v[192:195], v175 offset:21504
	ds_read_b128 v[196:199], v175 offset:22528
	ds_read_b128 v[200:203], v175 offset:23552
	global_load_lds_dwordx4 v232, s[26:27]
	s_mov_b32 m0, s15
	s_addc_u32 s23, s27, 0
	global_load_lds_dwordx4 v164, s[26:27]
	s_mov_b32 m0, s21
	s_nop 0
	global_load_lds_dwordx4 v232, s[22:23]
	s_mov_b32 m0, s52
	s_nop 0
	global_load_lds_dwordx4 v164, s[22:23]
	s_mov_b32 m0, s39
	s_nop 0
	global_load_lds_dwordx4 v160, s[28:29]
	s_mov_b32 m0, s40
	s_nop 0
	global_load_lds_dwordx4 v162, s[28:29]
	s_waitcnt vmcnt(8) lgkmcnt(0)
	s_barrier
	v_mfma_f32_16x16x32_bf16 v[64:67], v[128:131], v[168:171], v[64:67]
	v_mfma_f32_16x16x32_bf16 v[64:67], v[132:135], v[176:179], v[64:67]
	v_mfma_f32_16x16x32_bf16 v[68:71], v[136:139], v[168:171], v[68:71]
	v_mfma_f32_16x16x32_bf16 v[68:71], v[140:143], v[176:179], v[68:71]
	v_mfma_f32_16x16x32_bf16 v[80:83], v[128:131], v[180:183], v[80:83]
	v_mfma_f32_16x16x32_bf16 v[80:83], v[132:135], v[184:187], v[80:83]
	v_mfma_f32_16x16x32_bf16 v[84:87], v[136:139], v[180:183], v[84:87]
	v_mfma_f32_16x16x32_bf16 v[84:87], v[140:143], v[184:187], v[84:87]
	v_mfma_f32_16x16x32_bf16 v[96:99], v[128:131], v[188:191], v[96:99]
	v_mfma_f32_16x16x32_bf16 v[112:115], v[128:131], v[196:199], v[112:115]
	v_mfma_f32_16x16x32_bf16 v[116:119], v[136:139], v[196:199], v[116:119]
	v_mfma_f32_16x16x32_bf16 v[96:99], v[132:135], v[192:195], v[96:99]
	v_mfma_f32_16x16x32_bf16 v[100:103], v[136:139], v[188:191], v[100:103]
	v_mfma_f32_16x16x32_bf16 v[112:115], v[132:135], v[200:203], v[112:115]
	v_mfma_f32_16x16x32_bf16 v[116:119], v[140:143], v[200:203], v[116:119]
	v_mfma_f32_16x16x32_bf16 v[100:103], v[140:143], v[192:195], v[100:103]
	v_mfma_f32_16x16x32_bf16 v[72:75], v[144:147], v[168:171], v[72:75]
	v_mfma_f32_16x16x32_bf16 v[72:75], v[148:151], v[176:179], v[72:75]
	v_mfma_f32_16x16x32_bf16 v[76:79], v[152:155], v[168:171], v[76:79]
	v_mfma_f32_16x16x32_bf16 v[76:79], v[156:159], v[176:179], v[76:79]
	v_mfma_f32_16x16x32_bf16 v[88:91], v[144:147], v[180:183], v[88:91]
	v_mfma_f32_16x16x32_bf16 v[88:91], v[148:151], v[184:187], v[88:91]
	v_mfma_f32_16x16x32_bf16 v[92:95], v[152:155], v[180:183], v[92:95]
	v_mfma_f32_16x16x32_bf16 v[92:95], v[156:159], v[184:187], v[92:95]
	v_mfma_f32_16x16x32_bf16 v[104:107], v[144:147], v[188:191], v[104:107]
	v_mfma_f32_16x16x32_bf16 v[104:107], v[148:151], v[192:195], v[104:107]
	v_mfma_f32_16x16x32_bf16 v[108:111], v[152:155], v[188:191], v[108:111]
	v_mfma_f32_16x16x32_bf16 v[108:111], v[156:159], v[192:195], v[108:111]
	v_mfma_f32_16x16x32_bf16 v[120:123], v[144:147], v[196:199], v[120:123]
	v_mfma_f32_16x16x32_bf16 v[120:123], v[148:151], v[200:203], v[120:123]
	v_mfma_f32_16x16x32_bf16 v[124:127], v[152:155], v[196:199], v[124:127]
	v_mfma_f32_16x16x32_bf16 v[124:127], v[156:159], v[200:203], v[124:127]
	s_barrier
	s_nop 4
	v_add_u32_e32 v253, 0x18000, v174
	ds_read_b128 v[128:131], v253
	ds_read_b128 v[132:135], v253 offset:1024
	ds_read_b128 v[136:139], v253 offset:2048
	ds_read_b128 v[140:143], v253 offset:3072
	v_add_u32_e32 v253, 0x1c000, v174
	ds_read_b128 v[144:147], v253
	ds_read_b128 v[148:151], v253 offset:1024
	ds_read_b128 v[152:155], v253 offset:2048
	ds_read_b128 v[156:159], v253 offset:3072
	s_add_u32 s22, s28, 0x40000
	s_addc_u32 s23, s29, 0
	s_mov_b32 m0, s41
	ds_read_b128 v[168:171], v175 offset:32768
	ds_read_b128 v[176:179], v175 offset:33792
	ds_read_b128 v[180:183], v175 offset:34816
	ds_read_b128 v[184:187], v175 offset:35840
	ds_read_b128 v[188:191], v175 offset:36864
	ds_read_b128 v[192:195], v175 offset:37888
	ds_read_b128 v[196:199], v175 offset:38912
	ds_read_b128 v[200:203], v175 offset:39936
	global_load_lds_dwordx4 v160, s[22:23]
	s_mov_b32 m0, s42
	s_nop 0
	global_load_lds_dwordx4 v162, s[22:23]
	s_waitcnt vmcnt(8) lgkmcnt(0)
	s_barrier
	v_mfma_f32_16x16x32_bf16 v[0:3], v[128:131], v[168:171], v[0:3]
	v_mfma_f32_16x16x32_bf16 v[0:3], v[132:135], v[176:179], v[0:3]
	v_mfma_f32_16x16x32_bf16 v[4:7], v[136:139], v[168:171], v[4:7]
	v_mfma_f32_16x16x32_bf16 v[4:7], v[140:143], v[176:179], v[4:7]
	v_mfma_f32_16x16x32_bf16 v[16:19], v[128:131], v[180:183], v[16:19]
	v_mfma_f32_16x16x32_bf16 v[16:19], v[132:135], v[184:187], v[16:19]
	v_mfma_f32_16x16x32_bf16 v[20:23], v[136:139], v[180:183], v[20:23]
	v_mfma_f32_16x16x32_bf16 v[20:23], v[140:143], v[184:187], v[20:23]
	v_mfma_f32_16x16x32_bf16 v[32:35], v[128:131], v[188:191], v[32:35]
	v_mfma_f32_16x16x32_bf16 v[32:35], v[132:135], v[192:195], v[32:35]
	v_mfma_f32_16x16x32_bf16 v[36:39], v[136:139], v[188:191], v[36:39]
	v_mfma_f32_16x16x32_bf16 v[36:39], v[140:143], v[192:195], v[36:39]
	v_mfma_f32_16x16x32_bf16 v[48:51], v[128:131], v[196:199], v[48:51]
	v_mfma_f32_16x16x32_bf16 v[48:51], v[132:135], v[200:203], v[48:51]
	v_mfma_f32_16x16x32_bf16 v[52:55], v[136:139], v[196:199], v[52:55]
	v_mfma_f32_16x16x32_bf16 v[52:55], v[140:143], v[200:203], v[52:55]
	v_mfma_f32_16x16x32_bf16 v[12:15], v[152:155], v[168:171], v[12:15]
	v_mfma_f32_16x16x32_bf16 v[12:15], v[156:159], v[176:179], v[12:15]
	v_mfma_f32_16x16x32_bf16 v[24:27], v[144:147], v[180:183], v[24:27]
	v_mfma_f32_16x16x32_bf16 v[24:27], v[148:151], v[184:187], v[24:27]
	v_mfma_f32_16x16x32_bf16 v[28:31], v[152:155], v[180:183], v[28:31]
	v_mfma_f32_16x16x32_bf16 v[8:11], v[144:147], v[168:171], v[8:11]
	v_mfma_f32_16x16x32_bf16 v[28:31], v[156:159], v[184:187], v[28:31]
	v_mfma_f32_16x16x32_bf16 v[40:43], v[144:147], v[188:191], v[40:43]
	v_mfma_f32_16x16x32_bf16 v[8:11], v[148:151], v[176:179], v[8:11]
	v_mfma_f32_16x16x32_bf16 v[40:43], v[148:151], v[192:195], v[40:43]
	v_mfma_f32_16x16x32_bf16 v[44:47], v[152:155], v[188:191], v[44:47]
	v_mfma_f32_16x16x32_bf16 v[44:47], v[156:159], v[192:195], v[44:47]
	v_mfma_f32_16x16x32_bf16 v[56:59], v[144:147], v[196:199], v[56:59]
	v_mfma_f32_16x16x32_bf16 v[56:59], v[148:151], v[200:203], v[56:59]
	v_mfma_f32_16x16x32_bf16 v[60:63], v[152:155], v[196:199], v[60:63]
	v_mfma_f32_16x16x32_bf16 v[60:63], v[156:159], v[200:203], v[60:63]
	s_barrier
	s_mov_b32 m0, s56
	s_add_u32 s68, s26, s94
	s_addc_u32 s69, s27, s95
	s_add_u32 s70, s26, s94
	s_addc_u32 s71, s27, s95
	s_add_u32 s22, s26, 0x10080
	s_nop 1
	ds_read_b128 v[168:171], v175 offset:49152
	ds_read_b128 v[176:179], v175 offset:50176
	ds_read_b128 v[180:183], v175 offset:51200
	ds_read_b128 v[184:187], v175 offset:52224
	ds_read_b128 v[188:191], v175 offset:53248
	ds_read_b128 v[192:195], v175 offset:54272
	ds_read_b128 v[196:199], v175 offset:55296
	ds_read_b128 v[200:203], v175 offset:56320
	global_load_lds_dwordx4 v232, s[68:69]
	s_mov_b32 m0, s54
	s_addc_u32 s23, s27, 0
	global_load_lds_dwordx4 v164, s[70:71]
	s_mov_b32 m0, s24
	s_nop 0
	global_load_lds_dwordx4 v232, s[22:23]
	s_mov_b32 m0, s25
	s_nop 0
	global_load_lds_dwordx4 v164, s[22:23]
	s_add_u32 s68, s28, s94
	s_addc_u32 s69, s29, s95
	s_mov_b32 m0, s47
	s_nop 0
	global_load_lds_dwordx4 v160, s[68:69]
	s_add_u32 s68, s28, s94
	s_addc_u32 s69, s29, s95
	s_mov_b32 m0, s48
	s_nop 0
	global_load_lds_dwordx4 v162, s[68:69]
	s_waitcnt vmcnt(8) lgkmcnt(0)
	s_barrier
	v_mfma_f32_16x16x32_bf16 v[64:67], v[128:131], v[168:171], v[64:67]
	v_mfma_f32_16x16x32_bf16 v[64:67], v[132:135], v[176:179], v[64:67]
	v_mfma_f32_16x16x32_bf16 v[68:71], v[136:139], v[168:171], v[68:71]
	v_mfma_f32_16x16x32_bf16 v[68:71], v[140:143], v[176:179], v[68:71]
	v_mfma_f32_16x16x32_bf16 v[80:83], v[128:131], v[180:183], v[80:83]
	v_mfma_f32_16x16x32_bf16 v[80:83], v[132:135], v[184:187], v[80:83]
	v_mfma_f32_16x16x32_bf16 v[84:87], v[136:139], v[180:183], v[84:87]
	v_mfma_f32_16x16x32_bf16 v[84:87], v[140:143], v[184:187], v[84:87]
	v_mfma_f32_16x16x32_bf16 v[96:99], v[128:131], v[188:191], v[96:99]
	v_mfma_f32_16x16x32_bf16 v[112:115], v[128:131], v[196:199], v[112:115]
	v_mfma_f32_16x16x32_bf16 v[96:99], v[132:135], v[192:195], v[96:99]
	v_mfma_f32_16x16x32_bf16 v[100:103], v[136:139], v[188:191], v[100:103]
	v_mfma_f32_16x16x32_bf16 v[112:115], v[132:135], v[200:203], v[112:115]
	v_mfma_f32_16x16x32_bf16 v[116:119], v[136:139], v[196:199], v[116:119]
	v_mfma_f32_16x16x32_bf16 v[100:103], v[140:143], v[192:195], v[100:103]
	v_mfma_f32_16x16x32_bf16 v[116:119], v[140:143], v[200:203], v[116:119]
	v_mfma_f32_16x16x32_bf16 v[72:75], v[144:147], v[168:171], v[72:75]
	v_mfma_f32_16x16x32_bf16 v[72:75], v[148:151], v[176:179], v[72:75]
	v_mfma_f32_16x16x32_bf16 v[76:79], v[152:155], v[168:171], v[76:79]
	v_mfma_f32_16x16x32_bf16 v[76:79], v[156:159], v[176:179], v[76:79]
	v_mfma_f32_16x16x32_bf16 v[88:91], v[144:147], v[180:183], v[88:91]
	v_mfma_f32_16x16x32_bf16 v[88:91], v[148:151], v[184:187], v[88:91]
	v_mfma_f32_16x16x32_bf16 v[92:95], v[152:155], v[180:183], v[92:95]
	v_mfma_f32_16x16x32_bf16 v[92:95], v[156:159], v[184:187], v[92:95]
	v_mfma_f32_16x16x32_bf16 v[104:107], v[144:147], v[188:191], v[104:107]
	v_mfma_f32_16x16x32_bf16 v[104:107], v[148:151], v[192:195], v[104:107]
	v_mfma_f32_16x16x32_bf16 v[108:111], v[152:155], v[188:191], v[108:111]
	v_mfma_f32_16x16x32_bf16 v[108:111], v[156:159], v[192:195], v[108:111]
	v_mfma_f32_16x16x32_bf16 v[120:123], v[144:147], v[196:199], v[120:123]
	v_mfma_f32_16x16x32_bf16 v[120:123], v[148:151], v[200:203], v[120:123]
	v_mfma_f32_16x16x32_bf16 v[124:127], v[152:155], v[196:199], v[124:127]
	v_mfma_f32_16x16x32_bf16 v[124:127], v[156:159], v[200:203], v[124:127]
	s_barrier
	s_andn2_b64 vcc, exec, s[10:11]
	s_cbranch_vccnz .LBB0_1020
	s_barrier

.LBB0_1163:
	s_ashr_i32 s23, s22, 31
	s_lshl_b64 s[24:25], s[22:23], 19
	s_add_u32 s24, s42, s24
	s_addc_u32 s25, s43, s25
	s_and_b64 s[26:27], s[4:5], exec
	s_cselect_b32 s23, s25, s35
	s_cselect_b32 s56, s24, s34
	s_ashr_i32 s21, s20, 31
	s_lshl_b64 s[26:27], s[20:21], 19
	s_add_u32 s26, s44, s26
	s_addc_u32 s27, s45, s27
	s_and_b64 s[36:37], s[4:5], exec
	s_cselect_b32 s21, s27, s31
	s_cselect_b32 s57, s26, s30
	s_add_u32 s58, s30, 0x100
	s_addc_u32 s59, s31, 0
	s_add_u32 s30, s34, 0x40080
	s_addc_u32 s31, s35, 0
	s_mov_b32 s60, -2
	s_waitcnt vmcnt(0)
	s_add_u32 s34, s30, 0xfffc0080
	s_addc_u32 s35, s31, -1
	s_add_i32 s61, 0, 0x10000
	s_cmp_eq_u32 s60, 12
	s_cselect_b32 s37, s23, s35
	s_cselect_b32 s36, s56, s34
	s_cselect_b32 s35, s21, s59
	s_cselect_b32 s34, s57, s58
	s_add_i32 s64, 0, 0x14000
	v_add_u32_e32 v140, s61, v174
	v_add_u32_e32 v166, s64, v174
	ds_read_b128 v[128:131], v140
	ds_read_b128 v[132:135], v140 offset:1024
	ds_read_b128 v[136:139], v140 offset:2048
	ds_read_b128 v[140:143], v140 offset:3072
	ds_read_b128 v[154:157], v166
	ds_read_b128 v[158:161], v166 offset:1024
	ds_read_b128 v[162:165], v166 offset:2048
	ds_read_b128 v[166:169], v166 offset:3072
	v_lshl_add_u64 v[204:205], s[30:31], 0, v[152:153]
	s_add_i32 m0, s29, 0xc000
	ds_read_b128 v[170:173], v175
	ds_read_b128 v[176:179], v175 offset:1024
	ds_read_b128 v[180:183], v175 offset:2048
	ds_read_b128 v[184:187], v175 offset:3072
	ds_read_b128 v[188:191], v175 offset:4096
	ds_read_b128 v[192:195], v175 offset:5120
	ds_read_b128 v[196:199], v175 offset:6144
	ds_read_b128 v[200:203], v175 offset:7168
	global_load_lds_dwordx4 v[204:205], off
	v_lshl_add_u64 v[204:205], s[30:31], 0, v[150:151]
	s_add_i32 m0, s29, 0xe000
	s_nop 0
	global_load_lds_dwordx4 v[204:205], off
	s_waitcnt vmcnt(8) lgkmcnt(0)
	s_barrier
	v_mfma_f32_16x16x32_bf16 v[124:127], v[128:131], v[170:173], 0
	v_mfma_f32_16x16x32_bf16 v[120:123], v[136:139], v[170:173], 0
	v_mfma_f32_16x16x32_bf16 v[108:111], v[128:131], v[180:183], 0
	v_mfma_f32_16x16x32_bf16 v[104:107], v[136:139], v[180:183], 0
	v_mfma_f32_16x16x32_bf16 v[92:95], v[128:131], v[188:191], 0
	v_mfma_f32_16x16x32_bf16 v[88:91], v[136:139], v[188:191], 0
	v_mfma_f32_16x16x32_bf16 v[80:83], v[128:131], v[196:199], 0
	v_mfma_f32_16x16x32_bf16 v[72:75], v[136:139], v[196:199], 0
	v_mfma_f32_16x16x32_bf16 v[124:127], v[132:135], v[176:179], v[124:127]
	v_mfma_f32_16x16x32_bf16 v[120:123], v[140:143], v[176:179], v[120:123]
	v_mfma_f32_16x16x32_bf16 v[108:111], v[132:135], v[184:187], v[108:111]
	v_mfma_f32_16x16x32_bf16 v[104:107], v[140:143], v[184:187], v[104:107]
	v_mfma_f32_16x16x32_bf16 v[92:95], v[132:135], v[192:195], v[92:95]
	v_mfma_f32_16x16x32_bf16 v[88:91], v[140:143], v[192:195], v[88:91]
	v_mfma_f32_16x16x32_bf16 v[80:83], v[132:135], v[200:203], v[80:83]
	v_mfma_f32_16x16x32_bf16 v[72:75], v[140:143], v[200:203], v[72:75]
	v_mfma_f32_16x16x32_bf16 v[116:119], v[154:157], v[170:173], 0
	v_mfma_f32_16x16x32_bf16 v[112:115], v[162:165], v[170:173], 0
	v_mfma_f32_16x16x32_bf16 v[100:103], v[154:157], v[180:183], 0
	v_mfma_f32_16x16x32_bf16 v[96:99], v[162:165], v[180:183], 0
	v_mfma_f32_16x16x32_bf16 v[84:87], v[154:157], v[188:191], 0
	v_mfma_f32_16x16x32_bf16 v[76:79], v[162:165], v[188:191], 0
	v_mfma_f32_16x16x32_bf16 v[68:71], v[154:157], v[196:199], 0
	v_mfma_f32_16x16x32_bf16 v[64:67], v[162:165], v[196:199], 0
	v_mfma_f32_16x16x32_bf16 v[116:119], v[158:161], v[176:179], v[116:119]
	v_mfma_f32_16x16x32_bf16 v[112:115], v[166:169], v[176:179], v[112:115]
	v_mfma_f32_16x16x32_bf16 v[100:103], v[158:161], v[184:187], v[100:103]
	v_mfma_f32_16x16x32_bf16 v[96:99], v[166:169], v[184:187], v[96:99]
	v_mfma_f32_16x16x32_bf16 v[84:87], v[158:161], v[192:195], v[84:87]
	v_mfma_f32_16x16x32_bf16 v[76:79], v[166:169], v[192:195], v[76:79]
	v_mfma_f32_16x16x32_bf16 v[68:71], v[158:161], v[200:203], v[68:71]
	v_mfma_f32_16x16x32_bf16 v[64:67], v[166:169], v[200:203], v[64:67]
	s_barrier
	s_add_i32 s61, s61, s41
	v_lshl_add_u64 v[204:205], s[34:35], 0, v[232:233]
	s_mov_b32 m0, s61
	ds_read_b128 v[170:173], v175 offset:16384
	ds_read_b128 v[176:179], v175 offset:17408
	ds_read_b128 v[180:183], v175 offset:18432
	ds_read_b128 v[184:187], v175 offset:19456
	ds_read_b128 v[188:191], v175 offset:20480
	ds_read_b128 v[192:195], v175 offset:21504
	ds_read_b128 v[196:199], v175 offset:22528
	ds_read_b128 v[200:203], v175 offset:23552
	global_load_lds_dwordx4 v[204:205], off
	s_add_i32 m0, s61, 0x2000
	s_add_u32 s62, s34, 0x40000
	v_lshl_add_u64 v[206:207], s[34:35], 0, v[148:149]
	s_addc_u32 s63, s35, 0
	s_add_i32 s61, s64, s41
	global_load_lds_dwordx4 v[206:207], off
	v_lshl_add_u64 v[208:209], s[62:63], 0, v[232:233]
	s_mov_b32 m0, s61
	v_lshl_add_u64 v[210:211], s[36:37], 0, v[146:147]
	global_load_lds_dwordx4 v[208:209], off
	v_lshl_add_u64 v[208:209], s[62:63], 0, v[148:149]
	s_add_i32 m0, s61, 0x2000
	s_nop 0
	global_load_lds_dwordx4 v[208:209], off
	v_lshl_add_u64 v[208:209], s[36:37], 0, v[144:145]
	s_waitcnt vmcnt(6) lgkmcnt(0)
	s_barrier
	v_mfma_f32_16x16x32_bf16 v[60:63], v[128:131], v[170:173], 0
	v_mfma_f32_16x16x32_bf16 v[56:59], v[136:139], v[170:173], 0
	v_mfma_f32_16x16x32_bf16 v[48:51], v[128:131], v[180:183], 0
	v_mfma_f32_16x16x32_bf16 v[40:43], v[136:139], v[180:183], 0
	v_mfma_f32_16x16x32_bf16 v[28:31], v[128:131], v[188:191], 0
	v_mfma_f32_16x16x32_bf16 v[24:27], v[136:139], v[188:191], 0
	v_mfma_f32_16x16x32_bf16 v[16:19], v[128:131], v[196:199], 0
	v_mfma_f32_16x16x32_bf16 v[8:11], v[136:139], v[196:199], 0
	v_mfma_f32_16x16x32_bf16 v[60:63], v[132:135], v[176:179], v[60:63]
	v_mfma_f32_16x16x32_bf16 v[56:59], v[140:143], v[176:179], v[56:59]
	v_mfma_f32_16x16x32_bf16 v[48:51], v[132:135], v[184:187], v[48:51]
	v_mfma_f32_16x16x32_bf16 v[40:43], v[140:143], v[184:187], v[40:43]
	v_mfma_f32_16x16x32_bf16 v[28:31], v[132:135], v[192:195], v[28:31]
	v_mfma_f32_16x16x32_bf16 v[24:27], v[140:143], v[192:195], v[24:27]
	v_mfma_f32_16x16x32_bf16 v[16:19], v[132:135], v[200:203], v[16:19]
	v_mfma_f32_16x16x32_bf16 v[8:11], v[140:143], v[200:203], v[8:11]
	v_mfma_f32_16x16x32_bf16 v[52:55], v[154:157], v[170:173], 0
	v_mfma_f32_16x16x32_bf16 v[44:47], v[162:165], v[170:173], 0
	v_mfma_f32_16x16x32_bf16 v[36:39], v[154:157], v[180:183], 0
	v_mfma_f32_16x16x32_bf16 v[32:35], v[162:165], v[180:183], 0
	v_mfma_f32_16x16x32_bf16 v[20:23], v[154:157], v[188:191], 0
	v_mfma_f32_16x16x32_bf16 v[12:15], v[162:165], v[188:191], 0
	v_mfma_f32_16x16x32_bf16 v[4:7], v[154:157], v[196:199], 0
	v_mfma_f32_16x16x32_bf16 v[0:3], v[162:165], v[196:199], 0
	v_mfma_f32_16x16x32_bf16 v[52:55], v[158:161], v[176:179], v[52:55]
	v_mfma_f32_16x16x32_bf16 v[44:47], v[166:169], v[176:179], v[44:47]
	v_mfma_f32_16x16x32_bf16 v[36:39], v[158:161], v[184:187], v[36:39]
	v_mfma_f32_16x16x32_bf16 v[32:35], v[166:169], v[184:187], v[32:35]
	v_mfma_f32_16x16x32_bf16 v[20:23], v[158:161], v[192:195], v[20:23]
	v_mfma_f32_16x16x32_bf16 v[12:15], v[166:169], v[192:195], v[12:15]
	v_mfma_f32_16x16x32_bf16 v[4:7], v[158:161], v[200:203], v[4:7]
	v_mfma_f32_16x16x32_bf16 v[0:3], v[166:169], v[200:203], v[0:3]
	s_barrier
	s_branch .Lzmid_3
.LBB0_1164:
	s_add_u32 s34, s30, 0xfffc0080
	s_addc_u32 s35, s31, -1
	s_add_i32 s61, 0, 0x10000
	s_cmp_eq_u32 s60, 12
	s_cselect_b32 s37, s23, s35
	s_cselect_b32 s36, s56, s34
	s_cselect_b32 s35, s21, s59
	s_cselect_b32 s34, s57, s58
	s_add_i32 s64, 0, 0x14000
	v_add_u32_e32 v140, s61, v174
	v_add_u32_e32 v166, s64, v174
	ds_read_b128 v[128:131], v140
	ds_read_b128 v[132:135], v140 offset:1024
	ds_read_b128 v[136:139], v140 offset:2048
	ds_read_b128 v[140:143], v140 offset:3072
	ds_read_b128 v[154:157], v166
	ds_read_b128 v[158:161], v166 offset:1024
	ds_read_b128 v[162:165], v166 offset:2048
	ds_read_b128 v[166:169], v166 offset:3072
	v_lshl_add_u64 v[204:205], s[30:31], 0, v[152:153]
	s_add_i32 m0, s29, 0xc000
	ds_read_b128 v[170:173], v175
	ds_read_b128 v[176:179], v175 offset:1024
	ds_read_b128 v[180:183], v175 offset:2048
	ds_read_b128 v[184:187], v175 offset:3072
	ds_read_b128 v[188:191], v175 offset:4096
	ds_read_b128 v[192:195], v175 offset:5120
	ds_read_b128 v[196:199], v175 offset:6144
	ds_read_b128 v[200:203], v175 offset:7168
	global_load_lds_dwordx4 v[204:205], off
	v_lshl_add_u64 v[204:205], s[30:31], 0, v[150:151]
	s_add_i32 m0, s29, 0xe000
	s_nop 0
	global_load_lds_dwordx4 v[204:205], off
	s_waitcnt vmcnt(8) lgkmcnt(0)
	s_barrier
	v_mfma_f32_16x16x32_bf16 v[124:127], v[128:131], v[170:173], v[124:127]
	v_mfma_f32_16x16x32_bf16 v[120:123], v[136:139], v[170:173], v[120:123]
	v_mfma_f32_16x16x32_bf16 v[108:111], v[128:131], v[180:183], v[108:111]
	v_mfma_f32_16x16x32_bf16 v[104:107], v[136:139], v[180:183], v[104:107]
	v_mfma_f32_16x16x32_bf16 v[92:95], v[128:131], v[188:191], v[92:95]
	v_mfma_f32_16x16x32_bf16 v[88:91], v[136:139], v[188:191], v[88:91]
	v_mfma_f32_16x16x32_bf16 v[80:83], v[128:131], v[196:199], v[80:83]
	v_mfma_f32_16x16x32_bf16 v[72:75], v[136:139], v[196:199], v[72:75]
	v_mfma_f32_16x16x32_bf16 v[124:127], v[132:135], v[176:179], v[124:127]
	v_mfma_f32_16x16x32_bf16 v[120:123], v[140:143], v[176:179], v[120:123]
	v_mfma_f32_16x16x32_bf16 v[108:111], v[132:135], v[184:187], v[108:111]
	v_mfma_f32_16x16x32_bf16 v[104:107], v[140:143], v[184:187], v[104:107]
	v_mfma_f32_16x16x32_bf16 v[92:95], v[132:135], v[192:195], v[92:95]
	v_mfma_f32_16x16x32_bf16 v[88:91], v[140:143], v[192:195], v[88:91]
	v_mfma_f32_16x16x32_bf16 v[80:83], v[132:135], v[200:203], v[80:83]
	v_mfma_f32_16x16x32_bf16 v[72:75], v[140:143], v[200:203], v[72:75]
	v_mfma_f32_16x16x32_bf16 v[116:119], v[154:157], v[170:173], v[116:119]
	v_mfma_f32_16x16x32_bf16 v[112:115], v[162:165], v[170:173], v[112:115]
	v_mfma_f32_16x16x32_bf16 v[100:103], v[154:157], v[180:183], v[100:103]
	v_mfma_f32_16x16x32_bf16 v[96:99], v[162:165], v[180:183], v[96:99]
	v_mfma_f32_16x16x32_bf16 v[84:87], v[154:157], v[188:191], v[84:87]
	v_mfma_f32_16x16x32_bf16 v[76:79], v[162:165], v[188:191], v[76:79]
	v_mfma_f32_16x16x32_bf16 v[68:71], v[154:157], v[196:199], v[68:71]
	v_mfma_f32_16x16x32_bf16 v[64:67], v[162:165], v[196:199], v[64:67]
	v_mfma_f32_16x16x32_bf16 v[116:119], v[158:161], v[176:179], v[116:119]
	v_mfma_f32_16x16x32_bf16 v[112:115], v[166:169], v[176:179], v[112:115]
	v_mfma_f32_16x16x32_bf16 v[100:103], v[158:161], v[184:187], v[100:103]
	v_mfma_f32_16x16x32_bf16 v[96:99], v[166:169], v[184:187], v[96:99]
	v_mfma_f32_16x16x32_bf16 v[84:87], v[158:161], v[192:195], v[84:87]
	v_mfma_f32_16x16x32_bf16 v[76:79], v[166:169], v[192:195], v[76:79]
	v_mfma_f32_16x16x32_bf16 v[68:71], v[158:161], v[200:203], v[68:71]
	v_mfma_f32_16x16x32_bf16 v[64:67], v[166:169], v[200:203], v[64:67]
	s_barrier
	s_add_i32 s61, s61, s41
	v_lshl_add_u64 v[204:205], s[34:35], 0, v[232:233]
	s_mov_b32 m0, s61
	ds_read_b128 v[170:173], v175 offset:16384
	ds_read_b128 v[176:179], v175 offset:17408
	ds_read_b128 v[180:183], v175 offset:18432
	ds_read_b128 v[184:187], v175 offset:19456
	ds_read_b128 v[188:191], v175 offset:20480
	ds_read_b128 v[192:195], v175 offset:21504
	ds_read_b128 v[196:199], v175 offset:22528
	ds_read_b128 v[200:203], v175 offset:23552
	global_load_lds_dwordx4 v[204:205], off
	s_add_i32 m0, s61, 0x2000
	s_add_u32 s62, s34, 0x40000
	v_lshl_add_u64 v[206:207], s[34:35], 0, v[148:149]
	s_addc_u32 s63, s35, 0
	s_add_i32 s61, s64, s41
	global_load_lds_dwordx4 v[206:207], off
	v_lshl_add_u64 v[208:209], s[62:63], 0, v[232:233]
	s_mov_b32 m0, s61
	v_lshl_add_u64 v[210:211], s[36:37], 0, v[146:147]
	global_load_lds_dwordx4 v[208:209], off
	v_lshl_add_u64 v[208:209], s[62:63], 0, v[148:149]
	s_add_i32 m0, s61, 0x2000
	s_nop 0
	global_load_lds_dwordx4 v[208:209], off
	v_lshl_add_u64 v[208:209], s[36:37], 0, v[144:145]
	s_waitcnt vmcnt(6) lgkmcnt(0)
	s_barrier
	v_mfma_f32_16x16x32_bf16 v[60:63], v[128:131], v[170:173], v[60:63]
	v_mfma_f32_16x16x32_bf16 v[56:59], v[136:139], v[170:173], v[56:59]
	v_mfma_f32_16x16x32_bf16 v[48:51], v[128:131], v[180:183], v[48:51]
	v_mfma_f32_16x16x32_bf16 v[40:43], v[136:139], v[180:183], v[40:43]
	v_mfma_f32_16x16x32_bf16 v[28:31], v[128:131], v[188:191], v[28:31]
	v_mfma_f32_16x16x32_bf16 v[24:27], v[136:139], v[188:191], v[24:27]
	v_mfma_f32_16x16x32_bf16 v[16:19], v[128:131], v[196:199], v[16:19]
	v_mfma_f32_16x16x32_bf16 v[8:11], v[136:139], v[196:199], v[8:11]
	v_mfma_f32_16x16x32_bf16 v[60:63], v[132:135], v[176:179], v[60:63]
	v_mfma_f32_16x16x32_bf16 v[56:59], v[140:143], v[176:179], v[56:59]
	v_mfma_f32_16x16x32_bf16 v[48:51], v[132:135], v[184:187], v[48:51]
	v_mfma_f32_16x16x32_bf16 v[40:43], v[140:143], v[184:187], v[40:43]
	v_mfma_f32_16x16x32_bf16 v[28:31], v[132:135], v[192:195], v[28:31]
	v_mfma_f32_16x16x32_bf16 v[24:27], v[140:143], v[192:195], v[24:27]
	v_mfma_f32_16x16x32_bf16 v[16:19], v[132:135], v[200:203], v[16:19]
	v_mfma_f32_16x16x32_bf16 v[8:11], v[140:143], v[200:203], v[8:11]
	v_mfma_f32_16x16x32_bf16 v[52:55], v[154:157], v[170:173], v[52:55]
	v_mfma_f32_16x16x32_bf16 v[44:47], v[162:165], v[170:173], v[44:47]
	v_mfma_f32_16x16x32_bf16 v[36:39], v[154:157], v[180:183], v[36:39]
	v_mfma_f32_16x16x32_bf16 v[32:35], v[162:165], v[180:183], v[32:35]
	v_mfma_f32_16x16x32_bf16 v[20:23], v[154:157], v[188:191], v[20:23]
	v_mfma_f32_16x16x32_bf16 v[12:15], v[162:165], v[188:191], v[12:15]
	v_mfma_f32_16x16x32_bf16 v[4:7], v[154:157], v[196:199], v[4:7]
	v_mfma_f32_16x16x32_bf16 v[0:3], v[162:165], v[196:199], v[0:3]
	v_mfma_f32_16x16x32_bf16 v[52:55], v[158:161], v[176:179], v[52:55]
	v_mfma_f32_16x16x32_bf16 v[44:47], v[166:169], v[176:179], v[44:47]
	v_mfma_f32_16x16x32_bf16 v[36:39], v[158:161], v[184:187], v[36:39]
	v_mfma_f32_16x16x32_bf16 v[32:35], v[166:169], v[184:187], v[32:35]
	v_mfma_f32_16x16x32_bf16 v[20:23], v[158:161], v[192:195], v[20:23]
	v_mfma_f32_16x16x32_bf16 v[12:15], v[166:169], v[192:195], v[12:15]
	v_mfma_f32_16x16x32_bf16 v[4:7], v[158:161], v[200:203], v[4:7]
	v_mfma_f32_16x16x32_bf16 v[0:3], v[166:169], v[200:203], v[0:3]
	s_barrier
.Lzmid_3:
	s_add_i32 s61, 0, 0x18000
	s_add_i32 s62, 0, 0x1c000
	v_add_u32_e32 v140, s61, v174
	v_add_u32_e32 v166, s62, v174
	ds_read_b128 v[128:131], v140
	ds_read_b128 v[132:135], v140 offset:1024
	ds_read_b128 v[136:139], v140 offset:2048
	ds_read_b128 v[140:143], v140 offset:3072
	ds_read_b128 v[154:157], v166
	ds_read_b128 v[158:161], v166 offset:1024
	ds_read_b128 v[162:165], v166 offset:2048
	ds_read_b128 v[166:169], v166 offset:3072
	s_add_u32 s36, s36, 0x40000
	s_addc_u32 s37, s37, 0
	s_mov_b32 m0, s29
	s_nop 0
	global_load_lds_dwordx4 v[208:209], off
	s_mov_b32 m0, s46
	s_nop 0
	global_load_lds_dwordx4 v[210:211], off
	s_mov_b32 m0, s47
	v_lshl_add_u64 v[212:213], s[36:37], 0, v[144:145]
	ds_read_b128 v[170:173], v175 offset:32768
	ds_read_b128 v[176:179], v175 offset:33792
	ds_read_b128 v[180:183], v175 offset:34816
	ds_read_b128 v[184:187], v175 offset:35840
	ds_read_b128 v[188:191], v175 offset:36864
	ds_read_b128 v[192:195], v175 offset:37888
	ds_read_b128 v[196:199], v175 offset:38912
	ds_read_b128 v[200:203], v175 offset:39936
	global_load_lds_dwordx4 v[212:213], off
	v_lshl_add_u64 v[212:213], s[36:37], 0, v[146:147]
	s_mov_b32 m0, s48
	s_nop 0
	global_load_lds_dwordx4 v[212:213], off
	s_waitcnt vmcnt(8) lgkmcnt(0)
	s_barrier
	v_mfma_f32_16x16x32_bf16 v[124:127], v[128:131], v[170:173], v[124:127]
	v_mfma_f32_16x16x32_bf16 v[120:123], v[136:139], v[170:173], v[120:123]
	v_mfma_f32_16x16x32_bf16 v[108:111], v[128:131], v[180:183], v[108:111]
	v_mfma_f32_16x16x32_bf16 v[104:107], v[136:139], v[180:183], v[104:107]
	v_mfma_f32_16x16x32_bf16 v[92:95], v[128:131], v[188:191], v[92:95]
	v_mfma_f32_16x16x32_bf16 v[88:91], v[136:139], v[188:191], v[88:91]
	v_mfma_f32_16x16x32_bf16 v[80:83], v[128:131], v[196:199], v[80:83]
	v_mfma_f32_16x16x32_bf16 v[72:75], v[136:139], v[196:199], v[72:75]
	v_mfma_f32_16x16x32_bf16 v[124:127], v[132:135], v[176:179], v[124:127]
	v_mfma_f32_16x16x32_bf16 v[120:123], v[140:143], v[176:179], v[120:123]
	v_mfma_f32_16x16x32_bf16 v[108:111], v[132:135], v[184:187], v[108:111]
	v_mfma_f32_16x16x32_bf16 v[104:107], v[140:143], v[184:187], v[104:107]
	v_mfma_f32_16x16x32_bf16 v[92:95], v[132:135], v[192:195], v[92:95]
	v_mfma_f32_16x16x32_bf16 v[88:91], v[140:143], v[192:195], v[88:91]
	v_mfma_f32_16x16x32_bf16 v[80:83], v[132:135], v[200:203], v[80:83]
	v_mfma_f32_16x16x32_bf16 v[72:75], v[140:143], v[200:203], v[72:75]
	v_mfma_f32_16x16x32_bf16 v[116:119], v[154:157], v[170:173], v[116:119]
	v_mfma_f32_16x16x32_bf16 v[112:115], v[162:165], v[170:173], v[112:115]
	v_mfma_f32_16x16x32_bf16 v[100:103], v[154:157], v[180:183], v[100:103]
	v_mfma_f32_16x16x32_bf16 v[96:99], v[162:165], v[180:183], v[96:99]
	v_mfma_f32_16x16x32_bf16 v[84:87], v[154:157], v[188:191], v[84:87]
	v_mfma_f32_16x16x32_bf16 v[76:79], v[162:165], v[188:191], v[76:79]
	v_mfma_f32_16x16x32_bf16 v[68:71], v[154:157], v[196:199], v[68:71]
	v_mfma_f32_16x16x32_bf16 v[64:67], v[162:165], v[196:199], v[64:67]
	v_mfma_f32_16x16x32_bf16 v[116:119], v[158:161], v[176:179], v[116:119]
	v_mfma_f32_16x16x32_bf16 v[112:115], v[166:169], v[176:179], v[112:115]
	v_mfma_f32_16x16x32_bf16 v[100:103], v[158:161], v[184:187], v[100:103]
	v_mfma_f32_16x16x32_bf16 v[96:99], v[166:169], v[184:187], v[96:99]
	v_mfma_f32_16x16x32_bf16 v[84:87], v[158:161], v[192:195], v[84:87]
	v_mfma_f32_16x16x32_bf16 v[76:79], v[166:169], v[192:195], v[76:79]
	v_mfma_f32_16x16x32_bf16 v[68:71], v[158:161], v[200:203], v[68:71]
	v_mfma_f32_16x16x32_bf16 v[64:67], v[166:169], v[200:203], v[64:67]
	s_barrier
	s_add_i32 s36, s61, s41
	v_lshl_add_u64 v[204:205], v[204:205], 0, s[94:95]
	s_mov_b32 m0, s36
	ds_read_b128 v[170:173], v175 offset:49152
	ds_read_b128 v[176:179], v175 offset:50176
	ds_read_b128 v[180:183], v175 offset:51200
	ds_read_b128 v[184:187], v175 offset:52224
	ds_read_b128 v[188:191], v175 offset:53248
	ds_read_b128 v[192:195], v175 offset:54272
	ds_read_b128 v[196:199], v175 offset:55296
	ds_read_b128 v[200:203], v175 offset:56320
	global_load_lds_dwordx4 v[204:205], off
	s_add_i32 m0, s36, 0x2000
	s_add_u32 s34, s34, 0x40080
	v_lshl_add_u64 v[204:205], v[206:207], 0, s[94:95]
	s_addc_u32 s35, s35, 0
	s_add_i32 s36, s62, s41
	global_load_lds_dwordx4 v[204:205], off
	v_lshl_add_u64 v[204:205], s[34:35], 0, v[232:233]
	s_mov_b32 m0, s36
	s_nop 0
	global_load_lds_dwordx4 v[204:205], off
	v_lshl_add_u64 v[204:205], s[34:35], 0, v[148:149]
	s_add_i32 m0, s36, 0x2000
	s_nop 0
	global_load_lds_dwordx4 v[204:205], off
	v_lshl_add_u64 v[204:205], v[208:209], 0, s[94:95]
	s_mov_b32 m0, s51
	s_nop 0
	global_load_lds_dwordx4 v[204:205], off
	v_lshl_add_u64 v[204:205], v[210:211], 0, s[94:95]
	s_mov_b32 m0, s52
	s_nop 0
	global_load_lds_dwordx4 v[204:205], off
	s_waitcnt vmcnt(8) lgkmcnt(0)
	s_barrier
	v_mfma_f32_16x16x32_bf16 v[60:63], v[128:131], v[170:173], v[60:63]
	v_mfma_f32_16x16x32_bf16 v[56:59], v[136:139], v[170:173], v[56:59]
	v_mfma_f32_16x16x32_bf16 v[48:51], v[128:131], v[180:183], v[48:51]
	v_mfma_f32_16x16x32_bf16 v[40:43], v[136:139], v[180:183], v[40:43]
	v_mfma_f32_16x16x32_bf16 v[28:31], v[128:131], v[188:191], v[28:31]
	v_mfma_f32_16x16x32_bf16 v[24:27], v[136:139], v[188:191], v[24:27]
	v_mfma_f32_16x16x32_bf16 v[16:19], v[128:131], v[196:199], v[16:19]
	v_mfma_f32_16x16x32_bf16 v[8:11], v[136:139], v[196:199], v[8:11]
	v_mfma_f32_16x16x32_bf16 v[60:63], v[132:135], v[176:179], v[60:63]
	v_mfma_f32_16x16x32_bf16 v[56:59], v[140:143], v[176:179], v[56:59]
	v_mfma_f32_16x16x32_bf16 v[48:51], v[132:135], v[184:187], v[48:51]
	v_mfma_f32_16x16x32_bf16 v[40:43], v[140:143], v[184:187], v[40:43]
	v_mfma_f32_16x16x32_bf16 v[28:31], v[132:135], v[192:195], v[28:31]
	v_mfma_f32_16x16x32_bf16 v[24:27], v[140:143], v[192:195], v[24:27]
	v_mfma_f32_16x16x32_bf16 v[16:19], v[132:135], v[200:203], v[16:19]
	v_mfma_f32_16x16x32_bf16 v[8:11], v[140:143], v[200:203], v[8:11]
	v_mfma_f32_16x16x32_bf16 v[52:55], v[154:157], v[170:173], v[52:55]
	v_mfma_f32_16x16x32_bf16 v[44:47], v[162:165], v[170:173], v[44:47]
	v_mfma_f32_16x16x32_bf16 v[36:39], v[154:157], v[180:183], v[36:39]
	v_mfma_f32_16x16x32_bf16 v[32:35], v[162:165], v[180:183], v[32:35]
	v_mfma_f32_16x16x32_bf16 v[20:23], v[154:157], v[188:191], v[20:23]
	v_mfma_f32_16x16x32_bf16 v[12:15], v[162:165], v[188:191], v[12:15]
	v_mfma_f32_16x16x32_bf16 v[4:7], v[154:157], v[196:199], v[4:7]
	v_mfma_f32_16x16x32_bf16 v[0:3], v[162:165], v[196:199], v[0:3]
	v_mfma_f32_16x16x32_bf16 v[52:55], v[158:161], v[176:179], v[52:55]
	v_mfma_f32_16x16x32_bf16 v[44:47], v[166:169], v[176:179], v[44:47]
	v_mfma_f32_16x16x32_bf16 v[36:39], v[158:161], v[184:187], v[36:39]
	v_mfma_f32_16x16x32_bf16 v[32:35], v[166:169], v[184:187], v[32:35]
	v_mfma_f32_16x16x32_bf16 v[20:23], v[158:161], v[192:195], v[20:23]
	v_mfma_f32_16x16x32_bf16 v[12:15], v[166:169], v[192:195], v[12:15]
	v_mfma_f32_16x16x32_bf16 v[4:7], v[158:161], v[200:203], v[4:7]
	v_mfma_f32_16x16x32_bf16 v[0:3], v[166:169], v[200:203], v[0:3]
	s_barrier
	s_add_i32 s60, s60, 2
	s_add_u32 s58, s58, 0x100
	s_addc_u32 s59, s59, 0
	s_add_u32 s30, s30, 0x100
	s_addc_u32 s31, s31, 0
	s_cmp_gt_u32 s60, 13
	s_cbranch_scc0 .LBB0_1164
	s_and_b64 vcc, exec, s[18:19]
	s_cbranch_vccz .LBB0_1167
	s_barrier

.LBB0_1306:
	s_ashr_i32 s17, s16, 31
	s_lshl_b64 s[18:19], s[16:17], 19
	s_add_u32 s18, s34, s18
	s_addc_u32 s19, s35, s19
	s_and_b64 s[20:21], s[4:5], exec
	s_cselect_b32 s7, s19, s27
	s_cselect_b32 s17, s18, s26
	s_ashr_i32 s15, s14, 31
	s_lshl_b64 s[20:21], s[14:15], 19
	s_add_u32 s20, s36, s20
	s_addc_u32 s21, s37, s21
	s_and_b64 s[28:29], s[4:5], exec
	s_cselect_b32 s15, s21, s25
	s_cselect_b32 s23, s20, s24
	s_add_u32 s50, s24, 0x100
	s_addc_u32 s51, s25, 0
	s_add_u32 s24, s26, 0x40080
	s_addc_u32 s25, s27, 0
	s_mov_b32 s52, -2
	s_add_u32 s26, s24, 0xfffc0080
	s_addc_u32 s27, s25, -1
	s_add_i32 s53, 0, 0x10000
	s_cmp_eq_u32 s52, 12
	s_cselect_b32 s29, s7, s27
	s_cselect_b32 s28, s17, s26
	v_add_u32_e32 v142, s53, v144
	s_cselect_b32 s27, s15, s51
	s_cselect_b32 s26, s23, s50
	s_add_i32 s56, 0, 0x14000
	ds_read_b128 v[138:141], v142
	ds_read_b128 v[146:149], v142 offset:1024
	ds_read_b128 v[150:153], v142 offset:2048
	ds_read_b128 v[154:157], v142 offset:3072
	v_add_u32_e32 v142, s56, v144
	ds_read_b128 v[158:161], v142
	ds_read_b128 v[162:165], v142 offset:1024
	ds_read_b128 v[166:169], v142 offset:2048
	ds_read_b128 v[170:173], v142 offset:3072
	v_lshl_add_u64 v[142:143], s[24:25], 0, v[136:137]
	s_add_i32 m0, s39, 0xc000
	ds_read_b128 v[174:177], v145
	ds_read_b128 v[178:181], v145 offset:1024
	ds_read_b128 v[182:185], v145 offset:2048
	ds_read_b128 v[186:189], v145 offset:3072
	ds_read_b128 v[190:193], v145 offset:4096
	ds_read_b128 v[194:197], v145 offset:5120
	ds_read_b128 v[198:201], v145 offset:6144
	ds_read_b128 v[202:205], v145 offset:7168
	global_load_lds_dwordx4 v[142:143], off
	v_lshl_add_u64 v[142:143], s[24:25], 0, v[134:135]
	s_add_i32 m0, s39, 0xe000
	s_nop 0
	global_load_lds_dwordx4 v[142:143], off
	s_waitcnt vmcnt(8) lgkmcnt(0)
	s_barrier
	v_mfma_f32_16x16x32_bf16 v[124:127], v[138:141], v[174:177], 0
	v_mfma_f32_16x16x32_bf16 v[120:123], v[150:153], v[174:177], 0
	v_mfma_f32_16x16x32_bf16 v[108:111], v[138:141], v[182:185], 0
	v_mfma_f32_16x16x32_bf16 v[104:107], v[150:153], v[182:185], 0
	v_mfma_f32_16x16x32_bf16 v[92:95], v[138:141], v[190:193], 0
	v_mfma_f32_16x16x32_bf16 v[88:91], v[150:153], v[190:193], 0
	v_mfma_f32_16x16x32_bf16 v[76:79], v[138:141], v[198:201], 0
	v_mfma_f32_16x16x32_bf16 v[72:75], v[150:153], v[198:201], 0
	v_mfma_f32_16x16x32_bf16 v[124:127], v[146:149], v[178:181], v[124:127]
	v_mfma_f32_16x16x32_bf16 v[120:123], v[154:157], v[178:181], v[120:123]
	v_mfma_f32_16x16x32_bf16 v[108:111], v[146:149], v[186:189], v[108:111]
	v_mfma_f32_16x16x32_bf16 v[104:107], v[154:157], v[186:189], v[104:107]
	v_mfma_f32_16x16x32_bf16 v[92:95], v[146:149], v[194:197], v[92:95]
	v_mfma_f32_16x16x32_bf16 v[88:91], v[154:157], v[194:197], v[88:91]
	v_mfma_f32_16x16x32_bf16 v[76:79], v[146:149], v[202:205], v[76:79]
	v_mfma_f32_16x16x32_bf16 v[72:75], v[154:157], v[202:205], v[72:75]
	v_mfma_f32_16x16x32_bf16 v[116:119], v[158:161], v[174:177], 0
	v_mfma_f32_16x16x32_bf16 v[112:115], v[166:169], v[174:177], 0
	v_mfma_f32_16x16x32_bf16 v[100:103], v[158:161], v[182:185], 0
	v_mfma_f32_16x16x32_bf16 v[96:99], v[166:169], v[182:185], 0
	v_mfma_f32_16x16x32_bf16 v[84:87], v[158:161], v[190:193], 0
	v_mfma_f32_16x16x32_bf16 v[80:83], v[166:169], v[190:193], 0
	v_mfma_f32_16x16x32_bf16 v[68:71], v[158:161], v[198:201], 0
	v_mfma_f32_16x16x32_bf16 v[64:67], v[166:169], v[198:201], 0
	v_mfma_f32_16x16x32_bf16 v[116:119], v[162:165], v[178:181], v[116:119]
	v_mfma_f32_16x16x32_bf16 v[112:115], v[170:173], v[178:181], v[112:115]
	v_mfma_f32_16x16x32_bf16 v[100:103], v[162:165], v[186:189], v[100:103]
	v_mfma_f32_16x16x32_bf16 v[96:99], v[170:173], v[186:189], v[96:99]
	v_mfma_f32_16x16x32_bf16 v[84:87], v[162:165], v[194:197], v[84:87]
	v_mfma_f32_16x16x32_bf16 v[80:83], v[170:173], v[194:197], v[80:83]
	v_mfma_f32_16x16x32_bf16 v[68:71], v[162:165], v[202:205], v[68:71]
	v_mfma_f32_16x16x32_bf16 v[64:67], v[170:173], v[202:205], v[64:67]
	s_barrier
	s_add_i32 s53, s53, s38
	v_lshl_add_u64 v[142:143], s[26:27], 0, v[232:233]
	s_mov_b32 m0, s53
	ds_read_b128 v[174:177], v145 offset:16384
	ds_read_b128 v[178:181], v145 offset:17408
	ds_read_b128 v[182:185], v145 offset:18432
	ds_read_b128 v[186:189], v145 offset:19456
	ds_read_b128 v[190:193], v145 offset:20480
	ds_read_b128 v[194:197], v145 offset:21504
	ds_read_b128 v[198:201], v145 offset:22528
	ds_read_b128 v[202:205], v145 offset:23552
	global_load_lds_dwordx4 v[142:143], off
	s_add_i32 m0, s53, 0x2000
	s_add_u32 s54, s26, 0x40000
	v_lshl_add_u64 v[206:207], s[26:27], 0, v[132:133]
	s_addc_u32 s55, s27, 0
	s_add_i32 s53, s56, s38
	global_load_lds_dwordx4 v[206:207], off
	v_lshl_add_u64 v[208:209], s[54:55], 0, v[232:233]
	s_mov_b32 m0, s53
	v_lshl_add_u64 v[210:211], s[28:29], 0, v[130:131]
	global_load_lds_dwordx4 v[208:209], off
	v_lshl_add_u64 v[208:209], s[54:55], 0, v[132:133]
	s_add_i32 m0, s53, 0x2000
	s_nop 0
	global_load_lds_dwordx4 v[208:209], off
	v_lshl_add_u64 v[208:209], s[28:29], 0, v[128:129]
	s_waitcnt vmcnt(6) lgkmcnt(0)
	s_barrier
	v_mfma_f32_16x16x32_bf16 v[60:63], v[138:141], v[174:177], 0
	v_mfma_f32_16x16x32_bf16 v[56:59], v[150:153], v[174:177], 0
	v_mfma_f32_16x16x32_bf16 v[44:47], v[138:141], v[182:185], 0
	v_mfma_f32_16x16x32_bf16 v[40:43], v[150:153], v[182:185], 0
	v_mfma_f32_16x16x32_bf16 v[28:31], v[138:141], v[190:193], 0
	v_mfma_f32_16x16x32_bf16 v[24:27], v[150:153], v[190:193], 0
	v_mfma_f32_16x16x32_bf16 v[12:15], v[138:141], v[198:201], 0
	v_mfma_f32_16x16x32_bf16 v[8:11], v[150:153], v[198:201], 0
	v_mfma_f32_16x16x32_bf16 v[60:63], v[146:149], v[178:181], v[60:63]
	v_mfma_f32_16x16x32_bf16 v[56:59], v[154:157], v[178:181], v[56:59]
	v_mfma_f32_16x16x32_bf16 v[44:47], v[146:149], v[186:189], v[44:47]
	v_mfma_f32_16x16x32_bf16 v[40:43], v[154:157], v[186:189], v[40:43]
	v_mfma_f32_16x16x32_bf16 v[28:31], v[146:149], v[194:197], v[28:31]
	v_mfma_f32_16x16x32_bf16 v[24:27], v[154:157], v[194:197], v[24:27]
	v_mfma_f32_16x16x32_bf16 v[12:15], v[146:149], v[202:205], v[12:15]
	v_mfma_f32_16x16x32_bf16 v[8:11], v[154:157], v[202:205], v[8:11]
	v_mfma_f32_16x16x32_bf16 v[52:55], v[158:161], v[174:177], 0
	v_mfma_f32_16x16x32_bf16 v[48:51], v[166:169], v[174:177], 0
	v_mfma_f32_16x16x32_bf16 v[36:39], v[158:161], v[182:185], 0
	v_mfma_f32_16x16x32_bf16 v[32:35], v[166:169], v[182:185], 0
	v_mfma_f32_16x16x32_bf16 v[20:23], v[158:161], v[190:193], 0
	v_mfma_f32_16x16x32_bf16 v[16:19], v[166:169], v[190:193], 0
	v_mfma_f32_16x16x32_bf16 v[4:7], v[158:161], v[198:201], 0
	v_mfma_f32_16x16x32_bf16 v[0:3], v[166:169], v[198:201], 0
	v_mfma_f32_16x16x32_bf16 v[52:55], v[162:165], v[178:181], v[52:55]
	v_mfma_f32_16x16x32_bf16 v[48:51], v[170:173], v[178:181], v[48:51]
	v_mfma_f32_16x16x32_bf16 v[36:39], v[162:165], v[186:189], v[36:39]
	v_mfma_f32_16x16x32_bf16 v[32:35], v[170:173], v[186:189], v[32:35]
	v_mfma_f32_16x16x32_bf16 v[20:23], v[162:165], v[194:197], v[20:23]
	v_mfma_f32_16x16x32_bf16 v[16:19], v[170:173], v[194:197], v[16:19]
	v_mfma_f32_16x16x32_bf16 v[4:7], v[162:165], v[202:205], v[4:7]
	v_mfma_f32_16x16x32_bf16 v[0:3], v[170:173], v[202:205], v[0:3]
	s_barrier
	s_branch .Lzmid_4
.LBB0_1307:
	s_add_u32 s26, s24, 0xfffc0080
	s_addc_u32 s27, s25, -1
	s_add_i32 s53, 0, 0x10000
	s_cmp_eq_u32 s52, 12
	s_cselect_b32 s29, s7, s27
	s_cselect_b32 s28, s17, s26
	v_add_u32_e32 v142, s53, v144
	s_cselect_b32 s27, s15, s51
	s_cselect_b32 s26, s23, s50
	s_add_i32 s56, 0, 0x14000
	ds_read_b128 v[138:141], v142
	ds_read_b128 v[146:149], v142 offset:1024
	ds_read_b128 v[150:153], v142 offset:2048
	ds_read_b128 v[154:157], v142 offset:3072
	v_add_u32_e32 v142, s56, v144
	ds_read_b128 v[158:161], v142
	ds_read_b128 v[162:165], v142 offset:1024
	ds_read_b128 v[166:169], v142 offset:2048
	ds_read_b128 v[170:173], v142 offset:3072
	v_lshl_add_u64 v[142:143], s[24:25], 0, v[136:137]
	s_add_i32 m0, s39, 0xc000
	ds_read_b128 v[174:177], v145
	ds_read_b128 v[178:181], v145 offset:1024
	ds_read_b128 v[182:185], v145 offset:2048
	ds_read_b128 v[186:189], v145 offset:3072
	ds_read_b128 v[190:193], v145 offset:4096
	ds_read_b128 v[194:197], v145 offset:5120
	ds_read_b128 v[198:201], v145 offset:6144
	ds_read_b128 v[202:205], v145 offset:7168
	global_load_lds_dwordx4 v[142:143], off
	v_lshl_add_u64 v[142:143], s[24:25], 0, v[134:135]
	s_add_i32 m0, s39, 0xe000
	s_nop 0
	global_load_lds_dwordx4 v[142:143], off
	s_waitcnt vmcnt(8) lgkmcnt(0)
	s_barrier
	v_mfma_f32_16x16x32_bf16 v[124:127], v[138:141], v[174:177], v[124:127]
	v_mfma_f32_16x16x32_bf16 v[120:123], v[150:153], v[174:177], v[120:123]
	v_mfma_f32_16x16x32_bf16 v[108:111], v[138:141], v[182:185], v[108:111]
	v_mfma_f32_16x16x32_bf16 v[104:107], v[150:153], v[182:185], v[104:107]
	v_mfma_f32_16x16x32_bf16 v[92:95], v[138:141], v[190:193], v[92:95]
	v_mfma_f32_16x16x32_bf16 v[88:91], v[150:153], v[190:193], v[88:91]
	v_mfma_f32_16x16x32_bf16 v[76:79], v[138:141], v[198:201], v[76:79]
	v_mfma_f32_16x16x32_bf16 v[72:75], v[150:153], v[198:201], v[72:75]
	v_mfma_f32_16x16x32_bf16 v[124:127], v[146:149], v[178:181], v[124:127]
	v_mfma_f32_16x16x32_bf16 v[120:123], v[154:157], v[178:181], v[120:123]
	v_mfma_f32_16x16x32_bf16 v[108:111], v[146:149], v[186:189], v[108:111]
	v_mfma_f32_16x16x32_bf16 v[104:107], v[154:157], v[186:189], v[104:107]
	v_mfma_f32_16x16x32_bf16 v[92:95], v[146:149], v[194:197], v[92:95]
	v_mfma_f32_16x16x32_bf16 v[88:91], v[154:157], v[194:197], v[88:91]
	v_mfma_f32_16x16x32_bf16 v[76:79], v[146:149], v[202:205], v[76:79]
	v_mfma_f32_16x16x32_bf16 v[72:75], v[154:157], v[202:205], v[72:75]
	v_mfma_f32_16x16x32_bf16 v[116:119], v[158:161], v[174:177], v[116:119]
	v_mfma_f32_16x16x32_bf16 v[112:115], v[166:169], v[174:177], v[112:115]
	v_mfma_f32_16x16x32_bf16 v[100:103], v[158:161], v[182:185], v[100:103]
	v_mfma_f32_16x16x32_bf16 v[96:99], v[166:169], v[182:185], v[96:99]
	v_mfma_f32_16x16x32_bf16 v[84:87], v[158:161], v[190:193], v[84:87]
	v_mfma_f32_16x16x32_bf16 v[80:83], v[166:169], v[190:193], v[80:83]
	v_mfma_f32_16x16x32_bf16 v[68:71], v[158:161], v[198:201], v[68:71]
	v_mfma_f32_16x16x32_bf16 v[64:67], v[166:169], v[198:201], v[64:67]
	v_mfma_f32_16x16x32_bf16 v[116:119], v[162:165], v[178:181], v[116:119]
	v_mfma_f32_16x16x32_bf16 v[112:115], v[170:173], v[178:181], v[112:115]
	v_mfma_f32_16x16x32_bf16 v[100:103], v[162:165], v[186:189], v[100:103]
	v_mfma_f32_16x16x32_bf16 v[96:99], v[170:173], v[186:189], v[96:99]
	v_mfma_f32_16x16x32_bf16 v[84:87], v[162:165], v[194:197], v[84:87]
	v_mfma_f32_16x16x32_bf16 v[80:83], v[170:173], v[194:197], v[80:83]
	v_mfma_f32_16x16x32_bf16 v[68:71], v[162:165], v[202:205], v[68:71]
	v_mfma_f32_16x16x32_bf16 v[64:67], v[170:173], v[202:205], v[64:67]
	s_barrier
	s_add_i32 s53, s53, s38
	v_lshl_add_u64 v[142:143], s[26:27], 0, v[232:233]
	s_mov_b32 m0, s53
	ds_read_b128 v[174:177], v145 offset:16384
	ds_read_b128 v[178:181], v145 offset:17408
	ds_read_b128 v[182:185], v145 offset:18432
	ds_read_b128 v[186:189], v145 offset:19456
	ds_read_b128 v[190:193], v145 offset:20480
	ds_read_b128 v[194:197], v145 offset:21504
	ds_read_b128 v[198:201], v145 offset:22528
	ds_read_b128 v[202:205], v145 offset:23552
	global_load_lds_dwordx4 v[142:143], off
	s_add_i32 m0, s53, 0x2000
	s_add_u32 s54, s26, 0x40000
	v_lshl_add_u64 v[206:207], s[26:27], 0, v[132:133]
	s_addc_u32 s55, s27, 0
	s_add_i32 s53, s56, s38
	global_load_lds_dwordx4 v[206:207], off
	v_lshl_add_u64 v[208:209], s[54:55], 0, v[232:233]
	s_mov_b32 m0, s53
	v_lshl_add_u64 v[210:211], s[28:29], 0, v[130:131]
	global_load_lds_dwordx4 v[208:209], off
	v_lshl_add_u64 v[208:209], s[54:55], 0, v[132:133]
	s_add_i32 m0, s53, 0x2000
	s_nop 0
	global_load_lds_dwordx4 v[208:209], off
	v_lshl_add_u64 v[208:209], s[28:29], 0, v[128:129]
	s_waitcnt vmcnt(6) lgkmcnt(0)
	s_barrier
	v_mfma_f32_16x16x32_bf16 v[60:63], v[138:141], v[174:177], v[60:63]
	v_mfma_f32_16x16x32_bf16 v[56:59], v[150:153], v[174:177], v[56:59]
	v_mfma_f32_16x16x32_bf16 v[44:47], v[138:141], v[182:185], v[44:47]
	v_mfma_f32_16x16x32_bf16 v[40:43], v[150:153], v[182:185], v[40:43]
	v_mfma_f32_16x16x32_bf16 v[28:31], v[138:141], v[190:193], v[28:31]
	v_mfma_f32_16x16x32_bf16 v[24:27], v[150:153], v[190:193], v[24:27]
	v_mfma_f32_16x16x32_bf16 v[12:15], v[138:141], v[198:201], v[12:15]
	v_mfma_f32_16x16x32_bf16 v[8:11], v[150:153], v[198:201], v[8:11]
	v_mfma_f32_16x16x32_bf16 v[60:63], v[146:149], v[178:181], v[60:63]
	v_mfma_f32_16x16x32_bf16 v[56:59], v[154:157], v[178:181], v[56:59]
	v_mfma_f32_16x16x32_bf16 v[44:47], v[146:149], v[186:189], v[44:47]
	v_mfma_f32_16x16x32_bf16 v[40:43], v[154:157], v[186:189], v[40:43]
	v_mfma_f32_16x16x32_bf16 v[28:31], v[146:149], v[194:197], v[28:31]
	v_mfma_f32_16x16x32_bf16 v[24:27], v[154:157], v[194:197], v[24:27]
	v_mfma_f32_16x16x32_bf16 v[12:15], v[146:149], v[202:205], v[12:15]
	v_mfma_f32_16x16x32_bf16 v[8:11], v[154:157], v[202:205], v[8:11]
	v_mfma_f32_16x16x32_bf16 v[52:55], v[158:161], v[174:177], v[52:55]
	v_mfma_f32_16x16x32_bf16 v[48:51], v[166:169], v[174:177], v[48:51]
	v_mfma_f32_16x16x32_bf16 v[36:39], v[158:161], v[182:185], v[36:39]
	v_mfma_f32_16x16x32_bf16 v[32:35], v[166:169], v[182:185], v[32:35]
	v_mfma_f32_16x16x32_bf16 v[20:23], v[158:161], v[190:193], v[20:23]
	v_mfma_f32_16x16x32_bf16 v[16:19], v[166:169], v[190:193], v[16:19]
	v_mfma_f32_16x16x32_bf16 v[4:7], v[158:161], v[198:201], v[4:7]
	v_mfma_f32_16x16x32_bf16 v[0:3], v[166:169], v[198:201], v[0:3]
	v_mfma_f32_16x16x32_bf16 v[52:55], v[162:165], v[178:181], v[52:55]
	v_mfma_f32_16x16x32_bf16 v[48:51], v[170:173], v[178:181], v[48:51]
	v_mfma_f32_16x16x32_bf16 v[36:39], v[162:165], v[186:189], v[36:39]
	v_mfma_f32_16x16x32_bf16 v[32:35], v[170:173], v[186:189], v[32:35]
	v_mfma_f32_16x16x32_bf16 v[20:23], v[162:165], v[194:197], v[20:23]
	v_mfma_f32_16x16x32_bf16 v[16:19], v[170:173], v[194:197], v[16:19]
	v_mfma_f32_16x16x32_bf16 v[4:7], v[162:165], v[202:205], v[4:7]
	v_mfma_f32_16x16x32_bf16 v[0:3], v[170:173], v[202:205], v[0:3]
	s_barrier
.Lzmid_4:
	s_add_i32 s53, 0, 0x18000
	s_add_i32 s54, 0, 0x1c000
	v_add_u32_e32 v154, s53, v144
	v_add_u32_e32 v170, s54, v144
	ds_read_b128 v[138:141], v154
	ds_read_b128 v[146:149], v154 offset:1024
	ds_read_b128 v[150:153], v154 offset:2048
	ds_read_b128 v[154:157], v154 offset:3072
	ds_read_b128 v[158:161], v170
	ds_read_b128 v[162:165], v170 offset:1024
	ds_read_b128 v[166:169], v170 offset:2048
	ds_read_b128 v[170:173], v170 offset:3072
	s_add_u32 s28, s28, 0x40000
	s_addc_u32 s29, s29, 0
	s_mov_b32 m0, s39
	s_nop 0
	global_load_lds_dwordx4 v[208:209], off
	s_mov_b32 m0, s40
	s_nop 0
	global_load_lds_dwordx4 v[210:211], off
	s_mov_b32 m0, s41
	v_lshl_add_u64 v[212:213], s[28:29], 0, v[128:129]
	ds_read_b128 v[174:177], v145 offset:32768
	ds_read_b128 v[178:181], v145 offset:33792
	ds_read_b128 v[182:185], v145 offset:34816
	ds_read_b128 v[186:189], v145 offset:35840
	ds_read_b128 v[190:193], v145 offset:36864
	ds_read_b128 v[194:197], v145 offset:37888
	ds_read_b128 v[198:201], v145 offset:38912
	ds_read_b128 v[202:205], v145 offset:39936
	global_load_lds_dwordx4 v[212:213], off
	v_lshl_add_u64 v[212:213], s[28:29], 0, v[130:131]
	s_mov_b32 m0, s42
	s_nop 0
	global_load_lds_dwordx4 v[212:213], off
	s_waitcnt vmcnt(8) lgkmcnt(0)
	s_barrier
	v_mfma_f32_16x16x32_bf16 v[124:127], v[138:141], v[174:177], v[124:127]
	v_mfma_f32_16x16x32_bf16 v[120:123], v[150:153], v[174:177], v[120:123]
	v_mfma_f32_16x16x32_bf16 v[108:111], v[138:141], v[182:185], v[108:111]
	v_mfma_f32_16x16x32_bf16 v[104:107], v[150:153], v[182:185], v[104:107]
	v_mfma_f32_16x16x32_bf16 v[92:95], v[138:141], v[190:193], v[92:95]
	v_mfma_f32_16x16x32_bf16 v[88:91], v[150:153], v[190:193], v[88:91]
	v_mfma_f32_16x16x32_bf16 v[76:79], v[138:141], v[198:201], v[76:79]
	v_mfma_f32_16x16x32_bf16 v[72:75], v[150:153], v[198:201], v[72:75]
	v_mfma_f32_16x16x32_bf16 v[124:127], v[146:149], v[178:181], v[124:127]
	v_mfma_f32_16x16x32_bf16 v[120:123], v[154:157], v[178:181], v[120:123]
	v_mfma_f32_16x16x32_bf16 v[108:111], v[146:149], v[186:189], v[108:111]
	v_mfma_f32_16x16x32_bf16 v[104:107], v[154:157], v[186:189], v[104:107]
	v_mfma_f32_16x16x32_bf16 v[92:95], v[146:149], v[194:197], v[92:95]
	v_mfma_f32_16x16x32_bf16 v[88:91], v[154:157], v[194:197], v[88:91]
	v_mfma_f32_16x16x32_bf16 v[76:79], v[146:149], v[202:205], v[76:79]
	v_mfma_f32_16x16x32_bf16 v[72:75], v[154:157], v[202:205], v[72:75]
	v_mfma_f32_16x16x32_bf16 v[116:119], v[158:161], v[174:177], v[116:119]
	v_mfma_f32_16x16x32_bf16 v[112:115], v[166:169], v[174:177], v[112:115]
	v_mfma_f32_16x16x32_bf16 v[100:103], v[158:161], v[182:185], v[100:103]
	v_mfma_f32_16x16x32_bf16 v[96:99], v[166:169], v[182:185], v[96:99]
	v_mfma_f32_16x16x32_bf16 v[84:87], v[158:161], v[190:193], v[84:87]
	v_mfma_f32_16x16x32_bf16 v[80:83], v[166:169], v[190:193], v[80:83]
	v_mfma_f32_16x16x32_bf16 v[68:71], v[158:161], v[198:201], v[68:71]
	v_mfma_f32_16x16x32_bf16 v[64:67], v[166:169], v[198:201], v[64:67]
	v_mfma_f32_16x16x32_bf16 v[116:119], v[162:165], v[178:181], v[116:119]
	v_mfma_f32_16x16x32_bf16 v[112:115], v[170:173], v[178:181], v[112:115]
	v_mfma_f32_16x16x32_bf16 v[100:103], v[162:165], v[186:189], v[100:103]
	v_mfma_f32_16x16x32_bf16 v[96:99], v[170:173], v[186:189], v[96:99]
	v_mfma_f32_16x16x32_bf16 v[84:87], v[162:165], v[194:197], v[84:87]
	v_mfma_f32_16x16x32_bf16 v[80:83], v[170:173], v[194:197], v[80:83]
	v_mfma_f32_16x16x32_bf16 v[68:71], v[162:165], v[202:205], v[68:71]
	v_mfma_f32_16x16x32_bf16 v[64:67], v[170:173], v[202:205], v[64:67]
	s_barrier
	s_add_i32 s28, s53, s38
	v_lshl_add_u64 v[142:143], v[142:143], 0, s[94:95]
	s_mov_b32 m0, s28
	ds_read_b128 v[174:177], v145 offset:49152
	ds_read_b128 v[178:181], v145 offset:50176
	ds_read_b128 v[182:185], v145 offset:51200
	ds_read_b128 v[186:189], v145 offset:52224
	ds_read_b128 v[190:193], v145 offset:53248
	ds_read_b128 v[194:197], v145 offset:54272
	ds_read_b128 v[198:201], v145 offset:55296
	ds_read_b128 v[202:205], v145 offset:56320
	global_load_lds_dwordx4 v[142:143], off
	s_add_i32 m0, s28, 0x2000
	s_add_u32 s26, s26, 0x40080
	v_lshl_add_u64 v[142:143], v[206:207], 0, s[94:95]
	s_addc_u32 s27, s27, 0
	s_add_i32 s28, s54, s38
	global_load_lds_dwordx4 v[142:143], off
	v_lshl_add_u64 v[142:143], s[26:27], 0, v[232:233]
	s_mov_b32 m0, s28
	s_nop 0
	global_load_lds_dwordx4 v[142:143], off
	v_lshl_add_u64 v[142:143], s[26:27], 0, v[132:133]
	s_add_i32 m0, s28, 0x2000
	s_nop 0
	global_load_lds_dwordx4 v[142:143], off
	v_lshl_add_u64 v[142:143], v[208:209], 0, s[94:95]
	s_mov_b32 m0, s45
	s_nop 0
	global_load_lds_dwordx4 v[142:143], off
	v_lshl_add_u64 v[142:143], v[210:211], 0, s[94:95]
	s_mov_b32 m0, s46
	s_nop 0
	global_load_lds_dwordx4 v[142:143], off
	s_waitcnt vmcnt(8) lgkmcnt(0)
	s_barrier
	v_mfma_f32_16x16x32_bf16 v[60:63], v[138:141], v[174:177], v[60:63]
	v_mfma_f32_16x16x32_bf16 v[56:59], v[150:153], v[174:177], v[56:59]
	v_mfma_f32_16x16x32_bf16 v[44:47], v[138:141], v[182:185], v[44:47]
	v_mfma_f32_16x16x32_bf16 v[40:43], v[150:153], v[182:185], v[40:43]
	v_mfma_f32_16x16x32_bf16 v[28:31], v[138:141], v[190:193], v[28:31]
	v_mfma_f32_16x16x32_bf16 v[24:27], v[150:153], v[190:193], v[24:27]
	v_mfma_f32_16x16x32_bf16 v[12:15], v[138:141], v[198:201], v[12:15]
	v_mfma_f32_16x16x32_bf16 v[8:11], v[150:153], v[198:201], v[8:11]
	v_mfma_f32_16x16x32_bf16 v[60:63], v[146:149], v[178:181], v[60:63]
	v_mfma_f32_16x16x32_bf16 v[56:59], v[154:157], v[178:181], v[56:59]
	v_mfma_f32_16x16x32_bf16 v[44:47], v[146:149], v[186:189], v[44:47]
	v_mfma_f32_16x16x32_bf16 v[40:43], v[154:157], v[186:189], v[40:43]
	v_mfma_f32_16x16x32_bf16 v[28:31], v[146:149], v[194:197], v[28:31]
	v_mfma_f32_16x16x32_bf16 v[24:27], v[154:157], v[194:197], v[24:27]
	v_mfma_f32_16x16x32_bf16 v[12:15], v[146:149], v[202:205], v[12:15]
	v_mfma_f32_16x16x32_bf16 v[8:11], v[154:157], v[202:205], v[8:11]
	v_mfma_f32_16x16x32_bf16 v[52:55], v[158:161], v[174:177], v[52:55]
	v_mfma_f32_16x16x32_bf16 v[48:51], v[166:169], v[174:177], v[48:51]
	v_mfma_f32_16x16x32_bf16 v[36:39], v[158:161], v[182:185], v[36:39]
	v_mfma_f32_16x16x32_bf16 v[32:35], v[166:169], v[182:185], v[32:35]
	v_mfma_f32_16x16x32_bf16 v[20:23], v[158:161], v[190:193], v[20:23]
	v_mfma_f32_16x16x32_bf16 v[16:19], v[166:169], v[190:193], v[16:19]
	v_mfma_f32_16x16x32_bf16 v[4:7], v[158:161], v[198:201], v[4:7]
	v_mfma_f32_16x16x32_bf16 v[0:3], v[166:169], v[198:201], v[0:3]
	v_mfma_f32_16x16x32_bf16 v[52:55], v[162:165], v[178:181], v[52:55]
	v_mfma_f32_16x16x32_bf16 v[48:51], v[170:173], v[178:181], v[48:51]
	v_mfma_f32_16x16x32_bf16 v[36:39], v[162:165], v[186:189], v[36:39]
	v_mfma_f32_16x16x32_bf16 v[32:35], v[170:173], v[186:189], v[32:35]
	v_mfma_f32_16x16x32_bf16 v[20:23], v[162:165], v[194:197], v[20:23]
	v_mfma_f32_16x16x32_bf16 v[16:19], v[170:173], v[194:197], v[16:19]
	v_mfma_f32_16x16x32_bf16 v[4:7], v[162:165], v[202:205], v[4:7]
	v_mfma_f32_16x16x32_bf16 v[0:3], v[170:173], v[202:205], v[0:3]
	s_barrier
	s_add_i32 s52, s52, 2
	s_add_u32 s50, s50, 0x100
	s_addc_u32 s51, s51, 0
	s_add_u32 s24, s24, 0x100
	s_addc_u32 s25, s25, 0
	s_cmp_gt_u32 s52, 13
	s_cbranch_scc0 .LBB0_1307
	s_and_b64 vcc, exec, s[12:13]
	s_cbranch_vccz .LBB0_1310
	s_barrier

.LBB0_1420:
	s_ashr_i32 s17, s16, 31
	s_lshl_b64 s[18:19], s[16:17], 17
	s_add_u32 s18, s35, s18
	s_addc_u32 s19, s36, s19
	s_and_b64 s[20:21], s[4:5], exec
	s_cselect_b32 s31, s19, s25
	s_cselect_b32 s30, s18, s24
	s_ashr_i32 s15, s14, 31
	s_lshl_b64 s[20:21], s[14:15], 17
	s_add_u32 s20, s37, s20
	s_addc_u32 s21, s38, s21
	s_and_b64 s[28:29], s[4:5], exec
	s_cselect_b32 s29, s21, s27
	s_cselect_b32 s28, s20, s26
	s_add_i32 s17, 0, 0x10000
	s_add_i32 s49, 0, 0x14000
	v_add_u32_e32 v210, s17, v164
	v_add_u32_e32 v211, s49, v164
	ds_read_b128 v[0:3], v210
	ds_read_b128 v[4:7], v210 offset:1024
	ds_read_b128 v[8:11], v210 offset:2048
	ds_read_b128 v[12:15], v210 offset:3072
	ds_read_b128 v[16:19], v211
	ds_read_b128 v[20:23], v211 offset:1024
	ds_read_b128 v[24:27], v211 offset:2048
	ds_read_b128 v[28:31], v211 offset:3072
	v_mov_b64_e32 v[246:247], 0xff
	v_mov_b32_e32 v250, 0x3727c5ac
	s_add_u32 s50, s24, 0x10080
	s_addc_u32 s51, s25, 0
	s_add_i32 s53, s40, 0xc000
	s_waitcnt vmcnt(0)
	v_lshl_add_u64 v[64:65], s[50:51], 0, v[148:149]
	s_mov_b32 m0, s53
	s_add_i32 s15, s40, 0xe000
	ds_read_b128 v[32:35], v165
	ds_read_b128 v[36:39], v165 offset:1024
	ds_read_b128 v[40:43], v165 offset:2048
	ds_read_b128 v[44:47], v165 offset:3072
	ds_read_b128 v[48:51], v165 offset:4096
	ds_read_b128 v[52:55], v165 offset:5120
	ds_read_b128 v[56:59], v165 offset:6144
	ds_read_b128 v[60:63], v165 offset:7168
	global_load_lds_dwordx4 v[64:65], off
	v_lshl_add_u64 v[64:65], s[50:51], 0, v[150:151]
	s_mov_b32 m0, s15
	s_nop 0
	global_load_lds_dwordx4 v[64:65], off
	s_waitcnt vmcnt(8) lgkmcnt(0)
	s_barrier
	v_mfma_f32_16x16x32_bf16 v[64:67], v[0:3], v[32:35], 0
	v_mfma_f32_16x16x32_bf16 v[68:71], v[8:11], v[32:35], 0
	v_mfma_f32_16x16x32_bf16 v[72:75], v[0:3], v[40:43], 0
	v_mfma_f32_16x16x32_bf16 v[76:79], v[8:11], v[40:43], 0
	v_mfma_f32_16x16x32_bf16 v[80:83], v[0:3], v[48:51], 0
	v_mfma_f32_16x16x32_bf16 v[84:87], v[8:11], v[48:51], 0
	v_mfma_f32_16x16x32_bf16 v[88:91], v[0:3], v[56:59], 0
	v_mfma_f32_16x16x32_bf16 v[92:95], v[8:11], v[56:59], 0
	v_mfma_f32_16x16x32_bf16 v[64:67], v[4:7], v[36:39], v[64:67]
	v_mfma_f32_16x16x32_bf16 v[68:71], v[12:15], v[36:39], v[68:71]
	v_mfma_f32_16x16x32_bf16 v[72:75], v[4:7], v[44:47], v[72:75]
	v_mfma_f32_16x16x32_bf16 v[76:79], v[12:15], v[44:47], v[76:79]
	v_mfma_f32_16x16x32_bf16 v[80:83], v[4:7], v[52:55], v[80:83]
	v_mfma_f32_16x16x32_bf16 v[84:87], v[12:15], v[52:55], v[84:87]
	v_mfma_f32_16x16x32_bf16 v[88:91], v[4:7], v[60:63], v[88:91]
	v_mfma_f32_16x16x32_bf16 v[92:95], v[12:15], v[60:63], v[92:95]
	v_mfma_f32_16x16x32_bf16 v[96:99], v[16:19], v[32:35], 0
	v_mfma_f32_16x16x32_bf16 v[32:35], v[24:27], v[32:35], 0
	v_mfma_f32_16x16x32_bf16 v[96:99], v[20:23], v[36:39], v[96:99]
	v_mfma_f32_16x16x32_bf16 v[32:35], v[28:31], v[36:39], v[32:35]
	v_mfma_f32_16x16x32_bf16 v[36:39], v[16:19], v[40:43], 0
	v_mfma_f32_16x16x32_bf16 v[40:43], v[24:27], v[40:43], 0
	v_mfma_f32_16x16x32_bf16 v[36:39], v[20:23], v[44:47], v[36:39]
	v_mfma_f32_16x16x32_bf16 v[40:43], v[28:31], v[44:47], v[40:43]
	v_mfma_f32_16x16x32_bf16 v[44:47], v[16:19], v[48:51], 0
	v_mfma_f32_16x16x32_bf16 v[48:51], v[24:27], v[48:51], 0
	v_mfma_f32_16x16x32_bf16 v[44:47], v[20:23], v[52:55], v[44:47]
	v_mfma_f32_16x16x32_bf16 v[48:51], v[28:31], v[52:55], v[48:51]
	v_mfma_f32_16x16x32_bf16 v[52:55], v[16:19], v[56:59], 0
	v_mfma_f32_16x16x32_bf16 v[56:59], v[24:27], v[56:59], 0
	v_mfma_f32_16x16x32_bf16 v[52:55], v[20:23], v[60:63], v[52:55]
	v_mfma_f32_16x16x32_bf16 v[56:59], v[28:31], v[60:63], v[56:59]
	s_barrier
	s_add_i32 s51, s17, s39
	v_lshl_add_u64 v[162:163], s[26:27], 0, v[232:233]
	s_mov_b64 s[56:57], 0x100
	s_add_i32 s17, s51, 0x2000
	v_lshl_add_u64 v[128:129], v[162:163], 0, s[56:57]
	s_mov_b32 m0, s51
	v_lshl_add_u64 v[202:203], s[26:27], 0, v[152:153]
	s_add_u32 s54, s26, 0x10100
	ds_read_b128 v[60:63], v165 offset:16384
	ds_read_b128 v[100:103], v165 offset:17408
	ds_read_b128 v[104:107], v165 offset:18432
	ds_read_b128 v[108:111], v165 offset:19456
	ds_read_b128 v[112:115], v165 offset:20480
	ds_read_b128 v[116:119], v165 offset:21504
	ds_read_b128 v[120:123], v165 offset:22528
	ds_read_b128 v[124:127], v165 offset:23552
	global_load_lds_dwordx4 v[128:129], off
	v_lshl_add_u64 v[128:129], v[202:203], 0, s[56:57]
	s_mov_b32 m0, s17
	s_addc_u32 s55, s27, 0
	s_add_i32 s49, s49, s39
	global_load_lds_dwordx4 v[128:129], off
	v_lshl_add_u64 v[128:129], s[54:55], 0, v[232:233]
	s_mov_b32 m0, s49
	s_add_i32 s50, s49, 0x2000
	global_load_lds_dwordx4 v[128:129], off
	v_lshl_add_u64 v[128:129], s[54:55], 0, v[152:153]
	s_mov_b32 m0, s50
	v_lshl_add_u64 v[204:205], s[24:25], 0, v[148:149]
	global_load_lds_dwordx4 v[128:129], off
	v_lshl_add_u64 v[128:129], v[204:205], 0, s[56:57]
	s_mov_b32 m0, s40
	v_lshl_add_u64 v[206:207], s[24:25], 0, v[150:151]
	global_load_lds_dwordx4 v[128:129], off
	v_lshl_add_u64 v[128:129], v[206:207], 0, s[56:57]
	s_mov_b32 m0, s41
	s_nop 0
	global_load_lds_dwordx4 v[128:129], off
	s_waitcnt vmcnt(8) lgkmcnt(0)
	s_barrier
	v_mfma_f32_16x16x32_bf16 v[128:131], v[0:3], v[60:63], 0
	v_mfma_f32_16x16x32_bf16 v[136:139], v[0:3], v[104:107], 0
	v_mfma_f32_16x16x32_bf16 v[144:147], v[0:3], v[112:115], 0
	v_mfma_f32_16x16x32_bf16 v[0:3], v[0:3], v[120:123], 0
	v_mfma_f32_16x16x32_bf16 v[128:131], v[4:7], v[100:103], v[128:131]
	v_mfma_f32_16x16x32_bf16 v[132:135], v[8:11], v[60:63], 0
	v_mfma_f32_16x16x32_bf16 v[136:139], v[4:7], v[108:111], v[136:139]
	v_mfma_f32_16x16x32_bf16 v[140:143], v[8:11], v[104:107], 0
	v_mfma_f32_16x16x32_bf16 v[144:147], v[4:7], v[116:119], v[144:147]
	v_mfma_f32_16x16x32_bf16 v[0:3], v[4:7], v[124:127], v[0:3]
	v_mfma_f32_16x16x32_bf16 v[4:7], v[8:11], v[120:123], 0
	v_mfma_f32_16x16x32_bf16 v[132:135], v[12:15], v[100:103], v[132:135]
	v_mfma_f32_16x16x32_bf16 v[140:143], v[12:15], v[108:111], v[140:143]
	v_mfma_f32_16x16x32_bf16 v[154:157], v[8:11], v[112:115], 0
	v_mfma_f32_16x16x32_bf16 v[4:7], v[12:15], v[124:127], v[4:7]
	v_mfma_f32_16x16x32_bf16 v[154:157], v[12:15], v[116:119], v[154:157]
	v_mfma_f32_16x16x32_bf16 v[8:11], v[16:19], v[60:63], 0
	v_mfma_f32_16x16x32_bf16 v[12:15], v[24:27], v[60:63], 0
	v_mfma_f32_16x16x32_bf16 v[8:11], v[20:23], v[100:103], v[8:11]
	v_mfma_f32_16x16x32_bf16 v[12:15], v[28:31], v[100:103], v[12:15]
	v_mfma_f32_16x16x32_bf16 v[60:63], v[16:19], v[104:107], 0
	v_mfma_f32_16x16x32_bf16 v[100:103], v[24:27], v[104:107], 0
	v_mfma_f32_16x16x32_bf16 v[104:107], v[16:19], v[112:115], 0
	v_mfma_f32_16x16x32_bf16 v[16:19], v[16:19], v[120:123], 0
	v_mfma_f32_16x16x32_bf16 v[60:63], v[20:23], v[108:111], v[60:63]
	v_mfma_f32_16x16x32_bf16 v[104:107], v[20:23], v[116:119], v[104:107]
	v_mfma_f32_16x16x32_bf16 v[16:19], v[20:23], v[124:127], v[16:19]
	v_mfma_f32_16x16x32_bf16 v[20:23], v[24:27], v[120:123], 0
	v_mfma_f32_16x16x32_bf16 v[100:103], v[28:31], v[108:111], v[100:103]
	v_mfma_f32_16x16x32_bf16 v[108:111], v[24:27], v[112:115], 0
	v_mfma_f32_16x16x32_bf16 v[20:23], v[28:31], v[124:127], v[20:23]
	v_mfma_f32_16x16x32_bf16 v[108:111], v[28:31], v[116:119], v[108:111]
	s_barrier
	s_add_i32 s52, 0, 0x18000
	s_add_i32 s58, 0, 0x1c000
	v_add_u32_e32 v222, s52, v164
	v_add_u32_e32 v223, s58, v164
	ds_read_b128 v[24:27], v222
	ds_read_b128 v[28:31], v222 offset:1024
	ds_read_b128 v[112:115], v222 offset:2048
	ds_read_b128 v[116:119], v222 offset:3072
	ds_read_b128 v[120:123], v223
	ds_read_b128 v[124:127], v223 offset:1024
	ds_read_b128 v[158:161], v223 offset:2048
	ds_read_b128 v[166:169], v223 offset:3072
	s_add_u32 s54, s24, 0x10100
	s_addc_u32 s55, s25, 0
	s_mov_b32 m0, s42
	v_lshl_add_u64 v[208:209], s[54:55], 0, v[148:149]
	ds_read_b128 v[170:173], v165 offset:32768
	ds_read_b128 v[174:177], v165 offset:33792
	ds_read_b128 v[178:181], v165 offset:34816
	ds_read_b128 v[182:185], v165 offset:35840
	ds_read_b128 v[186:189], v165 offset:36864
	ds_read_b128 v[190:193], v165 offset:37888
	ds_read_b128 v[194:197], v165 offset:38912
	ds_read_b128 v[198:201], v165 offset:39936
	global_load_lds_dwordx4 v[208:209], off
	v_lshl_add_u64 v[208:209], s[54:55], 0, v[150:151]
	s_mov_b32 m0, s43
	s_nop 0
	global_load_lds_dwordx4 v[208:209], off
	s_waitcnt vmcnt(8) lgkmcnt(0)
	s_barrier
	v_mfma_f32_16x16x32_bf16 v[64:67], v[24:27], v[170:173], v[64:67]
	v_mfma_f32_16x16x32_bf16 v[68:71], v[112:115], v[170:173], v[68:71]
	v_mfma_f32_16x16x32_bf16 v[72:75], v[24:27], v[178:181], v[72:75]
	v_mfma_f32_16x16x32_bf16 v[76:79], v[112:115], v[178:181], v[76:79]
	v_mfma_f32_16x16x32_bf16 v[80:83], v[24:27], v[186:189], v[80:83]
	v_mfma_f32_16x16x32_bf16 v[84:87], v[112:115], v[186:189], v[84:87]
	v_mfma_f32_16x16x32_bf16 v[88:91], v[24:27], v[194:197], v[88:91]
	v_mfma_f32_16x16x32_bf16 v[92:95], v[112:115], v[194:197], v[92:95]
	v_mfma_f32_16x16x32_bf16 v[64:67], v[28:31], v[174:177], v[64:67]
	v_mfma_f32_16x16x32_bf16 v[68:71], v[116:119], v[174:177], v[68:71]
	v_mfma_f32_16x16x32_bf16 v[72:75], v[28:31], v[182:185], v[72:75]
	v_mfma_f32_16x16x32_bf16 v[76:79], v[116:119], v[182:185], v[76:79]
	v_mfma_f32_16x16x32_bf16 v[80:83], v[28:31], v[190:193], v[80:83]
	v_mfma_f32_16x16x32_bf16 v[84:87], v[116:119], v[190:193], v[84:87]
	v_mfma_f32_16x16x32_bf16 v[88:91], v[28:31], v[198:201], v[88:91]
	v_mfma_f32_16x16x32_bf16 v[92:95], v[116:119], v[198:201], v[92:95]
	v_mfma_f32_16x16x32_bf16 v[96:99], v[120:123], v[170:173], v[96:99]
	v_mfma_f32_16x16x32_bf16 v[32:35], v[158:161], v[170:173], v[32:35]
	v_mfma_f32_16x16x32_bf16 v[36:39], v[120:123], v[178:181], v[36:39]
	v_mfma_f32_16x16x32_bf16 v[40:43], v[158:161], v[178:181], v[40:43]
	v_mfma_f32_16x16x32_bf16 v[44:47], v[120:123], v[186:189], v[44:47]
	v_mfma_f32_16x16x32_bf16 v[48:51], v[158:161], v[186:189], v[48:51]
	v_mfma_f32_16x16x32_bf16 v[52:55], v[120:123], v[194:197], v[52:55]
	v_mfma_f32_16x16x32_bf16 v[56:59], v[158:161], v[194:197], v[56:59]
	v_mfma_f32_16x16x32_bf16 v[96:99], v[124:127], v[174:177], v[96:99]
	v_mfma_f32_16x16x32_bf16 v[32:35], v[166:169], v[174:177], v[32:35]
	v_mfma_f32_16x16x32_bf16 v[36:39], v[124:127], v[182:185], v[36:39]
	v_mfma_f32_16x16x32_bf16 v[40:43], v[166:169], v[182:185], v[40:43]
	v_mfma_f32_16x16x32_bf16 v[44:47], v[124:127], v[190:193], v[44:47]
	v_mfma_f32_16x16x32_bf16 v[48:51], v[166:169], v[190:193], v[48:51]
	v_mfma_f32_16x16x32_bf16 v[52:55], v[124:127], v[198:201], v[52:55]
	v_mfma_f32_16x16x32_bf16 v[56:59], v[166:169], v[198:201], v[56:59]
	s_barrier
	s_add_i32 s54, s52, s39
	s_mov_b64 s[60:61], 0x180
	s_add_i32 s52, s54, 0x2000
	v_lshl_add_u64 v[162:163], v[162:163], 0, s[60:61]
	s_mov_b32 m0, s54
	s_add_u32 s56, s26, 0x10180
	ds_read_b128 v[170:173], v165 offset:49152
	ds_read_b128 v[174:177], v165 offset:50176
	ds_read_b128 v[178:181], v165 offset:51200
	ds_read_b128 v[182:185], v165 offset:52224
	ds_read_b128 v[186:189], v165 offset:53248
	ds_read_b128 v[190:193], v165 offset:54272
	ds_read_b128 v[194:197], v165 offset:55296
	ds_read_b128 v[198:201], v165 offset:56320
	global_load_lds_dwordx4 v[162:163], off
	v_lshl_add_u64 v[162:163], v[202:203], 0, s[60:61]
	s_mov_b32 m0, s52
	s_addc_u32 s57, s27, 0
	s_add_i32 s26, s58, s39
	global_load_lds_dwordx4 v[162:163], off
	v_lshl_add_u64 v[162:163], s[56:57], 0, v[232:233]
	s_mov_b32 m0, s26
	s_add_i32 s27, s26, 0x2000
	global_load_lds_dwordx4 v[162:163], off
	v_lshl_add_u64 v[162:163], s[56:57], 0, v[152:153]
	s_mov_b32 m0, s27
	s_nop 0
	global_load_lds_dwordx4 v[162:163], off
	v_lshl_add_u64 v[162:163], v[204:205], 0, s[60:61]
	s_mov_b32 m0, s46
	s_nop 0
	global_load_lds_dwordx4 v[162:163], off
	v_lshl_add_u64 v[162:163], v[206:207], 0, s[60:61]
	s_mov_b32 m0, s47
	s_nop 0
	global_load_lds_dwordx4 v[162:163], off
	s_waitcnt vmcnt(8) lgkmcnt(0)
	s_barrier
	v_mfma_f32_16x16x32_bf16 v[128:131], v[24:27], v[170:173], v[128:131]
	v_mfma_f32_16x16x32_bf16 v[132:135], v[112:115], v[170:173], v[132:135]
	v_mfma_f32_16x16x32_bf16 v[136:139], v[24:27], v[178:181], v[136:139]
	v_mfma_f32_16x16x32_bf16 v[140:143], v[112:115], v[178:181], v[140:143]
	v_mfma_f32_16x16x32_bf16 v[144:147], v[24:27], v[186:189], v[144:147]
	v_mfma_f32_16x16x32_bf16 v[0:3], v[24:27], v[194:197], v[0:3]
	v_mfma_f32_16x16x32_bf16 v[4:7], v[112:115], v[194:197], v[4:7]
	v_mfma_f32_16x16x32_bf16 v[128:131], v[28:31], v[174:177], v[128:131]
	v_mfma_f32_16x16x32_bf16 v[132:135], v[116:119], v[174:177], v[132:135]
	v_mfma_f32_16x16x32_bf16 v[136:139], v[28:31], v[182:185], v[136:139]
	v_mfma_f32_16x16x32_bf16 v[140:143], v[116:119], v[182:185], v[140:143]
	v_mfma_f32_16x16x32_bf16 v[144:147], v[28:31], v[190:193], v[144:147]
	v_mfma_f32_16x16x32_bf16 v[154:157], v[112:115], v[186:189], v[154:157]
	v_mfma_f32_16x16x32_bf16 v[0:3], v[28:31], v[198:201], v[0:3]
	v_mfma_f32_16x16x32_bf16 v[4:7], v[116:119], v[198:201], v[4:7]
	v_mfma_f32_16x16x32_bf16 v[154:157], v[116:119], v[190:193], v[154:157]
	v_mfma_f32_16x16x32_bf16 v[8:11], v[120:123], v[170:173], v[8:11]
	v_mfma_f32_16x16x32_bf16 v[12:15], v[158:161], v[170:173], v[12:15]
	v_mfma_f32_16x16x32_bf16 v[24:27], v[120:123], v[178:181], v[60:63]
	v_mfma_f32_16x16x32_bf16 v[28:31], v[158:161], v[178:181], v[100:103]
	v_mfma_f32_16x16x32_bf16 v[60:63], v[120:123], v[186:189], v[104:107]
	v_mfma_f32_16x16x32_bf16 v[100:103], v[158:161], v[186:189], v[108:111]
	v_mfma_f32_16x16x32_bf16 v[16:19], v[120:123], v[194:197], v[16:19]
	v_mfma_f32_16x16x32_bf16 v[20:23], v[158:161], v[194:197], v[20:23]
	v_mfma_f32_16x16x32_bf16 v[8:11], v[124:127], v[174:177], v[8:11]
	v_mfma_f32_16x16x32_bf16 v[12:15], v[166:169], v[174:177], v[12:15]
	v_mfma_f32_16x16x32_bf16 v[24:27], v[124:127], v[182:185], v[24:27]
	v_mfma_f32_16x16x32_bf16 v[28:31], v[166:169], v[182:185], v[28:31]
	v_mfma_f32_16x16x32_bf16 v[60:63], v[124:127], v[190:193], v[60:63]
	v_mfma_f32_16x16x32_bf16 v[100:103], v[166:169], v[190:193], v[100:103]
	v_mfma_f32_16x16x32_bf16 v[16:19], v[124:127], v[198:201], v[16:19]
	v_mfma_f32_16x16x32_bf16 v[20:23], v[166:169], v[198:201], v[20:23]
	s_barrier
	ds_read_b128 v[104:107], v210
	ds_read_b128 v[108:111], v210 offset:1024
	ds_read_b128 v[112:115], v210 offset:2048
	ds_read_b128 v[116:119], v210 offset:3072
	ds_read_b128 v[120:123], v211
	ds_read_b128 v[124:127], v211 offset:1024
	ds_read_b128 v[158:161], v211 offset:2048
	ds_read_b128 v[166:169], v211 offset:3072
	s_add_u32 s24, s24, 0x10180
	s_addc_u32 s25, s25, 0
	s_mov_b32 m0, s53
	v_lshl_add_u64 v[162:163], s[24:25], 0, v[148:149]
	ds_read_b128 v[170:173], v165
	ds_read_b128 v[174:177], v165 offset:1024
	ds_read_b128 v[178:181], v165 offset:2048
	ds_read_b128 v[182:185], v165 offset:3072
	ds_read_b128 v[186:189], v165 offset:4096
	ds_read_b128 v[190:193], v165 offset:5120
	ds_read_b128 v[194:197], v165 offset:6144
	ds_read_b128 v[198:201], v165 offset:7168
	global_load_lds_dwordx4 v[162:163], off
	v_lshl_add_u64 v[162:163], s[24:25], 0, v[150:151]
	s_mov_b32 m0, s15
	s_nop 0
	global_load_lds_dwordx4 v[162:163], off
	s_waitcnt vmcnt(8) lgkmcnt(0)
	s_barrier
	v_mfma_f32_16x16x32_bf16 v[64:67], v[104:107], v[170:173], v[64:67]
	v_mfma_f32_16x16x32_bf16 v[68:71], v[112:115], v[170:173], v[68:71]
	v_mfma_f32_16x16x32_bf16 v[72:75], v[104:107], v[178:181], v[72:75]
	v_mfma_f32_16x16x32_bf16 v[76:79], v[112:115], v[178:181], v[76:79]
	v_mfma_f32_16x16x32_bf16 v[80:83], v[104:107], v[186:189], v[80:83]
	v_mfma_f32_16x16x32_bf16 v[84:87], v[112:115], v[186:189], v[84:87]
	v_mfma_f32_16x16x32_bf16 v[88:91], v[104:107], v[194:197], v[88:91]
	v_mfma_f32_16x16x32_bf16 v[64:67], v[108:111], v[174:177], v[64:67]
	v_mfma_f32_16x16x32_bf16 v[68:71], v[116:119], v[174:177], v[68:71]
	v_mfma_f32_16x16x32_bf16 v[72:75], v[108:111], v[182:185], v[72:75]
	v_mfma_f32_16x16x32_bf16 v[76:79], v[116:119], v[182:185], v[76:79]
	v_mfma_f32_16x16x32_bf16 v[80:83], v[108:111], v[190:193], v[80:83]
	v_mfma_f32_16x16x32_bf16 v[84:87], v[116:119], v[190:193], v[84:87]
	v_mfma_f32_16x16x32_bf16 v[202:205], v[108:111], v[198:201], v[88:91]
	v_mfma_f32_16x16x32_bf16 v[88:91], v[112:115], v[194:197], v[92:95]
	v_mfma_f32_16x16x32_bf16 v[206:209], v[116:119], v[198:201], v[88:91]
	v_mfma_f32_16x16x32_bf16 v[88:91], v[120:123], v[170:173], v[96:99]
	v_mfma_f32_16x16x32_bf16 v[32:35], v[158:161], v[170:173], v[32:35]
	v_mfma_f32_16x16x32_bf16 v[36:39], v[120:123], v[178:181], v[36:39]
	v_mfma_f32_16x16x32_bf16 v[40:43], v[158:161], v[178:181], v[40:43]
	v_mfma_f32_16x16x32_bf16 v[44:47], v[120:123], v[186:189], v[44:47]
	v_mfma_f32_16x16x32_bf16 v[48:51], v[158:161], v[186:189], v[48:51]
	v_mfma_f32_16x16x32_bf16 v[52:55], v[120:123], v[194:197], v[52:55]
	v_mfma_f32_16x16x32_bf16 v[56:59], v[158:161], v[194:197], v[56:59]
	v_mfma_f32_16x16x32_bf16 v[96:99], v[124:127], v[174:177], v[88:91]
	v_mfma_f32_16x16x32_bf16 v[32:35], v[166:169], v[174:177], v[32:35]
	v_mfma_f32_16x16x32_bf16 v[36:39], v[124:127], v[182:185], v[36:39]
	v_mfma_f32_16x16x32_bf16 v[40:43], v[166:169], v[182:185], v[40:43]
	v_mfma_f32_16x16x32_bf16 v[44:47], v[124:127], v[190:193], v[44:47]
	v_mfma_f32_16x16x32_bf16 v[48:51], v[166:169], v[190:193], v[48:51]
	v_mfma_f32_16x16x32_bf16 v[52:55], v[124:127], v[198:201], v[52:55]
	v_mfma_f32_16x16x32_bf16 v[56:59], v[166:169], v[198:201], v[56:59]
	s_barrier
	s_mov_b32 m0, s51
	v_lshl_add_u64 v[162:163], s[28:29], 0, v[232:233]
	s_add_u32 s24, s28, 0x10000
	ds_read_b128 v[88:91], v165 offset:16384
	ds_read_b128 v[92:95], v165 offset:17408
	ds_read_b128 v[170:173], v165 offset:18432
	ds_read_b128 v[174:177], v165 offset:19456
	ds_read_b128 v[178:181], v165 offset:20480
	ds_read_b128 v[182:185], v165 offset:21504
	ds_read_b128 v[186:189], v165 offset:22528
	ds_read_b128 v[190:193], v165 offset:23552
	global_load_lds_dwordx4 v[162:163], off
	v_lshl_add_u64 v[230:231], s[28:29], 0, v[152:153]
	s_mov_b32 m0, s17
	s_addc_u32 s25, s29, 0
	global_load_lds_dwordx4 v[230:231], off
	v_lshl_add_u64 v[194:195], s[24:25], 0, v[232:233]
	s_mov_b32 m0, s49
	v_lshl_add_u64 v[242:243], s[30:31], 0, v[148:149]
	global_load_lds_dwordx4 v[194:195], off
	v_lshl_add_u64 v[194:195], s[24:25], 0, v[152:153]
	s_mov_b32 m0, s50
	v_lshl_add_u64 v[244:245], s[30:31], 0, v[150:151]
	global_load_lds_dwordx4 v[194:195], off
	s_mov_b32 m0, s40
	s_nop 0
	global_load_lds_dwordx4 v[242:243], off
	s_mov_b32 m0, s41
	s_nop 0
	global_load_lds_dwordx4 v[244:245], off
	s_waitcnt vmcnt(8) lgkmcnt(0)
	s_barrier
	v_mfma_f32_16x16x32_bf16 v[128:131], v[104:107], v[88:91], v[128:131]
	v_mfma_f32_16x16x32_bf16 v[194:197], v[108:111], v[92:95], v[128:131]
	v_mfma_f32_16x16x32_bf16 v[128:131], v[112:115], v[88:91], v[132:135]
	v_mfma_f32_16x16x32_bf16 v[198:201], v[116:119], v[92:95], v[128:131]
	v_mfma_f32_16x16x32_bf16 v[128:131], v[104:107], v[170:173], v[136:139]
	v_mfma_f32_16x16x32_bf16 v[210:213], v[108:111], v[174:177], v[128:131]
	v_mfma_f32_16x16x32_bf16 v[128:131], v[112:115], v[170:173], v[140:143]
	v_mfma_f32_16x16x32_bf16 v[214:217], v[116:119], v[174:177], v[128:131]
	v_mfma_f32_16x16x32_bf16 v[128:131], v[104:107], v[178:181], v[144:147]
	v_mfma_f32_16x16x32_bf16 v[0:3], v[104:107], v[186:189], v[0:3]
	v_mfma_f32_16x16x32_bf16 v[4:7], v[112:115], v[186:189], v[4:7]
	v_mfma_f32_16x16x32_bf16 v[218:221], v[108:111], v[182:185], v[128:131]
	v_mfma_f32_16x16x32_bf16 v[128:131], v[112:115], v[178:181], v[154:157]
	v_mfma_f32_16x16x32_bf16 v[0:3], v[108:111], v[190:193], v[0:3]
	v_mfma_f32_16x16x32_bf16 v[4:7], v[116:119], v[190:193], v[4:7]
	v_mfma_f32_16x16x32_bf16 v[154:157], v[116:119], v[182:185], v[128:131]
	v_mfma_f32_16x16x32_bf16 v[8:11], v[120:123], v[88:91], v[8:11]
	v_mfma_f32_16x16x32_bf16 v[104:107], v[124:127], v[92:95], v[8:11]
	v_mfma_f32_16x16x32_bf16 v[8:11], v[158:161], v[88:91], v[12:15]
	v_mfma_f32_16x16x32_bf16 v[108:111], v[166:169], v[92:95], v[8:11]
	v_mfma_f32_16x16x32_bf16 v[8:11], v[120:123], v[170:173], v[24:27]
	v_mfma_f32_16x16x32_bf16 v[112:115], v[124:127], v[174:177], v[8:11]
	v_mfma_f32_16x16x32_bf16 v[8:11], v[158:161], v[170:173], v[28:31]
	v_mfma_f32_16x16x32_bf16 v[116:119], v[166:169], v[174:177], v[8:11]
	v_mfma_f32_16x16x32_bf16 v[8:11], v[120:123], v[178:181], v[60:63]
	v_mfma_f32_16x16x32_bf16 v[170:173], v[124:127], v[182:185], v[8:11]
	v_mfma_f32_16x16x32_bf16 v[8:11], v[158:161], v[178:181], v[100:103]
	v_mfma_f32_16x16x32_bf16 v[174:177], v[166:169], v[182:185], v[8:11]
	v_mfma_f32_16x16x32_bf16 v[8:11], v[120:123], v[186:189], v[16:19]
	v_mfma_f32_16x16x32_bf16 v[124:127], v[124:127], v[190:193], v[8:11]
	v_mfma_f32_16x16x32_bf16 v[8:11], v[158:161], v[186:189], v[20:23]
	v_mfma_f32_16x16x32_bf16 v[158:161], v[166:169], v[190:193], v[8:11]
	s_barrier
	s_nop 4
	ds_read_b128 v[8:11], v222
	ds_read_b128 v[12:15], v222 offset:1024
	ds_read_b128 v[16:19], v222 offset:2048
	ds_read_b128 v[20:23], v222 offset:3072
	ds_read_b128 v[166:169], v223
	ds_read_b128 v[178:181], v223 offset:1024
	ds_read_b128 v[182:185], v223 offset:2048
	ds_read_b128 v[186:189], v223 offset:3072
	s_add_u32 s24, s30, 0x10000
	s_addc_u32 s25, s31, 0
	s_mov_b32 m0, s42
	v_lshl_add_u64 v[88:89], s[24:25], 0, v[148:149]
	ds_read_b128 v[24:27], v165 offset:32768
	ds_read_b128 v[28:31], v165 offset:33792
	ds_read_b128 v[60:63], v165 offset:34816
	ds_read_b128 v[190:193], v165 offset:35840
	ds_read_b128 v[222:225], v165 offset:36864
	ds_read_b128 v[226:229], v165 offset:37888
	ds_read_b128 v[234:237], v165 offset:38912
	ds_read_b128 v[238:241], v165 offset:39936
	global_load_lds_dwordx4 v[88:89], off
	v_lshl_add_u64 v[88:89], s[24:25], 0, v[150:151]
	s_mov_b32 m0, s43
	s_nop 0
	global_load_lds_dwordx4 v[88:89], off
	s_waitcnt vmcnt(8) lgkmcnt(0)
	s_barrier
	v_mfma_f32_16x16x32_bf16 v[64:67], v[8:11], v[24:27], v[64:67]
	v_mfma_f32_16x16x32_bf16 v[144:147], v[12:15], v[28:31], v[64:67]
	v_mfma_f32_16x16x32_bf16 v[64:67], v[16:19], v[24:27], v[68:71]
	v_mfma_f32_16x16x32_bf16 v[140:143], v[20:23], v[28:31], v[64:67]
	v_mfma_f32_16x16x32_bf16 v[64:67], v[8:11], v[60:63], v[72:75]
	v_mfma_f32_16x16x32_bf16 v[128:131], v[12:15], v[190:193], v[64:67]
	v_mfma_f32_16x16x32_bf16 v[64:67], v[16:19], v[60:63], v[76:79]
	v_mfma_f32_16x16x32_bf16 v[120:123], v[20:23], v[190:193], v[64:67]
	v_mfma_f32_16x16x32_bf16 v[64:67], v[8:11], v[222:225], v[80:83]
	v_mfma_f32_16x16x32_bf16 v[92:95], v[12:15], v[226:229], v[64:67]
	v_mfma_f32_16x16x32_bf16 v[64:67], v[16:19], v[222:225], v[84:87]
	v_mfma_f32_16x16x32_bf16 v[88:91], v[20:23], v[226:229], v[64:67]
	v_mfma_f32_16x16x32_bf16 v[64:67], v[8:11], v[234:237], v[202:205]
	v_mfma_f32_16x16x32_bf16 v[76:79], v[12:15], v[238:241], v[64:67]
	v_mfma_f32_16x16x32_bf16 v[64:67], v[16:19], v[234:237], v[206:209]
	v_mfma_f32_16x16x32_bf16 v[72:75], v[20:23], v[238:241], v[64:67]
	v_mfma_f32_16x16x32_bf16 v[64:67], v[166:169], v[24:27], v[96:99]
	v_mfma_f32_16x16x32_bf16 v[24:27], v[182:185], v[24:27], v[32:35]
	v_mfma_f32_16x16x32_bf16 v[132:135], v[186:189], v[28:31], v[24:27]
	v_mfma_f32_16x16x32_bf16 v[24:27], v[166:169], v[60:63], v[36:39]
	v_mfma_f32_16x16x32_bf16 v[100:103], v[178:181], v[190:193], v[24:27]
	v_mfma_f32_16x16x32_bf16 v[24:27], v[182:185], v[60:63], v[40:43]
	v_mfma_f32_16x16x32_bf16 v[96:99], v[186:189], v[190:193], v[24:27]
	v_mfma_f32_16x16x32_bf16 v[24:27], v[166:169], v[222:225], v[44:47]
	v_mfma_f32_16x16x32_bf16 v[84:87], v[178:181], v[226:229], v[24:27]
	v_mfma_f32_16x16x32_bf16 v[24:27], v[182:185], v[222:225], v[48:51]
	v_mfma_f32_16x16x32_bf16 v[80:83], v[186:189], v[226:229], v[24:27]
	v_mfma_f32_16x16x32_bf16 v[24:27], v[166:169], v[234:237], v[52:55]
	v_mfma_f32_16x16x32_bf16 v[68:71], v[178:181], v[238:241], v[24:27]
	v_mfma_f32_16x16x32_bf16 v[24:27], v[182:185], v[234:237], v[56:59]
	v_mfma_f32_16x16x32_bf16 v[136:139], v[178:181], v[28:31], v[64:67]
	v_mfma_f32_16x16x32_bf16 v[64:67], v[186:189], v[238:241], v[24:27]
	s_barrier
	s_mov_b32 m0, s54
	s_nop 2
	v_lshl_add_u64 v[24:25], v[162:163], 0, s[94:95]
	s_add_u32 s24, s28, 0x10080
	ds_read_b128 v[32:35], v165 offset:49152
	ds_read_b128 v[36:39], v165 offset:50176
	ds_read_b128 v[190:193], v165 offset:51200
	ds_read_b128 v[202:205], v165 offset:52224
	ds_read_b128 v[206:209], v165 offset:53248
	ds_read_b128 v[222:225], v165 offset:54272
	ds_read_b128 v[226:229], v165 offset:55296
	ds_read_b128 v[234:237], v165 offset:56320
	global_load_lds_dwordx4 v[24:25], off
	v_lshl_add_u64 v[24:25], v[230:231], 0, s[94:95]
	s_mov_b32 m0, s52
	s_addc_u32 s25, s29, 0
	global_load_lds_dwordx4 v[24:25], off
	v_lshl_add_u64 v[24:25], s[24:25], 0, v[232:233]
	s_mov_b32 m0, s26
	s_nop 0
	global_load_lds_dwordx4 v[24:25], off
	v_lshl_add_u64 v[24:25], s[24:25], 0, v[152:153]
	s_mov_b32 m0, s27
	s_nop 0
	global_load_lds_dwordx4 v[24:25], off
	v_lshl_add_u64 v[24:25], v[242:243], 0, s[94:95]
	s_mov_b32 m0, s46
	s_nop 0
	global_load_lds_dwordx4 v[24:25], off
	v_lshl_add_u64 v[24:25], v[244:245], 0, s[94:95]
	s_mov_b32 m0, s47
	s_nop 0
	global_load_lds_dwordx4 v[24:25], off
	s_waitcnt vmcnt(8) lgkmcnt(0)
	s_barrier
	v_mfma_f32_16x16x32_bf16 v[24:27], v[8:11], v[32:35], v[194:197]
	v_mfma_f32_16x16x32_bf16 v[60:63], v[12:15], v[36:39], v[24:27]
	v_mfma_f32_16x16x32_bf16 v[24:27], v[16:19], v[32:35], v[198:201]
	v_mfma_f32_16x16x32_bf16 v[56:59], v[20:23], v[36:39], v[24:27]
	v_mfma_f32_16x16x32_bf16 v[24:27], v[8:11], v[190:193], v[210:213]
	v_mfma_f32_16x16x32_bf16 v[44:47], v[12:15], v[202:205], v[24:27]
	v_mfma_f32_16x16x32_bf16 v[24:27], v[16:19], v[190:193], v[214:217]
	v_mfma_f32_16x16x32_bf16 v[40:43], v[20:23], v[202:205], v[24:27]
	v_mfma_f32_16x16x32_bf16 v[24:27], v[8:11], v[206:209], v[218:221]
	v_mfma_f32_16x16x32_bf16 v[0:3], v[8:11], v[226:229], v[0:3]
	v_mfma_f32_16x16x32_bf16 v[28:31], v[12:15], v[222:225], v[24:27]
	v_mfma_f32_16x16x32_bf16 v[24:27], v[16:19], v[206:209], v[154:157]
	v_mfma_f32_16x16x32_bf16 v[12:15], v[12:15], v[234:237], v[0:3]
	v_mfma_f32_16x16x32_bf16 v[0:3], v[16:19], v[226:229], v[4:7]
	v_mfma_f32_16x16x32_bf16 v[24:27], v[20:23], v[222:225], v[24:27]
	v_mfma_f32_16x16x32_bf16 v[8:11], v[20:23], v[234:237], v[0:3]
	v_mfma_f32_16x16x32_bf16 v[0:3], v[166:169], v[32:35], v[104:107]
	v_mfma_f32_16x16x32_bf16 v[52:55], v[178:181], v[36:39], v[0:3]
	v_mfma_f32_16x16x32_bf16 v[0:3], v[182:185], v[32:35], v[108:111]
	v_mfma_f32_16x16x32_bf16 v[48:51], v[186:189], v[36:39], v[0:3]
	v_mfma_f32_16x16x32_bf16 v[0:3], v[166:169], v[190:193], v[112:115]
	v_mfma_f32_16x16x32_bf16 v[36:39], v[178:181], v[202:205], v[0:3]
	v_mfma_f32_16x16x32_bf16 v[0:3], v[182:185], v[190:193], v[116:119]
	v_mfma_f32_16x16x32_bf16 v[32:35], v[186:189], v[202:205], v[0:3]
	v_mfma_f32_16x16x32_bf16 v[0:3], v[166:169], v[206:209], v[170:173]
	v_mfma_f32_16x16x32_bf16 v[20:23], v[178:181], v[222:225], v[0:3]
	v_mfma_f32_16x16x32_bf16 v[0:3], v[182:185], v[206:209], v[174:177]
	v_mfma_f32_16x16x32_bf16 v[16:19], v[186:189], v[222:225], v[0:3]
	v_mfma_f32_16x16x32_bf16 v[0:3], v[166:169], v[226:229], v[124:127]
	v_mfma_f32_16x16x32_bf16 v[4:7], v[178:181], v[234:237], v[0:3]
	v_mfma_f32_16x16x32_bf16 v[0:3], v[182:185], v[226:229], v[158:161]
	v_mfma_f32_16x16x32_bf16 v[0:3], v[186:189], v[234:237], v[0:3]
	s_barrier
	s_andn2_b64 vcc, exec, s[10:11]
	s_cbranch_vccnz .LBB0_1422
	s_barrier

.LBB0_1491:
	s_ashr_i32 s23, s22, 31
	s_lshl_b64 s[24:25], s[22:23], 21
	s_add_u32 s24, s70, s24
	s_addc_u32 s25, s71, s25
	s_and_b64 s[26:27], s[4:5], exec
	s_cselect_b32 s23, s25, s35
	s_cselect_b32 s56, s24, s34
	s_ashr_i32 s21, s20, 31
	s_lshl_b64 s[26:27], s[20:21], 21
	s_add_u32 s26, s72, s26
	s_addc_u32 s27, s76, s27
	s_and_b64 s[36:37], s[4:5], exec
	s_cselect_b32 s21, s27, s31
	s_cselect_b32 s57, s26, s30
	s_add_u32 s58, s30, 0x100
	s_addc_u32 s59, s31, 0
	s_add_u32 s30, s34, 0x100080
	s_addc_u32 s31, s35, 0
	s_mov_b32 s60, -2
	s_waitcnt vmcnt(0)
	s_add_u32 s34, s30, 0xfff00080
	s_addc_u32 s35, s31, -1
	s_add_i32 s61, 0, 0x10000
	s_cmp_eq_u32 s60, 60
	s_cselect_b32 s37, s23, s35
	s_cselect_b32 s36, s56, s34
	s_cselect_b32 s35, s21, s59
	s_cselect_b32 s34, s57, s58
	s_add_i32 s64, 0, 0x14000
	v_add_u32_e32 v100, s61, v220
	v_add_u32_e32 v156, s64, v220
	ds_read_b128 v[88:91], v100
	ds_read_b128 v[92:95], v100 offset:1024
	ds_read_b128 v[96:99], v100 offset:2048
	ds_read_b128 v[100:103], v100 offset:3072
	ds_read_b128 v[144:147], v156
	ds_read_b128 v[148:151], v156 offset:1024
	ds_read_b128 v[152:155], v156 offset:2048
	ds_read_b128 v[156:159], v156 offset:3072
	v_lshl_add_u64 v[202:203], s[30:31], 0, v[188:189]
	s_add_i32 m0, s78, 0xc000
	ds_read_b128 v[160:163], v221
	ds_read_b128 v[164:167], v221 offset:1024
	ds_read_b128 v[168:171], v221 offset:2048
	ds_read_b128 v[172:175], v221 offset:3072
	ds_read_b128 v[176:179], v221 offset:4096
	ds_read_b128 v[190:193], v221 offset:5120
	ds_read_b128 v[194:197], v221 offset:6144
	ds_read_b128 v[198:201], v221 offset:7168
	global_load_lds_dwordx4 v[202:203], off
	v_lshl_add_u64 v[202:203], s[30:31], 0, v[186:187]
	s_add_i32 m0, s78, 0xe000
	s_nop 0
	global_load_lds_dwordx4 v[202:203], off
	s_waitcnt vmcnt(8) lgkmcnt(0)
	s_barrier
	v_mfma_f32_16x16x32_bf16 v[140:143], v[88:91], v[160:163], 0
	v_mfma_f32_16x16x32_bf16 v[136:139], v[96:99], v[160:163], 0
	v_mfma_f32_16x16x32_bf16 v[124:127], v[88:91], v[168:171], 0
	v_mfma_f32_16x16x32_bf16 v[120:123], v[96:99], v[168:171], 0
	v_mfma_f32_16x16x32_bf16 v[108:111], v[88:91], v[176:179], 0
	v_mfma_f32_16x16x32_bf16 v[104:107], v[96:99], v[176:179], 0
	v_mfma_f32_16x16x32_bf16 v[76:79], v[88:91], v[194:197], 0
	v_mfma_f32_16x16x32_bf16 v[72:75], v[96:99], v[194:197], 0
	v_mfma_f32_16x16x32_bf16 v[140:143], v[92:95], v[164:167], v[140:143]
	v_mfma_f32_16x16x32_bf16 v[136:139], v[100:103], v[164:167], v[136:139]
	v_mfma_f32_16x16x32_bf16 v[124:127], v[92:95], v[172:175], v[124:127]
	v_mfma_f32_16x16x32_bf16 v[120:123], v[100:103], v[172:175], v[120:123]
	v_mfma_f32_16x16x32_bf16 v[108:111], v[92:95], v[190:193], v[108:111]
	v_mfma_f32_16x16x32_bf16 v[104:107], v[100:103], v[190:193], v[104:107]
	v_mfma_f32_16x16x32_bf16 v[76:79], v[92:95], v[198:201], v[76:79]
	v_mfma_f32_16x16x32_bf16 v[72:75], v[100:103], v[198:201], v[72:75]
	v_mfma_f32_16x16x32_bf16 v[132:135], v[144:147], v[160:163], 0
	v_mfma_f32_16x16x32_bf16 v[128:131], v[152:155], v[160:163], 0
	v_mfma_f32_16x16x32_bf16 v[116:119], v[144:147], v[168:171], 0
	v_mfma_f32_16x16x32_bf16 v[112:115], v[152:155], v[168:171], 0
	v_mfma_f32_16x16x32_bf16 v[84:87], v[144:147], v[176:179], 0
	v_mfma_f32_16x16x32_bf16 v[80:83], v[152:155], v[176:179], 0
	v_mfma_f32_16x16x32_bf16 v[68:71], v[144:147], v[194:197], 0
	v_mfma_f32_16x16x32_bf16 v[64:67], v[152:155], v[194:197], 0
	v_mfma_f32_16x16x32_bf16 v[132:135], v[148:151], v[164:167], v[132:135]
	v_mfma_f32_16x16x32_bf16 v[128:131], v[156:159], v[164:167], v[128:131]
	v_mfma_f32_16x16x32_bf16 v[116:119], v[148:151], v[172:175], v[116:119]
	v_mfma_f32_16x16x32_bf16 v[112:115], v[156:159], v[172:175], v[112:115]
	v_mfma_f32_16x16x32_bf16 v[84:87], v[148:151], v[190:193], v[84:87]
	v_mfma_f32_16x16x32_bf16 v[80:83], v[156:159], v[190:193], v[80:83]
	v_mfma_f32_16x16x32_bf16 v[68:71], v[148:151], v[198:201], v[68:71]
	v_mfma_f32_16x16x32_bf16 v[64:67], v[156:159], v[198:201], v[64:67]
	s_barrier
	s_add_i32 s61, s61, s77
	v_lshl_add_u64 v[202:203], s[34:35], 0, v[232:233]
	s_mov_b32 m0, s61
	ds_read_b128 v[160:163], v221 offset:16384
	ds_read_b128 v[164:167], v221 offset:17408
	ds_read_b128 v[168:171], v221 offset:18432
	ds_read_b128 v[172:175], v221 offset:19456
	ds_read_b128 v[176:179], v221 offset:20480
	ds_read_b128 v[190:193], v221 offset:21504
	ds_read_b128 v[194:197], v221 offset:22528
	ds_read_b128 v[198:201], v221 offset:23552
	global_load_lds_dwordx4 v[202:203], off
	s_add_i32 m0, s61, 0x2000
	s_add_u32 s62, s34, 0x100000
	v_lshl_add_u64 v[204:205], s[34:35], 0, v[184:185]
	s_addc_u32 s63, s35, 0
	s_add_i32 s61, s64, s77
	global_load_lds_dwordx4 v[204:205], off
	v_lshl_add_u64 v[206:207], s[62:63], 0, v[232:233]
	s_mov_b32 m0, s61
	v_lshl_add_u64 v[208:209], s[36:37], 0, v[182:183]
	global_load_lds_dwordx4 v[206:207], off
	v_lshl_add_u64 v[206:207], s[62:63], 0, v[184:185]
	s_add_i32 m0, s61, 0x2000
	s_nop 0
	global_load_lds_dwordx4 v[206:207], off
	v_lshl_add_u64 v[206:207], s[36:37], 0, v[180:181]
	s_waitcnt vmcnt(6) lgkmcnt(0)
	s_barrier
	v_mfma_f32_16x16x32_bf16 v[60:63], v[88:91], v[160:163], 0
	v_mfma_f32_16x16x32_bf16 v[56:59], v[96:99], v[160:163], 0
	v_mfma_f32_16x16x32_bf16 v[44:47], v[88:91], v[168:171], 0
	v_mfma_f32_16x16x32_bf16 v[40:43], v[96:99], v[168:171], 0
	v_mfma_f32_16x16x32_bf16 v[28:31], v[88:91], v[176:179], 0
	v_mfma_f32_16x16x32_bf16 v[24:27], v[96:99], v[176:179], 0
	v_mfma_f32_16x16x32_bf16 v[12:15], v[88:91], v[194:197], 0
	v_mfma_f32_16x16x32_bf16 v[8:11], v[96:99], v[194:197], 0
	v_mfma_f32_16x16x32_bf16 v[60:63], v[92:95], v[164:167], v[60:63]
	v_mfma_f32_16x16x32_bf16 v[56:59], v[100:103], v[164:167], v[56:59]
	v_mfma_f32_16x16x32_bf16 v[44:47], v[92:95], v[172:175], v[44:47]
	v_mfma_f32_16x16x32_bf16 v[40:43], v[100:103], v[172:175], v[40:43]
	v_mfma_f32_16x16x32_bf16 v[28:31], v[92:95], v[190:193], v[28:31]
	v_mfma_f32_16x16x32_bf16 v[24:27], v[100:103], v[190:193], v[24:27]
	v_mfma_f32_16x16x32_bf16 v[12:15], v[92:95], v[198:201], v[12:15]
	v_mfma_f32_16x16x32_bf16 v[8:11], v[100:103], v[198:201], v[8:11]
	v_mfma_f32_16x16x32_bf16 v[52:55], v[144:147], v[160:163], 0
	v_mfma_f32_16x16x32_bf16 v[48:51], v[152:155], v[160:163], 0
	v_mfma_f32_16x16x32_bf16 v[36:39], v[144:147], v[168:171], 0
	v_mfma_f32_16x16x32_bf16 v[32:35], v[152:155], v[168:171], 0
	v_mfma_f32_16x16x32_bf16 v[20:23], v[144:147], v[176:179], 0
	v_mfma_f32_16x16x32_bf16 v[16:19], v[152:155], v[176:179], 0
	v_mfma_f32_16x16x32_bf16 v[4:7], v[144:147], v[194:197], 0
	v_mfma_f32_16x16x32_bf16 v[0:3], v[152:155], v[194:197], 0
	v_mfma_f32_16x16x32_bf16 v[52:55], v[148:151], v[164:167], v[52:55]
	v_mfma_f32_16x16x32_bf16 v[48:51], v[156:159], v[164:167], v[48:51]
	v_mfma_f32_16x16x32_bf16 v[36:39], v[148:151], v[172:175], v[36:39]
	v_mfma_f32_16x16x32_bf16 v[32:35], v[156:159], v[172:175], v[32:35]
	v_mfma_f32_16x16x32_bf16 v[20:23], v[148:151], v[190:193], v[20:23]
	v_mfma_f32_16x16x32_bf16 v[16:19], v[156:159], v[190:193], v[16:19]
	v_mfma_f32_16x16x32_bf16 v[4:7], v[148:151], v[198:201], v[4:7]
	v_mfma_f32_16x16x32_bf16 v[0:3], v[156:159], v[198:201], v[0:3]
	s_barrier
	s_branch .Lzmid_6
.LBB0_1492:
	s_add_u32 s34, s30, 0xfff00080
	s_addc_u32 s35, s31, -1
	s_add_i32 s61, 0, 0x10000
	s_cmp_eq_u32 s60, 60
	s_cselect_b32 s37, s23, s35
	s_cselect_b32 s36, s56, s34
	s_cselect_b32 s35, s21, s59
	s_cselect_b32 s34, s57, s58
	s_add_i32 s64, 0, 0x14000
	v_add_u32_e32 v100, s61, v220
	v_add_u32_e32 v156, s64, v220
	ds_read_b128 v[88:91], v100
	ds_read_b128 v[92:95], v100 offset:1024
	ds_read_b128 v[96:99], v100 offset:2048
	ds_read_b128 v[100:103], v100 offset:3072
	ds_read_b128 v[144:147], v156
	ds_read_b128 v[148:151], v156 offset:1024
	ds_read_b128 v[152:155], v156 offset:2048
	ds_read_b128 v[156:159], v156 offset:3072
	v_lshl_add_u64 v[202:203], s[30:31], 0, v[188:189]
	s_add_i32 m0, s78, 0xc000
	ds_read_b128 v[160:163], v221
	ds_read_b128 v[164:167], v221 offset:1024
	ds_read_b128 v[168:171], v221 offset:2048
	ds_read_b128 v[172:175], v221 offset:3072
	ds_read_b128 v[176:179], v221 offset:4096
	ds_read_b128 v[190:193], v221 offset:5120
	ds_read_b128 v[194:197], v221 offset:6144
	ds_read_b128 v[198:201], v221 offset:7168
	global_load_lds_dwordx4 v[202:203], off
	v_lshl_add_u64 v[202:203], s[30:31], 0, v[186:187]
	s_add_i32 m0, s78, 0xe000
	s_nop 0
	global_load_lds_dwordx4 v[202:203], off
	s_waitcnt vmcnt(8) lgkmcnt(0)
	s_barrier
	v_mfma_f32_16x16x32_bf16 v[140:143], v[88:91], v[160:163], v[140:143]
	v_mfma_f32_16x16x32_bf16 v[136:139], v[96:99], v[160:163], v[136:139]
	v_mfma_f32_16x16x32_bf16 v[124:127], v[88:91], v[168:171], v[124:127]
	v_mfma_f32_16x16x32_bf16 v[120:123], v[96:99], v[168:171], v[120:123]
	v_mfma_f32_16x16x32_bf16 v[108:111], v[88:91], v[176:179], v[108:111]
	v_mfma_f32_16x16x32_bf16 v[104:107], v[96:99], v[176:179], v[104:107]
	v_mfma_f32_16x16x32_bf16 v[76:79], v[88:91], v[194:197], v[76:79]
	v_mfma_f32_16x16x32_bf16 v[72:75], v[96:99], v[194:197], v[72:75]
	v_mfma_f32_16x16x32_bf16 v[140:143], v[92:95], v[164:167], v[140:143]
	v_mfma_f32_16x16x32_bf16 v[136:139], v[100:103], v[164:167], v[136:139]
	v_mfma_f32_16x16x32_bf16 v[124:127], v[92:95], v[172:175], v[124:127]
	v_mfma_f32_16x16x32_bf16 v[120:123], v[100:103], v[172:175], v[120:123]
	v_mfma_f32_16x16x32_bf16 v[108:111], v[92:95], v[190:193], v[108:111]
	v_mfma_f32_16x16x32_bf16 v[104:107], v[100:103], v[190:193], v[104:107]
	v_mfma_f32_16x16x32_bf16 v[76:79], v[92:95], v[198:201], v[76:79]
	v_mfma_f32_16x16x32_bf16 v[72:75], v[100:103], v[198:201], v[72:75]
	v_mfma_f32_16x16x32_bf16 v[132:135], v[144:147], v[160:163], v[132:135]
	v_mfma_f32_16x16x32_bf16 v[128:131], v[152:155], v[160:163], v[128:131]
	v_mfma_f32_16x16x32_bf16 v[116:119], v[144:147], v[168:171], v[116:119]
	v_mfma_f32_16x16x32_bf16 v[112:115], v[152:155], v[168:171], v[112:115]
	v_mfma_f32_16x16x32_bf16 v[84:87], v[144:147], v[176:179], v[84:87]
	v_mfma_f32_16x16x32_bf16 v[80:83], v[152:155], v[176:179], v[80:83]
	v_mfma_f32_16x16x32_bf16 v[68:71], v[144:147], v[194:197], v[68:71]
	v_mfma_f32_16x16x32_bf16 v[64:67], v[152:155], v[194:197], v[64:67]
	v_mfma_f32_16x16x32_bf16 v[132:135], v[148:151], v[164:167], v[132:135]
	v_mfma_f32_16x16x32_bf16 v[128:131], v[156:159], v[164:167], v[128:131]
	v_mfma_f32_16x16x32_bf16 v[116:119], v[148:151], v[172:175], v[116:119]
	v_mfma_f32_16x16x32_bf16 v[112:115], v[156:159], v[172:175], v[112:115]
	v_mfma_f32_16x16x32_bf16 v[84:87], v[148:151], v[190:193], v[84:87]
	v_mfma_f32_16x16x32_bf16 v[80:83], v[156:159], v[190:193], v[80:83]
	v_mfma_f32_16x16x32_bf16 v[68:71], v[148:151], v[198:201], v[68:71]
	v_mfma_f32_16x16x32_bf16 v[64:67], v[156:159], v[198:201], v[64:67]
	s_barrier
	s_add_i32 s61, s61, s77
	v_lshl_add_u64 v[202:203], s[34:35], 0, v[232:233]
	s_mov_b32 m0, s61
	ds_read_b128 v[160:163], v221 offset:16384
	ds_read_b128 v[164:167], v221 offset:17408
	ds_read_b128 v[168:171], v221 offset:18432
	ds_read_b128 v[172:175], v221 offset:19456
	ds_read_b128 v[176:179], v221 offset:20480
	ds_read_b128 v[190:193], v221 offset:21504
	ds_read_b128 v[194:197], v221 offset:22528
	ds_read_b128 v[198:201], v221 offset:23552
	global_load_lds_dwordx4 v[202:203], off
	s_add_i32 m0, s61, 0x2000
	s_add_u32 s62, s34, 0x100000
	v_lshl_add_u64 v[204:205], s[34:35], 0, v[184:185]
	s_addc_u32 s63, s35, 0
	s_add_i32 s61, s64, s77
	global_load_lds_dwordx4 v[204:205], off
	v_lshl_add_u64 v[206:207], s[62:63], 0, v[232:233]
	s_mov_b32 m0, s61
	v_lshl_add_u64 v[208:209], s[36:37], 0, v[182:183]
	global_load_lds_dwordx4 v[206:207], off
	v_lshl_add_u64 v[206:207], s[62:63], 0, v[184:185]
	s_add_i32 m0, s61, 0x2000
	s_nop 0
	global_load_lds_dwordx4 v[206:207], off
	v_lshl_add_u64 v[206:207], s[36:37], 0, v[180:181]
	s_waitcnt vmcnt(6) lgkmcnt(0)
	s_barrier
	v_mfma_f32_16x16x32_bf16 v[60:63], v[88:91], v[160:163], v[60:63]
	v_mfma_f32_16x16x32_bf16 v[56:59], v[96:99], v[160:163], v[56:59]
	v_mfma_f32_16x16x32_bf16 v[44:47], v[88:91], v[168:171], v[44:47]
	v_mfma_f32_16x16x32_bf16 v[40:43], v[96:99], v[168:171], v[40:43]
	v_mfma_f32_16x16x32_bf16 v[28:31], v[88:91], v[176:179], v[28:31]
	v_mfma_f32_16x16x32_bf16 v[24:27], v[96:99], v[176:179], v[24:27]
	v_mfma_f32_16x16x32_bf16 v[12:15], v[88:91], v[194:197], v[12:15]
	v_mfma_f32_16x16x32_bf16 v[8:11], v[96:99], v[194:197], v[8:11]
	v_mfma_f32_16x16x32_bf16 v[60:63], v[92:95], v[164:167], v[60:63]
	v_mfma_f32_16x16x32_bf16 v[56:59], v[100:103], v[164:167], v[56:59]
	v_mfma_f32_16x16x32_bf16 v[44:47], v[92:95], v[172:175], v[44:47]
	v_mfma_f32_16x16x32_bf16 v[40:43], v[100:103], v[172:175], v[40:43]
	v_mfma_f32_16x16x32_bf16 v[28:31], v[92:95], v[190:193], v[28:31]
	v_mfma_f32_16x16x32_bf16 v[24:27], v[100:103], v[190:193], v[24:27]
	v_mfma_f32_16x16x32_bf16 v[12:15], v[92:95], v[198:201], v[12:15]
	v_mfma_f32_16x16x32_bf16 v[8:11], v[100:103], v[198:201], v[8:11]
	v_mfma_f32_16x16x32_bf16 v[52:55], v[144:147], v[160:163], v[52:55]
	v_mfma_f32_16x16x32_bf16 v[48:51], v[152:155], v[160:163], v[48:51]
	v_mfma_f32_16x16x32_bf16 v[36:39], v[144:147], v[168:171], v[36:39]
	v_mfma_f32_16x16x32_bf16 v[32:35], v[152:155], v[168:171], v[32:35]
	v_mfma_f32_16x16x32_bf16 v[20:23], v[144:147], v[176:179], v[20:23]
	v_mfma_f32_16x16x32_bf16 v[16:19], v[152:155], v[176:179], v[16:19]
	v_mfma_f32_16x16x32_bf16 v[4:7], v[144:147], v[194:197], v[4:7]
	v_mfma_f32_16x16x32_bf16 v[0:3], v[152:155], v[194:197], v[0:3]
	v_mfma_f32_16x16x32_bf16 v[52:55], v[148:151], v[164:167], v[52:55]
	v_mfma_f32_16x16x32_bf16 v[48:51], v[156:159], v[164:167], v[48:51]
	v_mfma_f32_16x16x32_bf16 v[36:39], v[148:151], v[172:175], v[36:39]
	v_mfma_f32_16x16x32_bf16 v[32:35], v[156:159], v[172:175], v[32:35]
	v_mfma_f32_16x16x32_bf16 v[20:23], v[148:151], v[190:193], v[20:23]
	v_mfma_f32_16x16x32_bf16 v[16:19], v[156:159], v[190:193], v[16:19]
	v_mfma_f32_16x16x32_bf16 v[4:7], v[148:151], v[198:201], v[4:7]
	v_mfma_f32_16x16x32_bf16 v[0:3], v[156:159], v[198:201], v[0:3]
	s_barrier
.Lzmid_6:
	s_add_i32 s61, 0, 0x18000
	s_add_i32 s62, 0, 0x1c000
	v_add_u32_e32 v100, s61, v220
	v_add_u32_e32 v156, s62, v220
	ds_read_b128 v[88:91], v100
	ds_read_b128 v[92:95], v100 offset:1024
	ds_read_b128 v[96:99], v100 offset:2048
	ds_read_b128 v[100:103], v100 offset:3072
	ds_read_b128 v[144:147], v156
	ds_read_b128 v[148:151], v156 offset:1024
	ds_read_b128 v[152:155], v156 offset:2048
	ds_read_b128 v[156:159], v156 offset:3072
	s_add_u32 s36, s36, 0x100000
	s_addc_u32 s37, s37, 0
	s_mov_b32 m0, s78
	s_nop 0
	global_load_lds_dwordx4 v[206:207], off
	s_mov_b32 m0, s79
	s_nop 0
	global_load_lds_dwordx4 v[208:209], off
	s_mov_b32 m0, s80
	v_lshl_add_u64 v[210:211], s[36:37], 0, v[180:181]
	ds_read_b128 v[160:163], v221 offset:32768
	ds_read_b128 v[164:167], v221 offset:33792
	ds_read_b128 v[168:171], v221 offset:34816
	ds_read_b128 v[172:175], v221 offset:35840
	ds_read_b128 v[176:179], v221 offset:36864
	ds_read_b128 v[190:193], v221 offset:37888
	ds_read_b128 v[194:197], v221 offset:38912
	ds_read_b128 v[198:201], v221 offset:39936
	global_load_lds_dwordx4 v[210:211], off
	v_lshl_add_u64 v[210:211], s[36:37], 0, v[182:183]
	s_mov_b32 m0, s81
	s_nop 0
	global_load_lds_dwordx4 v[210:211], off
	s_waitcnt vmcnt(8) lgkmcnt(0)
	s_barrier
	v_mfma_f32_16x16x32_bf16 v[140:143], v[88:91], v[160:163], v[140:143]
	v_mfma_f32_16x16x32_bf16 v[136:139], v[96:99], v[160:163], v[136:139]
	v_mfma_f32_16x16x32_bf16 v[124:127], v[88:91], v[168:171], v[124:127]
	v_mfma_f32_16x16x32_bf16 v[120:123], v[96:99], v[168:171], v[120:123]
	v_mfma_f32_16x16x32_bf16 v[108:111], v[88:91], v[176:179], v[108:111]
	v_mfma_f32_16x16x32_bf16 v[104:107], v[96:99], v[176:179], v[104:107]
	v_mfma_f32_16x16x32_bf16 v[76:79], v[88:91], v[194:197], v[76:79]
	v_mfma_f32_16x16x32_bf16 v[72:75], v[96:99], v[194:197], v[72:75]
	v_mfma_f32_16x16x32_bf16 v[140:143], v[92:95], v[164:167], v[140:143]
	v_mfma_f32_16x16x32_bf16 v[136:139], v[100:103], v[164:167], v[136:139]
	v_mfma_f32_16x16x32_bf16 v[124:127], v[92:95], v[172:175], v[124:127]
	v_mfma_f32_16x16x32_bf16 v[120:123], v[100:103], v[172:175], v[120:123]
	v_mfma_f32_16x16x32_bf16 v[108:111], v[92:95], v[190:193], v[108:111]
	v_mfma_f32_16x16x32_bf16 v[104:107], v[100:103], v[190:193], v[104:107]
	v_mfma_f32_16x16x32_bf16 v[76:79], v[92:95], v[198:201], v[76:79]
	v_mfma_f32_16x16x32_bf16 v[72:75], v[100:103], v[198:201], v[72:75]
	v_mfma_f32_16x16x32_bf16 v[132:135], v[144:147], v[160:163], v[132:135]
	v_mfma_f32_16x16x32_bf16 v[128:131], v[152:155], v[160:163], v[128:131]
	v_mfma_f32_16x16x32_bf16 v[116:119], v[144:147], v[168:171], v[116:119]
	v_mfma_f32_16x16x32_bf16 v[112:115], v[152:155], v[168:171], v[112:115]
	v_mfma_f32_16x16x32_bf16 v[84:87], v[144:147], v[176:179], v[84:87]
	v_mfma_f32_16x16x32_bf16 v[80:83], v[152:155], v[176:179], v[80:83]
	v_mfma_f32_16x16x32_bf16 v[68:71], v[144:147], v[194:197], v[68:71]
	v_mfma_f32_16x16x32_bf16 v[64:67], v[152:155], v[194:197], v[64:67]
	v_mfma_f32_16x16x32_bf16 v[132:135], v[148:151], v[164:167], v[132:135]
	v_mfma_f32_16x16x32_bf16 v[128:131], v[156:159], v[164:167], v[128:131]
	v_mfma_f32_16x16x32_bf16 v[116:119], v[148:151], v[172:175], v[116:119]
	v_mfma_f32_16x16x32_bf16 v[112:115], v[156:159], v[172:175], v[112:115]
	v_mfma_f32_16x16x32_bf16 v[84:87], v[148:151], v[190:193], v[84:87]
	v_mfma_f32_16x16x32_bf16 v[80:83], v[156:159], v[190:193], v[80:83]
	v_mfma_f32_16x16x32_bf16 v[68:71], v[148:151], v[198:201], v[68:71]
	v_mfma_f32_16x16x32_bf16 v[64:67], v[156:159], v[198:201], v[64:67]
	s_barrier
	s_add_i32 s36, s61, s77
	v_lshl_add_u64 v[202:203], v[202:203], 0, s[94:95]
	s_mov_b32 m0, s36
	ds_read_b128 v[160:163], v221 offset:49152
	ds_read_b128 v[164:167], v221 offset:50176
	ds_read_b128 v[168:171], v221 offset:51200
	ds_read_b128 v[172:175], v221 offset:52224
	ds_read_b128 v[176:179], v221 offset:53248
	ds_read_b128 v[190:193], v221 offset:54272
	ds_read_b128 v[194:197], v221 offset:55296
	ds_read_b128 v[198:201], v221 offset:56320
	global_load_lds_dwordx4 v[202:203], off
	s_add_i32 m0, s36, 0x2000
	s_add_u32 s34, s34, 0x100080
	v_lshl_add_u64 v[202:203], v[204:205], 0, s[94:95]
	s_addc_u32 s35, s35, 0
	s_add_i32 s36, s62, s77
	global_load_lds_dwordx4 v[202:203], off
	v_lshl_add_u64 v[202:203], s[34:35], 0, v[232:233]
	s_mov_b32 m0, s36
	s_nop 0
	global_load_lds_dwordx4 v[202:203], off
	v_lshl_add_u64 v[202:203], s[34:35], 0, v[184:185]
	s_add_i32 m0, s36, 0x2000
	s_nop 0
	global_load_lds_dwordx4 v[202:203], off
	v_lshl_add_u64 v[202:203], v[206:207], 0, s[94:95]
	s_mov_b32 m0, s52
	s_nop 0
	global_load_lds_dwordx4 v[202:203], off
	v_lshl_add_u64 v[202:203], v[208:209], 0, s[94:95]
	s_mov_b32 m0, s53
	s_nop 0
	global_load_lds_dwordx4 v[202:203], off
	s_waitcnt vmcnt(8) lgkmcnt(0)
	s_barrier
	v_mfma_f32_16x16x32_bf16 v[60:63], v[88:91], v[160:163], v[60:63]
	v_mfma_f32_16x16x32_bf16 v[56:59], v[96:99], v[160:163], v[56:59]
	v_mfma_f32_16x16x32_bf16 v[44:47], v[88:91], v[168:171], v[44:47]
	v_mfma_f32_16x16x32_bf16 v[40:43], v[96:99], v[168:171], v[40:43]
	v_mfma_f32_16x16x32_bf16 v[28:31], v[88:91], v[176:179], v[28:31]
	v_mfma_f32_16x16x32_bf16 v[24:27], v[96:99], v[176:179], v[24:27]
	v_mfma_f32_16x16x32_bf16 v[12:15], v[88:91], v[194:197], v[12:15]
	v_mfma_f32_16x16x32_bf16 v[8:11], v[96:99], v[194:197], v[8:11]
	v_mfma_f32_16x16x32_bf16 v[60:63], v[92:95], v[164:167], v[60:63]
	v_mfma_f32_16x16x32_bf16 v[56:59], v[100:103], v[164:167], v[56:59]
	v_mfma_f32_16x16x32_bf16 v[44:47], v[92:95], v[172:175], v[44:47]
	v_mfma_f32_16x16x32_bf16 v[40:43], v[100:103], v[172:175], v[40:43]
	v_mfma_f32_16x16x32_bf16 v[28:31], v[92:95], v[190:193], v[28:31]
	v_mfma_f32_16x16x32_bf16 v[24:27], v[100:103], v[190:193], v[24:27]
	v_mfma_f32_16x16x32_bf16 v[12:15], v[92:95], v[198:201], v[12:15]
	v_mfma_f32_16x16x32_bf16 v[8:11], v[100:103], v[198:201], v[8:11]
	v_mfma_f32_16x16x32_bf16 v[52:55], v[144:147], v[160:163], v[52:55]
	v_mfma_f32_16x16x32_bf16 v[48:51], v[152:155], v[160:163], v[48:51]
	v_mfma_f32_16x16x32_bf16 v[36:39], v[144:147], v[168:171], v[36:39]
	v_mfma_f32_16x16x32_bf16 v[32:35], v[152:155], v[168:171], v[32:35]
	v_mfma_f32_16x16x32_bf16 v[20:23], v[144:147], v[176:179], v[20:23]
	v_mfma_f32_16x16x32_bf16 v[16:19], v[152:155], v[176:179], v[16:19]
	v_mfma_f32_16x16x32_bf16 v[4:7], v[144:147], v[194:197], v[4:7]
	v_mfma_f32_16x16x32_bf16 v[0:3], v[152:155], v[194:197], v[0:3]
	v_mfma_f32_16x16x32_bf16 v[52:55], v[148:151], v[164:167], v[52:55]
	v_mfma_f32_16x16x32_bf16 v[48:51], v[156:159], v[164:167], v[48:51]
	v_mfma_f32_16x16x32_bf16 v[36:39], v[148:151], v[172:175], v[36:39]
	v_mfma_f32_16x16x32_bf16 v[32:35], v[156:159], v[172:175], v[32:35]
	v_mfma_f32_16x16x32_bf16 v[20:23], v[148:151], v[190:193], v[20:23]
	v_mfma_f32_16x16x32_bf16 v[16:19], v[156:159], v[190:193], v[16:19]
	v_mfma_f32_16x16x32_bf16 v[4:7], v[148:151], v[198:201], v[4:7]
	v_mfma_f32_16x16x32_bf16 v[0:3], v[156:159], v[198:201], v[0:3]
	s_barrier
	s_add_i32 s60, s60, 2
	s_add_u32 s58, s58, 0x100
	s_addc_u32 s59, s59, 0
	s_add_u32 s30, s30, 0x100
	s_addc_u32 s31, s31, 0
	s_cmp_gt_u32 s60, 61
	s_cbranch_scc0 .LBB0_1492
	s_and_b64 vcc, exec, s[18:19]
	s_cbranch_vccz .LBB0_1495
	s_barrier
